# v11: GLU and OUT epilogue cross-row statistic sums by v_permlane16/32_swap instead of ds_bpermute round trips (on top of v10)
# baseline (speedup 1.0000x reference)
.LBB0_467:
	s_lshl_b32 s0, s14, 8
	v_mov_b32_e32 v220, v240
	v_mov_b32_e32 v221, v241
	s_or_b32 s0, s0, s63
	s_lshl_b32 s15, s12, 8
	v_lshl_add_u32 v224, v221, 3, s0
	v_ashrrev_i32_e32 v225, 31, v224
	v_lshl_add_u64 v[62:63], v[224:225], 2, s[10:11]
	global_load_dwordx4 v[70:73], v[62:63], off offset:16
	global_load_dwordx4 v[82:85], v[62:63], off
	global_load_dwordx4 v[58:61], v[62:63], off offset:528
	s_nop 0
	global_load_dwordx4 v[62:65], v[62:63], off offset:512
	s_add_i32 s0, s15, s62
	v_add_u32_e32 v252, s0, v220
	v_lshlrev_b32_e32 v78, 4, v221
	v_and_b32_e32 v218, 16, v78
	v_ashrrev_i32_e32 v80, 4, v224
	v_ashrrev_i32_e32 v253, 31, v252
	v_lshl_add_u64 v[78:79], s[18:19], 0, v[218:219]
	v_ashrrev_i32_e32 v81, 31, v80
	v_lshlrev_b64 v[90:91], 5, v[252:253]
	v_lshlrev_b64 v[80:81], 19, v[80:81]
	v_lshl_add_u64 v[90:91], v[78:79], 0, v[90:91]
	v_lshl_add_u64 v[92:93], v[90:91], 0, v[80:81]
	global_load_dwordx4 v[206:209], v[92:93], off
	v_add_u32_e32 v92, 0x80, v224
	v_ashrrev_i32_e32 v92, 4, v92
	v_ashrrev_i32_e32 v93, 31, v92
	v_lshlrev_b64 v[250:251], 19, v[92:93]
	v_lshl_add_u64 v[90:91], v[90:91], 0, v[250:251]
	global_load_dwordx4 v[202:205], v[90:91], off
	v_add_u32_e32 v238, 16, v252
	v_ashrrev_i32_e32 v239, 31, v238
	v_lshlrev_b64 v[90:91], 5, v[238:239]
	v_lshl_add_u64 v[90:91], v[78:79], 0, v[90:91]
	v_add_u32_e32 v236, 32, v252
	v_lshl_add_u64 v[92:93], v[90:91], 0, v[80:81]
	v_lshl_add_u64 v[90:91], v[90:91], 0, v[250:251]
	v_ashrrev_i32_e32 v237, 31, v236
	global_load_dwordx4 v[198:201], v[92:93], off
	global_load_dwordx4 v[194:197], v[90:91], off
	v_lshlrev_b64 v[90:91], 5, v[236:237]
	v_lshl_add_u64 v[90:91], v[78:79], 0, v[90:91]
	v_add_u32_e32 v234, 48, v252
	v_lshl_add_u64 v[92:93], v[90:91], 0, v[80:81]
	v_lshl_add_u64 v[90:91], v[90:91], 0, v[250:251]
	v_ashrrev_i32_e32 v235, 31, v234
	global_load_dwordx4 v[190:193], v[92:93], off
	global_load_dwordx4 v[182:185], v[90:91], off
	v_lshlrev_b64 v[90:91], 5, v[234:235]
	v_lshl_add_u64 v[90:91], v[78:79], 0, v[90:91]
	v_add_u32_e32 v232, 0x80, v252
	v_lshl_add_u64 v[92:93], v[90:91], 0, v[80:81]
	v_lshl_add_u64 v[90:91], v[90:91], 0, v[250:251]
	v_ashrrev_i32_e32 v233, 31, v232
	global_load_dwordx4 v[174:177], v[92:93], off
	global_load_dwordx4 v[166:169], v[90:91], off
	v_lshlrev_b64 v[90:91], 5, v[232:233]
	v_lshl_add_u64 v[90:91], v[78:79], 0, v[90:91]
	v_add_u32_e32 v230, 0x90, v252
	v_lshl_add_u64 v[92:93], v[90:91], 0, v[80:81]
	v_lshl_add_u64 v[90:91], v[90:91], 0, v[250:251]
	v_ashrrev_i32_e32 v231, 31, v230
	global_load_dwordx4 v[158:161], v[92:93], off
	global_load_dwordx4 v[146:149], v[90:91], off
	v_lshlrev_b64 v[90:91], 5, v[230:231]
	v_lshl_add_u64 v[90:91], v[78:79], 0, v[90:91]
	v_add_u32_e32 v228, 0xa0, v252
	v_lshl_add_u64 v[92:93], v[90:91], 0, v[80:81]
	v_lshl_add_u64 v[90:91], v[90:91], 0, v[250:251]
	v_ashrrev_i32_e32 v229, 31, v228
	global_load_dwordx4 v[134:137], v[92:93], off
	global_load_dwordx4 v[122:125], v[90:91], off
	v_lshlrev_b64 v[90:91], 5, v[228:229]
	v_lshl_add_u64 v[90:91], v[78:79], 0, v[90:91]
	v_add_u32_e32 v226, 0xb0, v252
	v_lshl_add_u64 v[92:93], v[90:91], 0, v[80:81]
	v_lshl_add_u64 v[90:91], v[90:91], 0, v[250:251]
	v_ashrrev_i32_e32 v227, 31, v226
	global_load_dwordx4 v[110:113], v[92:93], off
	global_load_dwordx4 v[98:101], v[90:91], off
	v_lshlrev_b64 v[90:91], 5, v[226:227]
	v_lshl_add_u64 v[78:79], v[78:79], 0, v[90:91]
	v_lshl_add_u64 v[80:81], v[78:79], 0, v[80:81]
	v_lshl_add_u64 v[78:79], v[78:79], 0, v[250:251]
	global_load_dwordx4 v[90:93], v[80:81], off
	v_and_b32_e32 v249, 64, v248
	global_load_dwordx4 v[78:81], v[78:79], off
	s_waitcnt vmcnt(0)
	v_add_f32_e32 v178, v178, v70
	v_add_f32_e32 v188, v188, v84
	v_add_f32_e32 v189, v189, v85
	v_mul_f32_e32 v188, 0xbfb8aa3b, v188
	v_mul_f32_e32 v189, 0xbfb8aa3b, v189
	v_add_f32_e32 v179, v179, v71
	v_exp_f32_e32 v188, v188
	v_exp_f32_e32 v189, v189
	v_mul_f32_e32 v178, 0xbfb8aa3b, v178
	v_mul_f32_e32 v179, 0xbfb8aa3b, v179
	v_exp_f32_e32 v178, v178
	v_exp_f32_e32 v179, v179
	v_xor_b32_e32 v218, 16, v248
	v_add_u32_e32 v250, 64, v249
	v_cmp_lt_i32_e32 vcc, v218, v250
	v_add_f32_e32 v188, 1.0, v188
	v_add_f32_e32 v189, 1.0, v189
	v_cndmask_b32_e32 v218, v248, v218, vcc
	v_lshlrev_b32_e32 v249, 2, v218
	v_xor_b32_e32 v218, 32, v248
	v_rcp_f32_e32 v188, v188
	v_rcp_f32_e32 v189, v189
	v_add_f32_e32 v178, 1.0, v178
	v_add_f32_e32 v179, 1.0, v179
	v_cmp_lt_i32_e32 vcc, v218, v250
	v_rcp_f32_e32 v178, v178
	v_rcp_f32_e32 v179, v179
	v_cndmask_b32_e32 v218, v248, v218, vcc
	v_lshlrev_b32_e32 v250, 2, v218
	v_cmp_eq_u32_e32 vcc, 0, v221
	v_lshl_add_u32 v218, v220, 2, s67
	v_lshlrev_b32_e32 v220, 16, v206
	v_and_b32_e32 v221, 0xffff0000, v206
	v_lshlrev_b32_e32 v206, 16, v207
	v_and_b32_e32 v207, 0xffff0000, v207
	v_add_f32_e32 v186, v186, v82
	v_add_f32_e32 v187, v187, v83
	v_pk_mul_f32 v[188:189], v[188:189], v[206:207]
	v_lshlrev_b32_e32 v206, 16, v208
	v_and_b32_e32 v207, 0xffff0000, v208
	v_mul_f32_e32 v186, 0xbfb8aa3b, v186
	v_mul_f32_e32 v187, 0xbfb8aa3b, v187
	v_pk_mul_f32 v[206:207], v[178:179], v[206:207]
	v_add_f32_e32 v178, v180, v72
	v_add_f32_e32 v179, v181, v73
	v_exp_f32_e32 v186, v186
	v_exp_f32_e32 v187, v187
	v_mul_f32_e32 v178, 0xbfb8aa3b, v178
	v_mul_f32_e32 v179, 0xbfb8aa3b, v179
	v_exp_f32_e32 v178, v178
	v_exp_f32_e32 v179, v179
	v_add_f32_e32 v186, 1.0, v186
	v_add_f32_e32 v187, 1.0, v187
	v_rcp_f32_e32 v186, v186
	v_rcp_f32_e32 v187, v187
	v_add_f32_e32 v178, 1.0, v178
	v_add_f32_e32 v179, 1.0, v179
	v_rcp_f32_e32 v178, v178
	v_rcp_f32_e32 v179, v179
	v_add_f32_e32 v170, v170, v62
	v_add_f32_e32 v171, v171, v63
	v_mul_f32_e32 v170, 0xbfb8aa3b, v170
	v_mul_f32_e32 v171, 0xbfb8aa3b, v171
	v_add_f32_e32 v172, v172, v64
	v_add_f32_e32 v173, v173, v65
	v_exp_f32_e32 v170, v170
	v_exp_f32_e32 v171, v171
	v_mul_f32_e32 v172, 0xbfb8aa3b, v172
	v_mul_f32_e32 v173, 0xbfb8aa3b, v173
	v_add_f32_e32 v162, v162, v58
	v_add_f32_e32 v163, v163, v59
	v_lshlrev_b64 v[252:253], 11, v[252:253]
	v_pk_mul_f32 v[186:187], v[186:187], v[220:221]
	v_lshlrev_b32_e32 v180, 16, v209
	v_and_b32_e32 v181, 0xffff0000, v209
	v_exp_f32_e32 v172, v172
	v_exp_f32_e32 v173, v173
	v_mul_f32_e32 v162, 0xbfb8aa3b, v162
	v_mul_f32_e32 v163, 0xbfb8aa3b, v163
	v_pk_mul_f32 v[208:209], v[178:179], v[180:181]
	v_cvt_pk_bf16_f32 v178, v186, v187
	v_lshl_add_u64 v[186:187], s[20:21], 0, v[252:253]
	v_exp_f32_e32 v162, v162
	v_exp_f32_e32 v163, v163
	v_cvt_pk_bf16_f32 v179, v188, v189
	v_cvt_pk_bf16_f32 v180, v206, v207
	v_cvt_pk_bf16_f32 v181, v208, v209
	v_lshl_add_u64 v[186:187], v[224:225], 1, v[186:187]
	global_store_dwordx4 v[186:187], v[178:181], off
	v_lshlrev_b32_e32 v188, 16, v178
	v_add_f32_e32 v170, 1.0, v170
	v_and_b32_e32 v178, 0xffff0000, v178
	v_add_f32_e32 v171, 1.0, v171
	v_mul_f32_e32 v208, v178, v178
	v_rcp_f32_e32 v170, v170
	v_rcp_f32_e32 v171, v171
	v_add_f32_e32 v172, 1.0, v172
	v_add_f32_e32 v173, 1.0, v173
	v_lshlrev_b32_e32 v189, 16, v179
	v_fmac_f32_e32 v208, v188, v188
	v_rcp_f32_e32 v172, v172
	v_rcp_f32_e32 v173, v173
	v_add_f32_e32 v162, 1.0, v162
	v_add_f32_e32 v163, 1.0, v163
	v_and_b32_e32 v179, 0xffff0000, v179
	v_fmac_f32_e32 v208, v189, v189
	v_rcp_f32_e32 v162, v162
	v_rcp_f32_e32 v163, v163
	v_fmac_f32_e32 v208, v179, v179
	v_lshlrev_b32_e32 v178, 16, v202
	v_and_b32_e32 v179, 0xffff0000, v202
	v_pk_mul_f32 v[170:171], v[170:171], v[178:179]
	v_lshlrev_b32_e32 v178, 16, v203
	v_and_b32_e32 v179, 0xffff0000, v203
	v_pk_mul_f32 v[172:173], v[172:173], v[178:179]
	v_lshlrev_b32_e32 v178, 16, v204
	v_and_b32_e32 v179, 0xffff0000, v204
	v_pk_mul_f32 v[178:179], v[162:163], v[178:179]
	v_add_f32_e32 v162, v164, v60
	v_add_f32_e32 v163, v165, v61
	v_mul_f32_e32 v162, 0xbfb8aa3b, v162
	v_mul_f32_e32 v163, 0xbfb8aa3b, v163
	v_exp_f32_e32 v162, v162
	v_exp_f32_e32 v163, v163
	v_lshlrev_b32_e32 v206, 16, v180
	v_and_b32_e32 v180, 0xffff0000, v180
	v_add_f32_e32 v162, 1.0, v162
	v_add_f32_e32 v163, 1.0, v163
	v_rcp_f32_e32 v162, v162
	v_rcp_f32_e32 v163, v163
	v_fmac_f32_e32 v208, v206, v206
	v_lshlrev_b32_e32 v207, 16, v181
	v_fmac_f32_e32 v208, v180, v180
	v_and_b32_e32 v181, 0xffff0000, v181
	v_fmac_f32_e32 v208, v207, v207
	v_lshlrev_b32_e32 v164, 16, v205
	v_and_b32_e32 v165, 0xffff0000, v205
	v_fmac_f32_e32 v208, v181, v181
	v_pk_mul_f32 v[180:181], v[162:163], v[164:165]
	v_cvt_pk_bf16_f32 v162, v170, v171
	v_cvt_pk_bf16_f32 v163, v172, v173
	v_cvt_pk_bf16_f32 v164, v178, v179
	v_cvt_pk_bf16_f32 v165, v180, v181
	v_lshlrev_b32_e32 v170, 16, v162
	global_store_dwordx4 v[186:187], v[162:165], off offset:256
	v_fmac_f32_e32 v208, v170, v170
	v_lshlrev_b32_e32 v171, 16, v163
	v_and_b32_e32 v162, 0xffff0000, v162
	v_fmac_f32_e32 v208, v162, v162
	v_and_b32_e32 v163, 0xffff0000, v163
	v_fmac_f32_e32 v208, v171, v171
	v_lshlrev_b32_e32 v172, 16, v164
	v_fmac_f32_e32 v208, v163, v163
	v_and_b32_e32 v164, 0xffff0000, v164
	v_fmac_f32_e32 v208, v172, v172
	v_lshlrev_b32_e32 v173, 16, v165
	v_fmac_f32_e32 v208, v164, v164
	v_and_b32_e32 v165, 0xffff0000, v165
	v_fmac_f32_e32 v208, v173, v173
	v_fmac_f32_e32 v208, v165, v165
	s_nop 0
	s_waitcnt lgkmcnt(0)
	v_mov_b32_e32 v162, v208
	s_nop 1
	v_permlane16_swap_b32_e32 v162, v208
	v_add_f32_e32 v162, v208, v162
	v_mov_b32_e32 v163, v162
	s_nop 1
	v_permlane32_swap_b32_e32 v163, v162
	s_and_saveexec_b64 s[0:1], vcc
	s_cbranch_execz .LBB0_469
	s_waitcnt lgkmcnt(0)
	v_add_f32_e32 v162, v162, v163
	ds_write_b32 v218, v162
.LBB0_469:
	s_or_b64 exec, exec, s[0:1]
	v_add_f32_e32 v154, v154, v82
	v_add_f32_e32 v155, v155, v83
	v_mul_f32_e32 v154, 0xbfb8aa3b, v154
	v_mul_f32_e32 v155, 0xbfb8aa3b, v155
	v_add_f32_e32 v156, v156, v84
	v_add_f32_e32 v157, v157, v85
	v_exp_f32_e32 v154, v154
	v_exp_f32_e32 v155, v155
	v_mul_f32_e32 v156, 0xbfb8aa3b, v156
	v_mul_f32_e32 v157, 0xbfb8aa3b, v157
	v_add_f32_e32 v150, v150, v70
	v_add_f32_e32 v151, v151, v71
	v_exp_f32_e32 v156, v156
	v_exp_f32_e32 v157, v157
	v_mul_f32_e32 v150, 0xbfb8aa3b, v150
	v_mul_f32_e32 v151, 0xbfb8aa3b, v151
	v_add_f32_e32 v152, v152, v72
	v_add_f32_e32 v153, v153, v73
	v_exp_f32_e32 v150, v150
	v_exp_f32_e32 v151, v151
	v_mul_f32_e32 v152, 0xbfb8aa3b, v152
	v_mul_f32_e32 v153, 0xbfb8aa3b, v153
	v_exp_f32_e32 v152, v152
	v_exp_f32_e32 v153, v153
	v_add_f32_e32 v154, 1.0, v154
	v_add_f32_e32 v155, 1.0, v155
	v_rcp_f32_e32 v154, v154
	v_rcp_f32_e32 v155, v155
	v_add_f32_e32 v156, 1.0, v156
	v_add_f32_e32 v157, 1.0, v157
	v_rcp_f32_e32 v156, v156
	v_rcp_f32_e32 v157, v157
	v_add_f32_e32 v150, 1.0, v150
	v_add_f32_e32 v151, 1.0, v151
	v_rcp_f32_e32 v150, v150
	v_rcp_f32_e32 v151, v151
	v_add_f32_e32 v152, 1.0, v152
	v_add_f32_e32 v153, 1.0, v153
	v_lshlrev_b32_e32 v162, 16, v198
	s_waitcnt lgkmcnt(0)
	v_and_b32_e32 v163, 0xffff0000, v198
	v_rcp_f32_e32 v152, v152
	v_rcp_f32_e32 v153, v153
	v_pk_mul_f32 v[154:155], v[154:155], v[162:163]
	v_lshlrev_b32_e32 v162, 16, v199
	v_and_b32_e32 v163, 0xffff0000, v199
	v_pk_mul_f32 v[156:157], v[156:157], v[162:163]
	v_lshlrev_b32_e32 v162, 16, v200
	v_and_b32_e32 v163, 0xffff0000, v200
	v_add_f32_e32 v142, v142, v62
	v_add_f32_e32 v143, v143, v63
	v_pk_mul_f32 v[162:163], v[150:151], v[162:163]
	v_lshlrev_b32_e32 v150, 16, v201
	v_and_b32_e32 v151, 0xffff0000, v201
	v_mul_f32_e32 v142, 0xbfb8aa3b, v142
	v_mul_f32_e32 v143, 0xbfb8aa3b, v143
	v_add_f32_e32 v144, v144, v64
	v_add_f32_e32 v145, v145, v65
	v_pk_mul_f32 v[164:165], v[152:153], v[150:151]
	v_cvt_pk_bf16_f32 v150, v154, v155
	v_exp_f32_e32 v142, v142
	v_exp_f32_e32 v143, v143
	v_mul_f32_e32 v144, 0xbfb8aa3b, v144
	v_mul_f32_e32 v145, 0xbfb8aa3b, v145
	v_and_b32_e32 v155, 0xffff0000, v150
	v_exp_f32_e32 v144, v144
	v_exp_f32_e32 v145, v145
	v_cvt_pk_bf16_f32 v151, v156, v157
	v_lshlrev_b32_e32 v154, 16, v150
	v_mul_f32_e32 v170, v155, v155
	v_add_f32_e32 v138, v138, v58
	v_lshlrev_b32_e32 v156, 16, v151
	v_fmac_f32_e32 v170, v154, v154
	v_mul_f32_e32 v138, 0xbfb8aa3b, v138
	v_fmac_f32_e32 v170, v156, v156
	v_add_f32_e32 v142, 1.0, v142
	v_add_f32_e32 v143, 1.0, v143
	v_exp_f32_e32 v156, v138
	v_add_f32_e32 v138, v139, v59
	v_and_b32_e32 v157, 0xffff0000, v151
	v_rcp_f32_e32 v142, v142
	v_rcp_f32_e32 v143, v143
	v_add_f32_e32 v144, 1.0, v144
	v_add_f32_e32 v145, 1.0, v145
	v_mul_f32_e32 v138, 0xbfb8aa3b, v138
	v_add_f32_e32 v140, v140, v60
	v_add_f32_e32 v141, v141, v61
	v_fmac_f32_e32 v170, v157, v157
	v_rcp_f32_e32 v144, v144
	v_rcp_f32_e32 v145, v145
	v_exp_f32_e32 v157, v138
	v_mul_f32_e32 v140, 0xbfb8aa3b, v140
	v_mul_f32_e32 v141, 0xbfb8aa3b, v141
	v_exp_f32_e32 v140, v140
	v_exp_f32_e32 v141, v141
	v_lshlrev_b32_e32 v154, 16, v194
	v_and_b32_e32 v155, 0xffff0000, v194
	v_pk_mul_f32 v[142:143], v[142:143], v[154:155]
	v_lshlrev_b32_e32 v154, 16, v195
	v_and_b32_e32 v155, 0xffff0000, v195
	v_pk_mul_f32 v[138:139], v[144:145], v[154:155]
	v_add_f32_e32 v144, 1.0, v156
	v_add_f32_e32 v145, 1.0, v157
	v_rcp_f32_e32 v144, v144
	v_rcp_f32_e32 v145, v145
	v_add_f32_e32 v140, 1.0, v140
	v_add_f32_e32 v141, 1.0, v141
	v_cvt_pk_bf16_f32 v152, v162, v163
	v_rcp_f32_e32 v140, v140
	v_rcp_f32_e32 v141, v141
	v_lshlrev_b32_e32 v162, 16, v152
	v_cvt_pk_bf16_f32 v153, v164, v165
	v_and_b32_e32 v163, 0xffff0000, v152
	v_fmac_f32_e32 v170, v162, v162
	v_lshlrev_b32_e32 v154, 16, v196
	v_and_b32_e32 v155, 0xffff0000, v196
	v_lshlrev_b32_e32 v164, 16, v153
	v_fmac_f32_e32 v170, v163, v163
	v_pk_mul_f32 v[144:145], v[144:145], v[154:155]
	v_lshlrev_b32_e32 v154, 16, v197
	v_and_b32_e32 v155, 0xffff0000, v197
	v_and_b32_e32 v165, 0xffff0000, v153
	v_fmac_f32_e32 v170, v164, v164
	v_pk_mul_f32 v[154:155], v[140:141], v[154:155]
	v_cvt_pk_bf16_f32 v140, v142, v143
	v_fmac_f32_e32 v170, v165, v165
	v_cvt_pk_bf16_f32 v141, v138, v139
	v_lshlrev_b32_e32 v138, 16, v140
	v_and_b32_e32 v139, 0xffff0000, v140
	v_fmac_f32_e32 v170, v138, v138
	v_cvt_pk_bf16_f32 v142, v144, v145
	v_lshlrev_b32_e32 v144, 16, v141
	v_fmac_f32_e32 v170, v139, v139
	v_and_b32_e32 v145, 0xffff0000, v141
	v_fmac_f32_e32 v170, v144, v144
	v_cvt_pk_bf16_f32 v143, v154, v155
	v_lshlrev_b32_e32 v154, 16, v142
	v_fmac_f32_e32 v170, v145, v145
	v_and_b32_e32 v155, 0xffff0000, v142
	v_fmac_f32_e32 v170, v154, v154
	v_lshlrev_b32_e32 v156, 16, v143
	v_fmac_f32_e32 v170, v155, v155
	v_and_b32_e32 v157, 0xffff0000, v143
	v_fmac_f32_e32 v170, v156, v156
	v_fmac_f32_e32 v170, v157, v157
	s_nop 0
	v_lshlrev_b64 v[144:145], 11, v[238:239]
	v_lshl_add_u64 v[144:145], s[20:21], 0, v[144:145]
	v_lshl_add_u64 v[144:145], v[224:225], 1, v[144:145]
	global_store_dwordx4 v[144:145], v[150:153], off
	global_store_dwordx4 v[144:145], v[140:143], off offset:256
	s_waitcnt lgkmcnt(0)
	v_mov_b32_e32 v138, v170
	s_nop 1
	v_permlane16_swap_b32_e32 v138, v170
	v_add_f32_e32 v138, v170, v138
	v_mov_b32_e32 v139, v138
	s_nop 1
	v_permlane32_swap_b32_e32 v139, v138
	s_and_saveexec_b64 s[0:1], vcc
	s_cbranch_execz .LBB0_471
	s_waitcnt lgkmcnt(0)
	v_add_f32_e32 v138, v138, v139
	ds_write_b32 v218, v138 offset:64
.LBB0_471:
	s_or_b64 exec, exec, s[0:1]
	v_add_f32_e32 v130, v130, v82
	v_add_f32_e32 v131, v131, v83
	v_mul_f32_e32 v130, 0xbfb8aa3b, v130
	v_mul_f32_e32 v131, 0xbfb8aa3b, v131
	v_add_f32_e32 v132, v132, v84
	v_add_f32_e32 v133, v133, v85
	v_exp_f32_e32 v130, v130
	v_exp_f32_e32 v131, v131
	v_mul_f32_e32 v132, 0xbfb8aa3b, v132
	v_mul_f32_e32 v133, 0xbfb8aa3b, v133
	v_add_f32_e32 v126, v126, v70
	v_add_f32_e32 v127, v127, v71
	v_exp_f32_e32 v132, v132
	v_exp_f32_e32 v133, v133
	v_mul_f32_e32 v126, 0xbfb8aa3b, v126
	v_mul_f32_e32 v127, 0xbfb8aa3b, v127
	v_add_f32_e32 v128, v128, v72
	v_add_f32_e32 v129, v129, v73
	v_exp_f32_e32 v126, v126
	v_exp_f32_e32 v127, v127
	v_mul_f32_e32 v128, 0xbfb8aa3b, v128
	v_mul_f32_e32 v129, 0xbfb8aa3b, v129
	v_exp_f32_e32 v128, v128
	v_exp_f32_e32 v129, v129
	v_add_f32_e32 v130, 1.0, v130
	v_add_f32_e32 v131, 1.0, v131
	v_rcp_f32_e32 v130, v130
	v_rcp_f32_e32 v131, v131
	v_add_f32_e32 v132, 1.0, v132
	v_add_f32_e32 v133, 1.0, v133
	v_rcp_f32_e32 v132, v132
	v_rcp_f32_e32 v133, v133
	v_add_f32_e32 v126, 1.0, v126
	v_add_f32_e32 v127, 1.0, v127
	v_rcp_f32_e32 v126, v126
	v_rcp_f32_e32 v127, v127
	v_add_f32_e32 v128, 1.0, v128
	v_add_f32_e32 v129, 1.0, v129
	v_lshlrev_b32_e32 v138, 16, v190
	s_waitcnt lgkmcnt(0)
	v_and_b32_e32 v139, 0xffff0000, v190
	v_rcp_f32_e32 v128, v128
	v_rcp_f32_e32 v129, v129
	v_pk_mul_f32 v[130:131], v[130:131], v[138:139]
	v_lshlrev_b32_e32 v138, 16, v191
	v_and_b32_e32 v139, 0xffff0000, v191
	v_pk_mul_f32 v[132:133], v[132:133], v[138:139]
	v_lshlrev_b32_e32 v138, 16, v192
	v_and_b32_e32 v139, 0xffff0000, v192
	v_add_f32_e32 v118, v118, v62
	v_add_f32_e32 v119, v119, v63
	v_pk_mul_f32 v[138:139], v[126:127], v[138:139]
	v_lshlrev_b32_e32 v126, 16, v193
	v_and_b32_e32 v127, 0xffff0000, v193
	v_mul_f32_e32 v118, 0xbfb8aa3b, v118
	v_mul_f32_e32 v119, 0xbfb8aa3b, v119
	v_add_f32_e32 v120, v120, v64
	v_add_f32_e32 v121, v121, v65
	v_pk_mul_f32 v[140:141], v[128:129], v[126:127]
	v_cvt_pk_bf16_f32 v126, v130, v131
	v_exp_f32_e32 v118, v118
	v_exp_f32_e32 v119, v119
	v_mul_f32_e32 v120, 0xbfb8aa3b, v120
	v_mul_f32_e32 v121, 0xbfb8aa3b, v121
	v_and_b32_e32 v131, 0xffff0000, v126
	v_exp_f32_e32 v120, v120
	v_exp_f32_e32 v121, v121
	v_cvt_pk_bf16_f32 v127, v132, v133
	v_lshlrev_b32_e32 v130, 16, v126
	v_mul_f32_e32 v142, v131, v131
	v_add_f32_e32 v114, v114, v58
	v_lshlrev_b32_e32 v132, 16, v127
	v_fmac_f32_e32 v142, v130, v130
	v_mul_f32_e32 v114, 0xbfb8aa3b, v114
	v_fmac_f32_e32 v142, v132, v132
	v_add_f32_e32 v118, 1.0, v118
	v_add_f32_e32 v119, 1.0, v119
	v_exp_f32_e32 v132, v114
	v_add_f32_e32 v114, v115, v59
	v_and_b32_e32 v133, 0xffff0000, v127
	v_rcp_f32_e32 v118, v118
	v_rcp_f32_e32 v119, v119
	v_add_f32_e32 v120, 1.0, v120
	v_add_f32_e32 v121, 1.0, v121
	v_mul_f32_e32 v114, 0xbfb8aa3b, v114
	v_add_f32_e32 v116, v116, v60
	v_add_f32_e32 v117, v117, v61
	v_fmac_f32_e32 v142, v133, v133
	v_rcp_f32_e32 v120, v120
	v_rcp_f32_e32 v121, v121
	v_exp_f32_e32 v133, v114
	v_mul_f32_e32 v116, 0xbfb8aa3b, v116
	v_mul_f32_e32 v117, 0xbfb8aa3b, v117
	v_exp_f32_e32 v116, v116
	v_exp_f32_e32 v117, v117
	v_lshlrev_b32_e32 v130, 16, v182
	v_and_b32_e32 v131, 0xffff0000, v182
	v_pk_mul_f32 v[118:119], v[118:119], v[130:131]
	v_lshlrev_b32_e32 v130, 16, v183
	v_and_b32_e32 v131, 0xffff0000, v183
	v_pk_mul_f32 v[114:115], v[120:121], v[130:131]
	v_add_f32_e32 v120, 1.0, v132
	v_add_f32_e32 v121, 1.0, v133
	v_rcp_f32_e32 v120, v120
	v_rcp_f32_e32 v121, v121
	v_add_f32_e32 v116, 1.0, v116
	v_add_f32_e32 v117, 1.0, v117
	v_cvt_pk_bf16_f32 v128, v138, v139
	v_rcp_f32_e32 v116, v116
	v_rcp_f32_e32 v117, v117
	v_lshlrev_b32_e32 v138, 16, v128
	v_cvt_pk_bf16_f32 v129, v140, v141
	v_and_b32_e32 v139, 0xffff0000, v128
	v_fmac_f32_e32 v142, v138, v138
	v_lshlrev_b32_e32 v130, 16, v184
	v_and_b32_e32 v131, 0xffff0000, v184
	v_lshlrev_b32_e32 v140, 16, v129
	v_fmac_f32_e32 v142, v139, v139
	v_pk_mul_f32 v[120:121], v[120:121], v[130:131]
	v_lshlrev_b32_e32 v130, 16, v185
	v_and_b32_e32 v131, 0xffff0000, v185
	v_and_b32_e32 v141, 0xffff0000, v129
	v_fmac_f32_e32 v142, v140, v140
	v_pk_mul_f32 v[130:131], v[116:117], v[130:131]
	v_cvt_pk_bf16_f32 v116, v118, v119
	v_fmac_f32_e32 v142, v141, v141
	v_cvt_pk_bf16_f32 v117, v114, v115
	v_lshlrev_b32_e32 v114, 16, v116
	v_and_b32_e32 v115, 0xffff0000, v116
	v_fmac_f32_e32 v142, v114, v114
	v_cvt_pk_bf16_f32 v118, v120, v121
	v_lshlrev_b32_e32 v120, 16, v117
	v_fmac_f32_e32 v142, v115, v115
	v_and_b32_e32 v121, 0xffff0000, v117
	v_fmac_f32_e32 v142, v120, v120
	v_cvt_pk_bf16_f32 v119, v130, v131
	v_lshlrev_b32_e32 v130, 16, v118
	v_fmac_f32_e32 v142, v121, v121
	v_and_b32_e32 v131, 0xffff0000, v118
	v_fmac_f32_e32 v142, v130, v130
	v_lshlrev_b32_e32 v132, 16, v119
	v_fmac_f32_e32 v142, v131, v131
	v_and_b32_e32 v133, 0xffff0000, v119
	v_fmac_f32_e32 v142, v132, v132
	v_fmac_f32_e32 v142, v133, v133
	s_nop 0
	v_lshlrev_b64 v[120:121], 11, v[236:237]
	v_lshl_add_u64 v[120:121], s[20:21], 0, v[120:121]
	v_lshl_add_u64 v[120:121], v[224:225], 1, v[120:121]
	global_store_dwordx4 v[120:121], v[126:129], off
	global_store_dwordx4 v[120:121], v[116:119], off offset:256
	s_waitcnt lgkmcnt(0)
	v_mov_b32_e32 v114, v142
	s_nop 1
	v_permlane16_swap_b32_e32 v114, v142
	v_add_f32_e32 v114, v142, v114
	v_mov_b32_e32 v115, v114
	s_nop 1
	v_permlane32_swap_b32_e32 v115, v114
	s_and_saveexec_b64 s[0:1], vcc
	s_cbranch_execz .LBB0_473
	s_waitcnt lgkmcnt(0)
	v_add_f32_e32 v114, v114, v115
	ds_write_b32 v218, v114 offset:128
.LBB0_473:
	s_or_b64 exec, exec, s[0:1]
	v_add_f32_e32 v106, v106, v82
	v_add_f32_e32 v107, v107, v83
	v_mul_f32_e32 v106, 0xbfb8aa3b, v106
	v_mul_f32_e32 v107, 0xbfb8aa3b, v107
	v_add_f32_e32 v108, v108, v84
	v_add_f32_e32 v109, v109, v85
	v_exp_f32_e32 v106, v106
	v_exp_f32_e32 v107, v107
	v_mul_f32_e32 v108, 0xbfb8aa3b, v108
	v_mul_f32_e32 v109, 0xbfb8aa3b, v109
	v_add_f32_e32 v102, v102, v70
	v_add_f32_e32 v103, v103, v71
	v_exp_f32_e32 v108, v108
	v_exp_f32_e32 v109, v109
	v_mul_f32_e32 v102, 0xbfb8aa3b, v102
	v_mul_f32_e32 v103, 0xbfb8aa3b, v103
	v_add_f32_e32 v104, v104, v72
	v_add_f32_e32 v105, v105, v73
	v_exp_f32_e32 v102, v102
	v_exp_f32_e32 v103, v103
	v_mul_f32_e32 v104, 0xbfb8aa3b, v104
	v_mul_f32_e32 v105, 0xbfb8aa3b, v105
	v_exp_f32_e32 v104, v104
	v_exp_f32_e32 v105, v105
	v_add_f32_e32 v106, 1.0, v106
	v_add_f32_e32 v107, 1.0, v107
	v_rcp_f32_e32 v106, v106
	v_rcp_f32_e32 v107, v107
	v_add_f32_e32 v108, 1.0, v108
	v_add_f32_e32 v109, 1.0, v109
	v_rcp_f32_e32 v108, v108
	v_rcp_f32_e32 v109, v109
	v_add_f32_e32 v102, 1.0, v102
	v_add_f32_e32 v103, 1.0, v103
	v_rcp_f32_e32 v102, v102
	v_rcp_f32_e32 v103, v103
	v_add_f32_e32 v104, 1.0, v104
	v_add_f32_e32 v105, 1.0, v105
	v_lshlrev_b32_e32 v114, 16, v174
	s_waitcnt lgkmcnt(0)
	v_and_b32_e32 v115, 0xffff0000, v174
	v_rcp_f32_e32 v104, v104
	v_rcp_f32_e32 v105, v105
	v_pk_mul_f32 v[106:107], v[106:107], v[114:115]
	v_lshlrev_b32_e32 v114, 16, v175
	v_and_b32_e32 v115, 0xffff0000, v175
	v_pk_mul_f32 v[108:109], v[108:109], v[114:115]
	v_lshlrev_b32_e32 v114, 16, v176
	v_and_b32_e32 v115, 0xffff0000, v176
	v_add_f32_e32 v94, v94, v62
	v_add_f32_e32 v95, v95, v63
	v_pk_mul_f32 v[114:115], v[102:103], v[114:115]
	v_lshlrev_b32_e32 v102, 16, v177
	v_and_b32_e32 v103, 0xffff0000, v177
	v_mul_f32_e32 v94, 0xbfb8aa3b, v94
	v_mul_f32_e32 v95, 0xbfb8aa3b, v95
	v_add_f32_e32 v96, v96, v64
	v_add_f32_e32 v97, v97, v65
	v_pk_mul_f32 v[116:117], v[104:105], v[102:103]
	v_cvt_pk_bf16_f32 v102, v106, v107
	v_exp_f32_e32 v94, v94
	v_exp_f32_e32 v95, v95
	v_mul_f32_e32 v96, 0xbfb8aa3b, v96
	v_mul_f32_e32 v97, 0xbfb8aa3b, v97
	v_and_b32_e32 v107, 0xffff0000, v102
	v_exp_f32_e32 v96, v96
	v_exp_f32_e32 v97, v97
	v_cvt_pk_bf16_f32 v103, v108, v109
	v_lshlrev_b32_e32 v106, 16, v102
	v_mul_f32_e32 v118, v107, v107
	v_add_f32_e32 v86, v86, v58
	v_lshlrev_b32_e32 v108, 16, v103
	v_fmac_f32_e32 v118, v106, v106
	v_mul_f32_e32 v86, 0xbfb8aa3b, v86
	v_fmac_f32_e32 v118, v108, v108
	v_add_f32_e32 v94, 1.0, v94
	v_add_f32_e32 v95, 1.0, v95
	v_exp_f32_e32 v108, v86
	v_add_f32_e32 v86, v87, v59
	v_and_b32_e32 v109, 0xffff0000, v103
	v_rcp_f32_e32 v94, v94
	v_rcp_f32_e32 v95, v95
	v_add_f32_e32 v96, 1.0, v96
	v_add_f32_e32 v97, 1.0, v97
	v_mul_f32_e32 v86, 0xbfb8aa3b, v86
	v_add_f32_e32 v88, v88, v60
	v_add_f32_e32 v89, v89, v61
	v_fmac_f32_e32 v118, v109, v109
	v_rcp_f32_e32 v96, v96
	v_rcp_f32_e32 v97, v97
	v_exp_f32_e32 v109, v86
	v_mul_f32_e32 v88, 0xbfb8aa3b, v88
	v_mul_f32_e32 v89, 0xbfb8aa3b, v89
	v_exp_f32_e32 v88, v88
	v_exp_f32_e32 v89, v89
	v_lshlrev_b32_e32 v106, 16, v166
	v_and_b32_e32 v107, 0xffff0000, v166
	v_pk_mul_f32 v[94:95], v[94:95], v[106:107]
	v_lshlrev_b32_e32 v106, 16, v167
	v_and_b32_e32 v107, 0xffff0000, v167
	v_cvt_pk_bf16_f32 v104, v114, v115
	v_pk_mul_f32 v[86:87], v[96:97], v[106:107]
	v_add_f32_e32 v96, 1.0, v108
	v_add_f32_e32 v97, 1.0, v109
	v_lshlrev_b32_e32 v114, 16, v104
	v_rcp_f32_e32 v96, v96
	v_rcp_f32_e32 v97, v97
	v_add_f32_e32 v88, 1.0, v88
	v_add_f32_e32 v89, 1.0, v89
	v_cvt_pk_bf16_f32 v105, v116, v117
	v_and_b32_e32 v115, 0xffff0000, v104
	v_fmac_f32_e32 v118, v114, v114
	v_rcp_f32_e32 v88, v88
	v_rcp_f32_e32 v89, v89
	v_lshlrev_b32_e32 v116, 16, v105
	v_fmac_f32_e32 v118, v115, v115
	v_and_b32_e32 v117, 0xffff0000, v105
	v_fmac_f32_e32 v118, v116, v116
	v_lshlrev_b32_e32 v106, 16, v168
	v_and_b32_e32 v107, 0xffff0000, v168
	v_cvt_pk_bf16_f32 v94, v94, v95
	v_fmac_f32_e32 v118, v117, v117
	v_pk_mul_f32 v[96:97], v[96:97], v[106:107]
	v_lshlrev_b32_e32 v106, 16, v169
	v_and_b32_e32 v107, 0xffff0000, v169
	v_cvt_pk_bf16_f32 v95, v86, v87
	v_lshlrev_b32_e32 v86, 16, v94
	v_pk_mul_f32 v[88:89], v[88:89], v[106:107]
	v_and_b32_e32 v87, 0xffff0000, v94
	v_fmac_f32_e32 v118, v86, v86
	v_cvt_pk_bf16_f32 v96, v96, v97
	v_cvt_pk_bf16_f32 v97, v88, v89
	v_lshlrev_b32_e32 v88, 16, v95
	v_fmac_f32_e32 v118, v87, v87
	v_and_b32_e32 v89, 0xffff0000, v95
	v_fmac_f32_e32 v118, v88, v88
	v_lshlrev_b32_e32 v106, 16, v96
	v_fmac_f32_e32 v118, v89, v89
	v_and_b32_e32 v107, 0xffff0000, v96
	v_fmac_f32_e32 v118, v106, v106
	v_lshlrev_b32_e32 v108, 16, v97
	v_fmac_f32_e32 v118, v107, v107
	v_and_b32_e32 v109, 0xffff0000, v97
	v_fmac_f32_e32 v118, v108, v108
	v_fmac_f32_e32 v118, v109, v109
	s_nop 0
	v_lshlrev_b64 v[88:89], 11, v[234:235]
	v_lshl_add_u64 v[88:89], s[20:21], 0, v[88:89]
	v_lshl_add_u64 v[88:89], v[224:225], 1, v[88:89]
	global_store_dwordx4 v[88:89], v[102:105], off
	global_store_dwordx4 v[88:89], v[94:97], off offset:256
	s_waitcnt lgkmcnt(0)
	v_mov_b32_e32 v86, v118
	s_nop 1
	v_permlane16_swap_b32_e32 v86, v118
	v_add_f32_e32 v86, v118, v86
	v_mov_b32_e32 v87, v86
	s_nop 1
	v_permlane32_swap_b32_e32 v87, v86
	s_and_saveexec_b64 s[0:1], vcc
	s_cbranch_execz .LBB0_475
	s_waitcnt lgkmcnt(0)
	v_add_f32_e32 v86, v86, v87
	ds_write_b32 v218, v86 offset:192
.LBB0_475:
	s_or_b64 exec, exec, s[0:1]
	v_add_f32_e32 v74, v74, v82
	v_add_f32_e32 v75, v75, v83
	v_mul_f32_e32 v74, 0xbfb8aa3b, v74
	v_mul_f32_e32 v75, 0xbfb8aa3b, v75
	v_add_f32_e32 v76, v76, v84
	v_add_f32_e32 v77, v77, v85
	v_exp_f32_e32 v74, v74
	v_exp_f32_e32 v75, v75
	v_mul_f32_e32 v76, 0xbfb8aa3b, v76
	v_mul_f32_e32 v77, 0xbfb8aa3b, v77
	v_add_f32_e32 v66, v66, v70
	v_add_f32_e32 v67, v67, v71
	v_exp_f32_e32 v76, v76
	v_exp_f32_e32 v77, v77
	v_mul_f32_e32 v66, 0xbfb8aa3b, v66
	v_mul_f32_e32 v67, 0xbfb8aa3b, v67
	v_add_f32_e32 v68, v68, v72
	v_add_f32_e32 v69, v69, v73
	v_exp_f32_e32 v66, v66
	v_exp_f32_e32 v67, v67
	v_mul_f32_e32 v68, 0xbfb8aa3b, v68
	v_mul_f32_e32 v69, 0xbfb8aa3b, v69
	v_exp_f32_e32 v68, v68
	v_exp_f32_e32 v69, v69
	v_add_f32_e32 v74, 1.0, v74
	v_add_f32_e32 v75, 1.0, v75
	v_rcp_f32_e32 v74, v74
	v_rcp_f32_e32 v75, v75
	v_add_f32_e32 v76, 1.0, v76
	v_add_f32_e32 v77, 1.0, v77
	v_rcp_f32_e32 v76, v76
	v_rcp_f32_e32 v77, v77
	v_add_f32_e32 v66, 1.0, v66
	v_add_f32_e32 v67, 1.0, v67
	v_rcp_f32_e32 v66, v66
	v_rcp_f32_e32 v67, v67
	v_add_f32_e32 v68, 1.0, v68
	v_add_f32_e32 v69, 1.0, v69
	v_lshlrev_b32_e32 v86, 16, v158
	s_waitcnt lgkmcnt(0)
	v_and_b32_e32 v87, 0xffff0000, v158
	v_rcp_f32_e32 v68, v68
	v_rcp_f32_e32 v69, v69
	v_pk_mul_f32 v[74:75], v[74:75], v[86:87]
	v_lshlrev_b32_e32 v86, 16, v159
	v_and_b32_e32 v87, 0xffff0000, v159
	v_pk_mul_f32 v[76:77], v[76:77], v[86:87]
	v_lshlrev_b32_e32 v86, 16, v160
	v_and_b32_e32 v87, 0xffff0000, v160
	v_add_f32_e32 v54, v54, v62
	v_add_f32_e32 v55, v55, v63
	v_pk_mul_f32 v[86:87], v[66:67], v[86:87]
	v_lshlrev_b32_e32 v66, 16, v161
	v_and_b32_e32 v67, 0xffff0000, v161
	v_mul_f32_e32 v54, 0xbfb8aa3b, v54
	v_mul_f32_e32 v55, 0xbfb8aa3b, v55
	v_add_f32_e32 v56, v56, v64
	v_add_f32_e32 v57, v57, v65
	v_pk_mul_f32 v[88:89], v[68:69], v[66:67]
	v_cvt_pk_bf16_f32 v66, v74, v75
	v_exp_f32_e32 v54, v54
	v_exp_f32_e32 v55, v55
	v_mul_f32_e32 v56, 0xbfb8aa3b, v56
	v_mul_f32_e32 v57, 0xbfb8aa3b, v57
	v_and_b32_e32 v75, 0xffff0000, v66
	v_exp_f32_e32 v56, v56
	v_exp_f32_e32 v57, v57
	v_cvt_pk_bf16_f32 v67, v76, v77
	v_lshlrev_b32_e32 v74, 16, v66
	v_mul_f32_e32 v94, v75, v75
	v_add_f32_e32 v50, v50, v58
	v_lshlrev_b32_e32 v76, 16, v67
	v_fmac_f32_e32 v94, v74, v74
	v_mul_f32_e32 v50, 0xbfb8aa3b, v50
	v_fmac_f32_e32 v94, v76, v76
	v_add_f32_e32 v54, 1.0, v54
	v_add_f32_e32 v55, 1.0, v55
	v_exp_f32_e32 v76, v50
	v_add_f32_e32 v50, v51, v59
	v_and_b32_e32 v77, 0xffff0000, v67
	v_rcp_f32_e32 v54, v54
	v_rcp_f32_e32 v55, v55
	v_add_f32_e32 v56, 1.0, v56
	v_add_f32_e32 v57, 1.0, v57
	v_mul_f32_e32 v50, 0xbfb8aa3b, v50
	v_add_f32_e32 v52, v52, v60
	v_add_f32_e32 v53, v53, v61
	v_fmac_f32_e32 v94, v77, v77
	v_rcp_f32_e32 v56, v56
	v_rcp_f32_e32 v57, v57
	v_exp_f32_e32 v77, v50
	v_mul_f32_e32 v52, 0xbfb8aa3b, v52
	v_mul_f32_e32 v53, 0xbfb8aa3b, v53
	v_exp_f32_e32 v52, v52
	v_exp_f32_e32 v53, v53
	v_lshlrev_b32_e32 v74, 16, v146
	v_and_b32_e32 v75, 0xffff0000, v146
	v_pk_mul_f32 v[54:55], v[54:55], v[74:75]
	v_lshlrev_b32_e32 v74, 16, v147
	v_and_b32_e32 v75, 0xffff0000, v147
	v_pk_mul_f32 v[50:51], v[56:57], v[74:75]
	v_add_f32_e32 v56, 1.0, v76
	v_add_f32_e32 v57, 1.0, v77
	v_rcp_f32_e32 v56, v56
	v_rcp_f32_e32 v57, v57
	v_add_f32_e32 v52, 1.0, v52
	v_add_f32_e32 v53, 1.0, v53
	v_cvt_pk_bf16_f32 v68, v86, v87
	v_rcp_f32_e32 v52, v52
	v_rcp_f32_e32 v53, v53
	v_lshlrev_b32_e32 v86, 16, v68
	v_cvt_pk_bf16_f32 v69, v88, v89
	v_and_b32_e32 v87, 0xffff0000, v68
	v_fmac_f32_e32 v94, v86, v86
	v_lshlrev_b32_e32 v74, 16, v148
	v_and_b32_e32 v75, 0xffff0000, v148
	v_lshlrev_b32_e32 v88, 16, v69
	v_fmac_f32_e32 v94, v87, v87
	v_pk_mul_f32 v[56:57], v[56:57], v[74:75]
	v_lshlrev_b32_e32 v74, 16, v149
	v_and_b32_e32 v75, 0xffff0000, v149
	v_and_b32_e32 v89, 0xffff0000, v69
	v_fmac_f32_e32 v94, v88, v88
	v_pk_mul_f32 v[74:75], v[52:53], v[74:75]
	v_cvt_pk_bf16_f32 v52, v54, v55
	v_fmac_f32_e32 v94, v89, v89
	v_cvt_pk_bf16_f32 v53, v50, v51
	v_lshlrev_b32_e32 v50, 16, v52
	v_and_b32_e32 v51, 0xffff0000, v52
	v_fmac_f32_e32 v94, v50, v50
	v_cvt_pk_bf16_f32 v54, v56, v57
	v_lshlrev_b32_e32 v56, 16, v53
	v_fmac_f32_e32 v94, v51, v51
	v_and_b32_e32 v57, 0xffff0000, v53
	v_fmac_f32_e32 v94, v56, v56
	v_cvt_pk_bf16_f32 v55, v74, v75
	v_lshlrev_b32_e32 v74, 16, v54
	v_fmac_f32_e32 v94, v57, v57
	v_and_b32_e32 v75, 0xffff0000, v54
	v_fmac_f32_e32 v94, v74, v74
	v_lshlrev_b32_e32 v76, 16, v55
	v_fmac_f32_e32 v94, v75, v75
	v_and_b32_e32 v77, 0xffff0000, v55
	v_fmac_f32_e32 v94, v76, v76
	v_fmac_f32_e32 v94, v77, v77
	s_nop 0
	v_lshlrev_b64 v[56:57], 11, v[232:233]
	v_lshl_add_u64 v[56:57], s[20:21], 0, v[56:57]
	v_lshl_add_u64 v[56:57], v[224:225], 1, v[56:57]
	global_store_dwordx4 v[56:57], v[66:69], off
	global_store_dwordx4 v[56:57], v[52:55], off offset:256
	s_waitcnt lgkmcnt(0)
	v_mov_b32_e32 v50, v94
	s_nop 1
	v_permlane16_swap_b32_e32 v50, v94
	v_add_f32_e32 v50, v94, v50
	v_mov_b32_e32 v51, v50
	s_nop 1
	v_permlane32_swap_b32_e32 v51, v50
	s_and_saveexec_b64 s[0:1], vcc
	s_cbranch_execz .LBB0_477
	s_waitcnt lgkmcnt(0)
	v_add_f32_e32 v50, v50, v51
	ds_write_b32 v218, v50 offset:256
.LBB0_477:
	s_or_b64 exec, exec, s[0:1]
	v_add_f32_e32 v46, v46, v82
	v_add_f32_e32 v47, v47, v83
	v_mul_f32_e32 v46, 0xbfb8aa3b, v46
	v_mul_f32_e32 v47, 0xbfb8aa3b, v47
	v_add_f32_e32 v48, v48, v84
	v_add_f32_e32 v49, v49, v85
	v_exp_f32_e32 v46, v46
	v_exp_f32_e32 v47, v47
	v_mul_f32_e32 v48, 0xbfb8aa3b, v48
	v_mul_f32_e32 v49, 0xbfb8aa3b, v49
	v_add_f32_e32 v42, v42, v70
	v_add_f32_e32 v43, v43, v71
	v_exp_f32_e32 v48, v48
	v_exp_f32_e32 v49, v49
	v_mul_f32_e32 v42, 0xbfb8aa3b, v42
	v_mul_f32_e32 v43, 0xbfb8aa3b, v43
	v_add_f32_e32 v44, v44, v72
	v_add_f32_e32 v45, v45, v73
	v_exp_f32_e32 v42, v42
	v_exp_f32_e32 v43, v43
	v_mul_f32_e32 v44, 0xbfb8aa3b, v44
	v_mul_f32_e32 v45, 0xbfb8aa3b, v45
	v_exp_f32_e32 v44, v44
	v_exp_f32_e32 v45, v45
	v_add_f32_e32 v46, 1.0, v46
	v_add_f32_e32 v47, 1.0, v47
	v_rcp_f32_e32 v46, v46
	v_rcp_f32_e32 v47, v47
	v_add_f32_e32 v48, 1.0, v48
	v_add_f32_e32 v49, 1.0, v49
	v_rcp_f32_e32 v48, v48
	v_rcp_f32_e32 v49, v49
	v_add_f32_e32 v42, 1.0, v42
	v_add_f32_e32 v43, 1.0, v43
	v_rcp_f32_e32 v42, v42
	v_rcp_f32_e32 v43, v43
	v_add_f32_e32 v44, 1.0, v44
	v_add_f32_e32 v45, 1.0, v45
	v_lshlrev_b32_e32 v50, 16, v134
	s_waitcnt lgkmcnt(0)
	v_and_b32_e32 v51, 0xffff0000, v134
	v_rcp_f32_e32 v44, v44
	v_rcp_f32_e32 v45, v45
	v_pk_mul_f32 v[46:47], v[46:47], v[50:51]
	v_lshlrev_b32_e32 v50, 16, v135
	v_and_b32_e32 v51, 0xffff0000, v135
	v_pk_mul_f32 v[48:49], v[48:49], v[50:51]
	v_lshlrev_b32_e32 v50, 16, v136
	v_and_b32_e32 v51, 0xffff0000, v136
	v_add_f32_e32 v38, v38, v62
	v_add_f32_e32 v39, v39, v63
	v_pk_mul_f32 v[50:51], v[42:43], v[50:51]
	v_lshlrev_b32_e32 v42, 16, v137
	v_and_b32_e32 v43, 0xffff0000, v137
	v_mul_f32_e32 v38, 0xbfb8aa3b, v38
	v_mul_f32_e32 v39, 0xbfb8aa3b, v39
	v_add_f32_e32 v40, v40, v64
	v_add_f32_e32 v41, v41, v65
	v_pk_mul_f32 v[52:53], v[44:45], v[42:43]
	v_cvt_pk_bf16_f32 v42, v46, v47
	v_exp_f32_e32 v38, v38
	v_exp_f32_e32 v39, v39
	v_mul_f32_e32 v40, 0xbfb8aa3b, v40
	v_mul_f32_e32 v41, 0xbfb8aa3b, v41
	v_and_b32_e32 v47, 0xffff0000, v42
	v_exp_f32_e32 v40, v40
	v_exp_f32_e32 v41, v41
	v_cvt_pk_bf16_f32 v43, v48, v49
	v_lshlrev_b32_e32 v46, 16, v42
	v_mul_f32_e32 v54, v47, v47
	v_add_f32_e32 v34, v34, v58
	v_lshlrev_b32_e32 v48, 16, v43
	v_fmac_f32_e32 v54, v46, v46
	v_mul_f32_e32 v34, 0xbfb8aa3b, v34
	v_fmac_f32_e32 v54, v48, v48
	v_add_f32_e32 v38, 1.0, v38
	v_add_f32_e32 v39, 1.0, v39
	v_exp_f32_e32 v48, v34
	v_add_f32_e32 v34, v35, v59
	v_and_b32_e32 v49, 0xffff0000, v43
	v_rcp_f32_e32 v38, v38
	v_rcp_f32_e32 v39, v39
	v_add_f32_e32 v40, 1.0, v40
	v_add_f32_e32 v41, 1.0, v41
	v_mul_f32_e32 v34, 0xbfb8aa3b, v34
	v_add_f32_e32 v36, v36, v60
	v_add_f32_e32 v37, v37, v61
	v_fmac_f32_e32 v54, v49, v49
	v_rcp_f32_e32 v40, v40
	v_rcp_f32_e32 v41, v41
	v_exp_f32_e32 v49, v34
	v_mul_f32_e32 v36, 0xbfb8aa3b, v36
	v_mul_f32_e32 v37, 0xbfb8aa3b, v37
	v_exp_f32_e32 v36, v36
	v_exp_f32_e32 v37, v37
	v_lshlrev_b32_e32 v46, 16, v122
	v_and_b32_e32 v47, 0xffff0000, v122
	v_pk_mul_f32 v[38:39], v[38:39], v[46:47]
	v_lshlrev_b32_e32 v46, 16, v123
	v_and_b32_e32 v47, 0xffff0000, v123
	v_pk_mul_f32 v[34:35], v[40:41], v[46:47]
	v_add_f32_e32 v40, 1.0, v48
	v_add_f32_e32 v41, 1.0, v49
	v_rcp_f32_e32 v40, v40
	v_rcp_f32_e32 v41, v41
	v_add_f32_e32 v36, 1.0, v36
	v_add_f32_e32 v37, 1.0, v37
	v_cvt_pk_bf16_f32 v44, v50, v51
	v_rcp_f32_e32 v36, v36
	v_rcp_f32_e32 v37, v37
	v_lshlrev_b32_e32 v50, 16, v44
	v_cvt_pk_bf16_f32 v45, v52, v53
	v_and_b32_e32 v51, 0xffff0000, v44
	v_fmac_f32_e32 v54, v50, v50
	v_lshlrev_b32_e32 v46, 16, v124
	v_and_b32_e32 v47, 0xffff0000, v124
	v_lshlrev_b32_e32 v52, 16, v45
	v_fmac_f32_e32 v54, v51, v51
	v_pk_mul_f32 v[40:41], v[40:41], v[46:47]
	v_lshlrev_b32_e32 v46, 16, v125
	v_and_b32_e32 v47, 0xffff0000, v125
	v_and_b32_e32 v53, 0xffff0000, v45
	v_fmac_f32_e32 v54, v52, v52
	v_pk_mul_f32 v[46:47], v[36:37], v[46:47]
	v_cvt_pk_bf16_f32 v36, v38, v39
	v_fmac_f32_e32 v54, v53, v53
	v_cvt_pk_bf16_f32 v37, v34, v35
	v_lshlrev_b32_e32 v34, 16, v36
	v_and_b32_e32 v35, 0xffff0000, v36
	v_fmac_f32_e32 v54, v34, v34
	v_cvt_pk_bf16_f32 v38, v40, v41
	v_lshlrev_b32_e32 v40, 16, v37
	v_fmac_f32_e32 v54, v35, v35
	v_and_b32_e32 v41, 0xffff0000, v37
	v_fmac_f32_e32 v54, v40, v40
	v_cvt_pk_bf16_f32 v39, v46, v47
	v_lshlrev_b32_e32 v46, 16, v38
	v_fmac_f32_e32 v54, v41, v41
	v_and_b32_e32 v47, 0xffff0000, v38
	v_fmac_f32_e32 v54, v46, v46
	v_lshlrev_b32_e32 v48, 16, v39
	v_fmac_f32_e32 v54, v47, v47
	v_and_b32_e32 v49, 0xffff0000, v39
	v_fmac_f32_e32 v54, v48, v48
	v_fmac_f32_e32 v54, v49, v49
	s_nop 0
	v_lshlrev_b64 v[40:41], 11, v[230:231]
	v_lshl_add_u64 v[40:41], s[20:21], 0, v[40:41]
	v_lshl_add_u64 v[40:41], v[224:225], 1, v[40:41]
	global_store_dwordx4 v[40:41], v[42:45], off
	global_store_dwordx4 v[40:41], v[36:39], off offset:256
	s_waitcnt lgkmcnt(0)
	v_mov_b32_e32 v34, v54
	s_nop 1
	v_permlane16_swap_b32_e32 v34, v54
	v_add_f32_e32 v34, v54, v34
	v_mov_b32_e32 v35, v34
	s_nop 1
	v_permlane32_swap_b32_e32 v35, v34
	s_and_saveexec_b64 s[0:1], vcc
	s_cbranch_execz .LBB0_479
	s_waitcnt lgkmcnt(0)
	v_add_f32_e32 v34, v34, v35
	ds_write_b32 v218, v34 offset:320
.LBB0_479:
	s_or_b64 exec, exec, s[0:1]
	v_add_f32_e32 v30, v30, v82
	v_add_f32_e32 v31, v31, v83
	v_mul_f32_e32 v30, 0xbfb8aa3b, v30
	v_mul_f32_e32 v31, 0xbfb8aa3b, v31
	v_add_f32_e32 v32, v32, v84
	v_add_f32_e32 v33, v33, v85
	v_exp_f32_e32 v30, v30
	v_exp_f32_e32 v31, v31
	v_mul_f32_e32 v32, 0xbfb8aa3b, v32
	v_mul_f32_e32 v33, 0xbfb8aa3b, v33
	v_add_f32_e32 v26, v26, v70
	v_add_f32_e32 v27, v27, v71
	v_exp_f32_e32 v32, v32
	v_exp_f32_e32 v33, v33
	v_mul_f32_e32 v26, 0xbfb8aa3b, v26
	v_mul_f32_e32 v27, 0xbfb8aa3b, v27
	v_add_f32_e32 v28, v28, v72
	v_add_f32_e32 v29, v29, v73
	v_exp_f32_e32 v26, v26
	v_exp_f32_e32 v27, v27
	v_mul_f32_e32 v28, 0xbfb8aa3b, v28
	v_mul_f32_e32 v29, 0xbfb8aa3b, v29
	v_exp_f32_e32 v28, v28
	v_exp_f32_e32 v29, v29
	v_add_f32_e32 v30, 1.0, v30
	v_add_f32_e32 v31, 1.0, v31
	v_rcp_f32_e32 v30, v30
	v_rcp_f32_e32 v31, v31
	v_add_f32_e32 v32, 1.0, v32
	v_add_f32_e32 v33, 1.0, v33
	v_rcp_f32_e32 v32, v32
	v_rcp_f32_e32 v33, v33
	v_add_f32_e32 v26, 1.0, v26
	v_add_f32_e32 v27, 1.0, v27
	v_rcp_f32_e32 v26, v26
	v_rcp_f32_e32 v27, v27
	v_add_f32_e32 v28, 1.0, v28
	v_add_f32_e32 v29, 1.0, v29
	v_lshlrev_b32_e32 v34, 16, v110
	s_waitcnt lgkmcnt(0)
	v_and_b32_e32 v35, 0xffff0000, v110
	v_rcp_f32_e32 v28, v28
	v_rcp_f32_e32 v29, v29
	v_pk_mul_f32 v[30:31], v[30:31], v[34:35]
	v_lshlrev_b32_e32 v34, 16, v111
	v_and_b32_e32 v35, 0xffff0000, v111
	v_pk_mul_f32 v[32:33], v[32:33], v[34:35]
	v_lshlrev_b32_e32 v34, 16, v112
	v_and_b32_e32 v35, 0xffff0000, v112
	v_add_f32_e32 v22, v22, v62
	v_add_f32_e32 v23, v23, v63
	v_pk_mul_f32 v[34:35], v[26:27], v[34:35]
	v_lshlrev_b32_e32 v26, 16, v113
	v_and_b32_e32 v27, 0xffff0000, v113
	v_mul_f32_e32 v22, 0xbfb8aa3b, v22
	v_mul_f32_e32 v23, 0xbfb8aa3b, v23
	v_add_f32_e32 v24, v24, v64
	v_add_f32_e32 v25, v25, v65
	v_pk_mul_f32 v[36:37], v[28:29], v[26:27]
	v_cvt_pk_bf16_f32 v26, v30, v31
	v_exp_f32_e32 v22, v22
	v_exp_f32_e32 v23, v23
	v_mul_f32_e32 v24, 0xbfb8aa3b, v24
	v_mul_f32_e32 v25, 0xbfb8aa3b, v25
	v_and_b32_e32 v31, 0xffff0000, v26
	v_exp_f32_e32 v24, v24
	v_exp_f32_e32 v25, v25
	v_cvt_pk_bf16_f32 v27, v32, v33
	v_lshlrev_b32_e32 v30, 16, v26
	v_mul_f32_e32 v38, v31, v31
	v_add_f32_e32 v18, v18, v58
	v_lshlrev_b32_e32 v32, 16, v27
	v_fmac_f32_e32 v38, v30, v30
	v_mul_f32_e32 v18, 0xbfb8aa3b, v18
	v_fmac_f32_e32 v38, v32, v32
	v_add_f32_e32 v22, 1.0, v22
	v_add_f32_e32 v23, 1.0, v23
	v_exp_f32_e32 v32, v18
	v_add_f32_e32 v18, v19, v59
	v_and_b32_e32 v33, 0xffff0000, v27
	v_rcp_f32_e32 v22, v22
	v_rcp_f32_e32 v23, v23
	v_add_f32_e32 v24, 1.0, v24
	v_add_f32_e32 v25, 1.0, v25
	v_mul_f32_e32 v18, 0xbfb8aa3b, v18
	v_add_f32_e32 v20, v20, v60
	v_add_f32_e32 v21, v21, v61
	v_fmac_f32_e32 v38, v33, v33
	v_rcp_f32_e32 v24, v24
	v_rcp_f32_e32 v25, v25
	v_exp_f32_e32 v33, v18
	v_mul_f32_e32 v20, 0xbfb8aa3b, v20
	v_mul_f32_e32 v21, 0xbfb8aa3b, v21
	v_exp_f32_e32 v20, v20
	v_exp_f32_e32 v21, v21
	v_lshlrev_b32_e32 v30, 16, v98
	v_and_b32_e32 v31, 0xffff0000, v98
	v_pk_mul_f32 v[22:23], v[22:23], v[30:31]
	v_lshlrev_b32_e32 v30, 16, v99
	v_and_b32_e32 v31, 0xffff0000, v99
	v_pk_mul_f32 v[18:19], v[24:25], v[30:31]
	v_add_f32_e32 v24, 1.0, v32
	v_add_f32_e32 v25, 1.0, v33
	v_rcp_f32_e32 v24, v24
	v_rcp_f32_e32 v25, v25
	v_add_f32_e32 v20, 1.0, v20
	v_add_f32_e32 v21, 1.0, v21
	v_cvt_pk_bf16_f32 v28, v34, v35
	v_rcp_f32_e32 v20, v20
	v_rcp_f32_e32 v21, v21
	v_lshlrev_b32_e32 v34, 16, v28
	v_cvt_pk_bf16_f32 v29, v36, v37
	v_and_b32_e32 v35, 0xffff0000, v28
	v_fmac_f32_e32 v38, v34, v34
	v_lshlrev_b32_e32 v30, 16, v100
	v_and_b32_e32 v31, 0xffff0000, v100
	v_lshlrev_b32_e32 v36, 16, v29
	v_fmac_f32_e32 v38, v35, v35
	v_pk_mul_f32 v[24:25], v[24:25], v[30:31]
	v_lshlrev_b32_e32 v30, 16, v101
	v_and_b32_e32 v31, 0xffff0000, v101
	v_and_b32_e32 v37, 0xffff0000, v29
	v_fmac_f32_e32 v38, v36, v36
	v_pk_mul_f32 v[30:31], v[20:21], v[30:31]
	v_cvt_pk_bf16_f32 v20, v22, v23
	v_fmac_f32_e32 v38, v37, v37
	v_cvt_pk_bf16_f32 v21, v18, v19
	v_lshlrev_b32_e32 v18, 16, v20
	v_and_b32_e32 v19, 0xffff0000, v20
	v_fmac_f32_e32 v38, v18, v18
	v_cvt_pk_bf16_f32 v22, v24, v25
	v_lshlrev_b32_e32 v24, 16, v21
	v_fmac_f32_e32 v38, v19, v19
	v_and_b32_e32 v25, 0xffff0000, v21
	v_fmac_f32_e32 v38, v24, v24
	v_cvt_pk_bf16_f32 v23, v30, v31
	v_lshlrev_b32_e32 v30, 16, v22
	v_fmac_f32_e32 v38, v25, v25
	v_and_b32_e32 v31, 0xffff0000, v22
	v_fmac_f32_e32 v38, v30, v30
	v_lshlrev_b32_e32 v32, 16, v23
	v_fmac_f32_e32 v38, v31, v31
	v_and_b32_e32 v33, 0xffff0000, v23
	v_fmac_f32_e32 v38, v32, v32
	v_fmac_f32_e32 v38, v33, v33
	s_nop 0
	v_lshlrev_b64 v[24:25], 11, v[228:229]
	v_lshl_add_u64 v[24:25], s[20:21], 0, v[24:25]
	v_lshl_add_u64 v[24:25], v[224:225], 1, v[24:25]
	global_store_dwordx4 v[24:25], v[26:29], off
	global_store_dwordx4 v[24:25], v[20:23], off offset:256
	s_waitcnt lgkmcnt(0)
	v_mov_b32_e32 v18, v38
	s_nop 1
	v_permlane16_swap_b32_e32 v18, v38
	v_add_f32_e32 v18, v38, v18
	v_mov_b32_e32 v19, v18
	s_nop 1
	v_permlane32_swap_b32_e32 v19, v18
	s_and_saveexec_b64 s[0:1], vcc
	s_cbranch_execz .LBB0_481
	s_waitcnt lgkmcnt(0)
	v_add_f32_e32 v18, v18, v19
	ds_write_b32 v218, v18 offset:384
.LBB0_481:
	s_or_b64 exec, exec, s[0:1]
	v_add_f32_e32 v14, v14, v82
	v_add_f32_e32 v15, v15, v83
	v_mul_f32_e32 v14, 0xbfb8aa3b, v14
	v_mul_f32_e32 v15, 0xbfb8aa3b, v15
	v_add_f32_e32 v16, v16, v84
	v_add_f32_e32 v17, v17, v85
	v_exp_f32_e32 v14, v14
	v_exp_f32_e32 v15, v15
	v_mul_f32_e32 v16, 0xbfb8aa3b, v16
	v_mul_f32_e32 v17, 0xbfb8aa3b, v17
	v_add_f32_e32 v10, v10, v70
	v_add_f32_e32 v11, v11, v71
	v_exp_f32_e32 v16, v16
	v_exp_f32_e32 v17, v17
	v_mul_f32_e32 v10, 0xbfb8aa3b, v10
	v_mul_f32_e32 v11, 0xbfb8aa3b, v11
	v_add_f32_e32 v12, v12, v72
	v_add_f32_e32 v13, v13, v73
	v_exp_f32_e32 v10, v10
	v_exp_f32_e32 v11, v11
	v_mul_f32_e32 v12, 0xbfb8aa3b, v12
	v_mul_f32_e32 v13, 0xbfb8aa3b, v13
	v_exp_f32_e32 v12, v12
	v_exp_f32_e32 v13, v13
	v_add_f32_e32 v14, 1.0, v14
	v_add_f32_e32 v15, 1.0, v15
	v_rcp_f32_e32 v14, v14
	v_rcp_f32_e32 v15, v15
	v_add_f32_e32 v16, 1.0, v16
	v_add_f32_e32 v17, 1.0, v17
	v_rcp_f32_e32 v16, v16
	v_rcp_f32_e32 v17, v17
	v_add_f32_e32 v10, 1.0, v10
	v_add_f32_e32 v11, 1.0, v11
	v_rcp_f32_e32 v10, v10
	v_rcp_f32_e32 v11, v11
	v_add_f32_e32 v12, 1.0, v12
	v_add_f32_e32 v13, 1.0, v13
	v_lshlrev_b32_e32 v18, 16, v90
	s_waitcnt lgkmcnt(0)
	v_and_b32_e32 v19, 0xffff0000, v90
	v_rcp_f32_e32 v12, v12
	v_rcp_f32_e32 v13, v13
	v_pk_mul_f32 v[14:15], v[14:15], v[18:19]
	v_lshlrev_b32_e32 v18, 16, v91
	v_and_b32_e32 v19, 0xffff0000, v91
	v_pk_mul_f32 v[16:17], v[16:17], v[18:19]
	v_lshlrev_b32_e32 v18, 16, v92
	v_and_b32_e32 v19, 0xffff0000, v92
	v_add_f32_e32 v6, v6, v62
	v_add_f32_e32 v7, v7, v63
	v_pk_mul_f32 v[18:19], v[10:11], v[18:19]
	v_lshlrev_b32_e32 v10, 16, v93
	v_and_b32_e32 v11, 0xffff0000, v93
	v_mul_f32_e32 v6, 0xbfb8aa3b, v6
	v_mul_f32_e32 v7, 0xbfb8aa3b, v7
	v_add_f32_e32 v8, v8, v64
	v_add_f32_e32 v9, v9, v65
	v_pk_mul_f32 v[20:21], v[12:13], v[10:11]
	v_cvt_pk_bf16_f32 v10, v14, v15
	v_exp_f32_e32 v6, v6
	v_exp_f32_e32 v7, v7
	v_mul_f32_e32 v8, 0xbfb8aa3b, v8
	v_mul_f32_e32 v9, 0xbfb8aa3b, v9
	v_and_b32_e32 v15, 0xffff0000, v10
	v_exp_f32_e32 v8, v8
	v_exp_f32_e32 v9, v9
	v_cvt_pk_bf16_f32 v11, v16, v17
	v_lshlrev_b32_e32 v14, 16, v10
	v_mul_f32_e32 v22, v15, v15
	v_add_f32_e32 v2, v2, v58
	v_lshlrev_b32_e32 v16, 16, v11
	v_fmac_f32_e32 v22, v14, v14
	v_mul_f32_e32 v2, 0xbfb8aa3b, v2
	v_fmac_f32_e32 v22, v16, v16
	v_add_f32_e32 v6, 1.0, v6
	v_add_f32_e32 v7, 1.0, v7
	v_exp_f32_e32 v16, v2
	v_add_f32_e32 v2, v3, v59
	v_and_b32_e32 v17, 0xffff0000, v11
	v_rcp_f32_e32 v6, v6
	v_rcp_f32_e32 v7, v7
	v_add_f32_e32 v8, 1.0, v8
	v_add_f32_e32 v9, 1.0, v9
	v_mul_f32_e32 v2, 0xbfb8aa3b, v2
	v_add_f32_e32 v4, v4, v60
	v_add_f32_e32 v5, v5, v61
	v_fmac_f32_e32 v22, v17, v17
	v_rcp_f32_e32 v8, v8
	v_rcp_f32_e32 v9, v9
	v_exp_f32_e32 v17, v2
	v_mul_f32_e32 v4, 0xbfb8aa3b, v4
	v_mul_f32_e32 v5, 0xbfb8aa3b, v5
	v_exp_f32_e32 v4, v4
	v_exp_f32_e32 v5, v5
	v_lshlrev_b32_e32 v14, 16, v78
	v_and_b32_e32 v15, 0xffff0000, v78
	v_pk_mul_f32 v[6:7], v[6:7], v[14:15]
	v_lshlrev_b32_e32 v14, 16, v79
	v_and_b32_e32 v15, 0xffff0000, v79
	v_pk_mul_f32 v[2:3], v[8:9], v[14:15]
	v_add_f32_e32 v8, 1.0, v16
	v_add_f32_e32 v9, 1.0, v17
	v_rcp_f32_e32 v8, v8
	v_rcp_f32_e32 v9, v9
	v_add_f32_e32 v4, 1.0, v4
	v_add_f32_e32 v5, 1.0, v5
	v_cvt_pk_bf16_f32 v12, v18, v19
	v_rcp_f32_e32 v4, v4
	v_rcp_f32_e32 v5, v5
	v_lshlrev_b32_e32 v18, 16, v12
	v_cvt_pk_bf16_f32 v13, v20, v21
	v_and_b32_e32 v19, 0xffff0000, v12
	v_fmac_f32_e32 v22, v18, v18
	v_lshlrev_b32_e32 v14, 16, v80
	v_and_b32_e32 v15, 0xffff0000, v80
	v_lshlrev_b32_e32 v20, 16, v13
	v_fmac_f32_e32 v22, v19, v19
	v_pk_mul_f32 v[8:9], v[8:9], v[14:15]
	v_lshlrev_b32_e32 v14, 16, v81
	v_and_b32_e32 v15, 0xffff0000, v81
	v_and_b32_e32 v21, 0xffff0000, v13
	v_fmac_f32_e32 v22, v20, v20
	v_pk_mul_f32 v[14:15], v[4:5], v[14:15]
	v_cvt_pk_bf16_f32 v4, v6, v7
	v_fmac_f32_e32 v22, v21, v21
	v_cvt_pk_bf16_f32 v5, v2, v3
	v_lshlrev_b32_e32 v2, 16, v4
	v_and_b32_e32 v3, 0xffff0000, v4
	v_fmac_f32_e32 v22, v2, v2
	v_cvt_pk_bf16_f32 v6, v8, v9
	v_lshlrev_b32_e32 v8, 16, v5
	v_fmac_f32_e32 v22, v3, v3
	v_and_b32_e32 v9, 0xffff0000, v5
	v_fmac_f32_e32 v22, v8, v8
	v_cvt_pk_bf16_f32 v7, v14, v15
	v_lshlrev_b32_e32 v14, 16, v6
	v_fmac_f32_e32 v22, v9, v9
	v_and_b32_e32 v15, 0xffff0000, v6
	v_fmac_f32_e32 v22, v14, v14
	v_lshlrev_b32_e32 v16, 16, v7
	v_fmac_f32_e32 v22, v15, v15
	v_and_b32_e32 v17, 0xffff0000, v7
	v_fmac_f32_e32 v22, v16, v16
	v_fmac_f32_e32 v22, v17, v17
	s_nop 0
	v_lshlrev_b64 v[8:9], 11, v[226:227]
	v_lshl_add_u64 v[8:9], s[20:21], 0, v[8:9]
	v_lshl_add_u64 v[8:9], v[224:225], 1, v[8:9]
	global_store_dwordx4 v[8:9], v[10:13], off
	global_store_dwordx4 v[8:9], v[4:7], off offset:256
	s_waitcnt lgkmcnt(0)
	v_mov_b32_e32 v2, v22
	s_nop 1
	v_permlane16_swap_b32_e32 v2, v22
	v_add_f32_e32 v2, v22, v2
	v_mov_b32_e32 v3, v2
	s_nop 1
	v_permlane32_swap_b32_e32 v3, v2
	s_and_saveexec_b64 s[0:1], vcc
	s_cbranch_execz .LBB0_483
	s_waitcnt lgkmcnt(0)
	v_add_f32_e32 v2, v2, v3
	ds_write_b32 v218, v2 offset:448

.LBB0_862:
	s_lshl_b32 s0, s40, 8
	v_mov_b32_e32 v170, v210
	v_mov_b32_e32 v171, v211
	s_or_b32 s0, s0, s74
	v_and_b32_e32 v181, 64, v217
	v_lshl_add_u32 v0, v171, 3, s0
	s_ashr_i32 s0, s80, 31
	s_lshr_b32 s0, s0, 29
	s_add_i32 s0, s80, s0
	s_ashr_i32 s0, s0, 3
	s_mul_i32 s42, s0, 3
	s_ashr_i32 s43, s42, 31
	s_lshl_b64 s[0:1], s[42:43], 12
	s_add_u32 s0, s66, s0
	v_ashrrev_i32_e32 v1, 31, v0
	s_addc_u32 s1, s67, s1
	v_lshlrev_b64 v[182:183], 2, v[0:1]
	s_lshl_b32 s12, s80, 8
	v_add_u32_e32 v220, s73, v170
	v_lshl_add_u64 v[118:119], s[0:1], 0, v[182:183]
	v_add_u32_e32 v172, s12, v220
	v_readlane_b32 s0, v255, 0
	v_readlane_b32 s1, v255, 1
	v_ashrrev_i32_e32 v173, 31, v172
	v_lshlrev_b64 v[176:177], 12, v[172:173]
	v_lshl_add_u64 v[188:189], s[0:1], 0, v[182:183]
	v_lshl_add_u64 v[146:147], v[188:189], 0, v[176:177]
	global_load_dwordx4 v[184:187], v[146:147], off
	global_load_dwordx4 v[110:113], v[118:119], off
	global_load_dwordx4 v[106:109], v[118:119], off offset:16
	global_load_dwordx4 v[190:193], v[146:147], off offset:16
	global_load_dwordx4 v[194:197], v[146:147], off offset:512
	global_load_dwordx4 v[126:129], v[118:119], off offset:512
	s_nop 0
	global_load_dwordx4 v[118:121], v[118:119], off offset:528
	s_nop 0
	global_load_dwordx4 v[198:201], v[146:147], off offset:528
	v_add_u32_e32 v174, 16, v172
	v_ashrrev_i32_e32 v175, 31, v174
	v_lshlrev_b64 v[178:179], 12, v[174:175]
	v_lshl_add_u64 v[150:151], v[188:189], 0, v[178:179]
	global_load_dwordx4 v[154:157], v[150:151], off offset:16
	global_load_dwordx4 v[158:161], v[150:151], off
	global_load_dwordx4 v[146:149], v[150:151], off offset:528
	s_nop 0
	global_load_dwordx4 v[150:153], v[150:151], off offset:512
	v_xor_b32_e32 v180, 16, v217
	v_add_u32_e32 v181, 64, v181
	v_xor_b32_e32 v202, 32, v217
	v_cmp_lt_i32_e32 vcc, v180, v181
	v_lshl_add_u32 v221, v170, 2, s77
	s_mov_b64 s[0:1], 0x100
	v_cndmask_b32_e32 v180, v217, v180, vcc
	v_cmp_lt_i32_e32 vcc, v202, v181
	v_lshlrev_b32_e32 v223, 2, v180
	s_waitcnt vmcnt(0)
	v_pk_fma_f32 v[144:145], v[144:145], v[112:113], v[186:187]
	v_cndmask_b32_e32 v181, v217, v202, vcc
	v_cmp_eq_u32_e32 vcc, 0, v171
	v_lshlrev_b64 v[170:171], 1, v[0:1]
	v_lshl_add_u64 v[0:1], s[8:9], 0, v[176:177]
	v_pk_fma_f32 v[176:177], v[142:143], v[110:111], v[184:185]
	v_pk_fma_f32 v[142:143], v[138:139], v[106:107], v[190:191]
	v_pk_fma_f32 v[140:141], v[140:141], v[108:109], v[192:193]
	v_pk_fma_f32 v[138:139], v[134:135], v[126:127], v[194:195]
	v_pk_fma_f32 v[134:135], v[136:137], v[128:129], v[196:197]
	v_pk_mul_f32 v[136:137], v[176:177], v[176:177]
	v_pk_mul_f32 v[190:191], v[144:145], v[144:145]
	v_pk_mul_f32 v[192:193], v[142:143], v[142:143]
	v_pk_mul_f32 v[194:195], v[140:141], v[140:141]
	v_pk_fma_f32 v[130:131], v[130:131], v[118:119], v[198:199]
	v_pk_fma_f32 v[132:133], v[132:133], v[120:121], v[200:201]
	v_pk_mul_f32 v[196:197], v[138:139], v[138:139]
	v_pk_mul_f32 v[198:199], v[134:135], v[134:135]
	v_add_f32_e32 v194, v194, v195
	v_add_f32_e32 v192, v192, v193
	v_add_f32_e32 v190, v190, v191
	v_add_f32_e32 v136, v136, v137
	v_pk_mul_f32 v[200:201], v[130:131], v[130:131]
	v_pk_mul_f32 v[202:203], v[132:133], v[132:133]
	v_add_f32_e32 v137, v198, v199
	v_add_f32_e32 v191, v196, v197
	v_add_f32_e32 v192, v192, v194
	v_add_f32_e32 v136, v136, v190
	v_add_f32_e32 v193, v202, v203
	v_add_f32_e32 v195, v200, v201
	v_add_f32_e32 v137, v191, v137
	v_add_f32_e32 v136, v136, v192
	v_add_f32_e32 v136, v136, v137
	v_add_f32_e32 v137, v195, v193
	v_add_f32_e32 v136, v136, v137
	s_nop 0
	v_lshlrev_b32_e32 v222, 2, v181
	v_lshl_add_u64 v[180:181], v[0:1], 0, v[170:171]
	v_cvt_pk_bf16_f32 v184, v176, v177
	v_cvt_pk_bf16_f32 v185, v144, v145
	s_waitcnt lgkmcnt(0)
	v_mov_b32_e32 v137, v136
	s_nop 1
	v_permlane16_swap_b32_e32 v137, v136
	v_add_f32_e32 v136, v136, v137
	v_mov_b32_e32 v137, v136
	s_nop 1
	v_permlane32_swap_b32_e32 v137, v136
	v_cvt_pk_bf16_f32 v186, v142, v143
	v_cvt_pk_bf16_f32 v187, v140, v141
	v_lshl_add_u64 v[190:191], v[170:171], 0, s[0:1]
	global_store_dwordx4 v[180:181], v[184:187], off
	v_lshl_add_u64 v[0:1], v[0:1], 0, v[190:191]
	s_nop 0
	v_cvt_pk_bf16_f32 v184, v138, v139
	v_cvt_pk_bf16_f32 v185, v134, v135
	v_cvt_pk_bf16_f32 v186, v130, v131
	v_cvt_pk_bf16_f32 v187, v132, v133
	global_store_dwordx4 v[0:1], v[184:187], off
	s_and_saveexec_b64 s[0:1], vcc
	s_cbranch_execz .LBB0_864
	s_waitcnt lgkmcnt(0)
	v_add_f32_e32 v0, v136, v137
	ds_write_b32 v221, v0
.LBB0_864:
	s_or_b64 exec, exec, s[0:1]
	s_waitcnt lgkmcnt(0)
	v_pk_fma_f32 v[136:137], v[122:123], v[110:111], v[158:159]
	v_pk_fma_f32 v[158:159], v[124:125], v[112:113], v[160:161]
	v_pk_fma_f32 v[150:151], v[102:103], v[126:127], v[150:151]
	v_pk_fma_f32 v[152:153], v[104:105], v[128:129], v[152:153]
	v_pk_mul_f32 v[0:1], v[136:137], v[136:137]
	v_pk_mul_f32 v[122:123], v[158:159], v[158:159]
	v_pk_fma_f32 v[154:155], v[114:115], v[106:107], v[154:155]
	v_pk_fma_f32 v[156:157], v[116:117], v[108:109], v[156:157]
	v_pk_mul_f32 v[102:103], v[150:151], v[150:151]
	v_pk_mul_f32 v[104:105], v[152:153], v[152:153]
	v_pk_mul_f32 v[124:125], v[154:155], v[154:155]
	v_pk_mul_f32 v[160:161], v[156:157], v[156:157]
	v_add_f32_e32 v102, v102, v103
	v_add_f32_e32 v103, v104, v105
	v_add_f32_e32 v0, v0, v1
	v_add_f32_e32 v1, v122, v123
	v_pk_fma_f32 v[146:147], v[98:99], v[118:119], v[146:147]
	v_pk_fma_f32 v[148:149], v[100:101], v[120:121], v[148:149]
	v_add_f32_e32 v102, v102, v103
	v_add_f32_e32 v0, v0, v1
	v_add_f32_e32 v1, v160, v161
	v_add_f32_e32 v103, v124, v125
	v_pk_mul_f32 v[98:99], v[146:147], v[146:147]
	v_pk_mul_f32 v[100:101], v[148:149], v[148:149]
	v_add_f32_e32 v1, v103, v1
	v_add_f32_e32 v0, v0, v1
	v_add_f32_e32 v1, v100, v101
	v_add_f32_e32 v98, v98, v99
	v_lshl_add_u64 v[178:179], s[8:9], 0, v[178:179]
	v_add_f32_e32 v0, v0, v102
	v_add_f32_e32 v1, v98, v1
	v_add_f32_e32 v102, v0, v1
	v_cvt_pk_bf16_f32 v98, v150, v151
	v_cvt_pk_bf16_f32 v99, v152, v153
	v_cvt_pk_bf16_f32 v100, v146, v147
	v_cvt_pk_bf16_f32 v101, v148, v149
	v_lshl_add_u64 v[0:1], v[178:179], 0, v[190:191]
	global_store_dwordx4 v[0:1], v[98:101], off
	s_nop 0
	v_cvt_pk_bf16_f32 v114, v136, v137
	v_cvt_pk_bf16_f32 v115, v158, v159
	v_cvt_pk_bf16_f32 v116, v154, v155
	v_cvt_pk_bf16_f32 v117, v156, v157
	s_waitcnt lgkmcnt(0)
	v_mov_b32_e32 v0, v102
	v_mov_b32_e32 v98, v102
	s_nop 1
	v_permlane16_swap_b32_e32 v0, v98
	v_add_f32_e32 v98, v98, v0
	v_mov_b32_e32 v99, v98
	s_nop 1
	v_permlane32_swap_b32_e32 v99, v98
	v_lshl_add_u64 v[180:181], v[178:179], 0, v[170:171]
	global_store_dwordx4 v[180:181], v[114:117], off
	s_and_saveexec_b64 s[0:1], vcc
	s_cbranch_execz .LBB0_866
	s_waitcnt lgkmcnt(0)
	v_add_f32_e32 v0, v98, v99
	ds_write_b32 v221, v0 offset:64
.LBB0_866:
	s_or_b64 exec, exec, s[0:1]
	v_add_u32_e32 v160, 32, v172
	v_ashrrev_i32_e32 v161, 31, v160
	v_lshlrev_b64 v[0:1], 12, v[160:161]
	s_waitcnt lgkmcnt(0)
	v_lshl_add_u64 v[98:99], v[188:189], 0, v[0:1]
	global_load_dwordx4 v[192:195], v[98:99], off
	global_load_dwordx4 v[196:199], v[98:99], off offset:16
	global_load_dwordx4 v[200:203], v[98:99], off offset:512
	global_load_dwordx4 v[204:207], v[98:99], off offset:528
	v_add_u32_e32 v178, 48, v172
	v_ashrrev_i32_e32 v179, 31, v178
	v_lshlrev_b64 v[184:185], 12, v[178:179]
	v_lshl_add_u64 v[102:103], v[188:189], 0, v[184:185]
	global_load_dwordx4 v[114:117], v[102:103], off offset:16
	global_load_dwordx4 v[122:125], v[102:103], off
	global_load_dwordx4 v[98:101], v[102:103], off offset:528
	s_nop 0
	global_load_dwordx4 v[102:105], v[102:103], off offset:512
	v_lshl_add_u64 v[0:1], s[8:9], 0, v[0:1]
	s_waitcnt vmcnt(7)
	v_pk_fma_f32 v[180:181], v[94:95], v[110:111], v[192:193]
	v_pk_fma_f32 v[96:97], v[96:97], v[112:113], v[194:195]
	s_waitcnt vmcnt(6)
	v_pk_fma_f32 v[94:95], v[90:91], v[106:107], v[196:197]
	v_pk_fma_f32 v[90:91], v[92:93], v[108:109], v[198:199]
	s_waitcnt vmcnt(5)
	v_pk_fma_f32 v[86:87], v[86:87], v[126:127], v[200:201]
	v_pk_fma_f32 v[88:89], v[88:89], v[128:129], v[202:203]
	v_pk_mul_f32 v[92:93], v[180:181], v[180:181]
	v_pk_mul_f32 v[186:187], v[96:97], v[96:97]
	v_pk_mul_f32 v[196:197], v[94:95], v[94:95]
	v_pk_mul_f32 v[198:199], v[90:91], v[90:91]
	s_waitcnt vmcnt(4)
	v_pk_fma_f32 v[82:83], v[82:83], v[118:119], v[204:205]
	v_pk_fma_f32 v[84:85], v[84:85], v[120:121], v[206:207]
	v_pk_mul_f32 v[200:201], v[86:87], v[86:87]
	v_pk_mul_f32 v[202:203], v[88:89], v[88:89]
	v_add_f32_e32 v198, v198, v199
	v_add_f32_e32 v196, v196, v197
	v_add_f32_e32 v186, v186, v187
	v_add_f32_e32 v92, v92, v93
	v_pk_mul_f32 v[204:205], v[82:83], v[82:83]
	v_pk_mul_f32 v[206:207], v[84:85], v[84:85]
	v_add_f32_e32 v93, v202, v203
	v_add_f32_e32 v187, v200, v201
	v_add_f32_e32 v196, v196, v198
	v_add_f32_e32 v92, v92, v186
	v_add_f32_e32 v197, v206, v207
	v_add_f32_e32 v199, v204, v205
	v_add_f32_e32 v93, v187, v93
	v_add_f32_e32 v92, v92, v196
	v_add_f32_e32 v92, v92, v93
	v_add_f32_e32 v93, v199, v197
	v_add_f32_e32 v186, v92, v93
	s_nop 0
	v_cvt_pk_bf16_f32 v192, v180, v181
	v_cvt_pk_bf16_f32 v193, v96, v97
	v_cvt_pk_bf16_f32 v194, v94, v95
	v_cvt_pk_bf16_f32 v195, v90, v91
	v_lshl_add_u64 v[92:93], v[0:1], 0, v[170:171]
	global_store_dwordx4 v[92:93], v[192:195], off
	s_waitcnt lgkmcnt(0)
	v_mov_b32_e32 v187, v186
	v_mov_b32_e32 v92, v186
	s_nop 1
	v_permlane16_swap_b32_e32 v187, v92
	v_add_f32_e32 v92, v92, v187
	v_mov_b32_e32 v93, v92
	s_nop 1
	v_permlane32_swap_b32_e32 v93, v92
	v_cvt_pk_bf16_f32 v192, v86, v87
	v_cvt_pk_bf16_f32 v193, v88, v89
	v_cvt_pk_bf16_f32 v194, v82, v83
	v_cvt_pk_bf16_f32 v195, v84, v85
	v_lshl_add_u64 v[0:1], v[0:1], 0, v[190:191]
	global_store_dwordx4 v[0:1], v[192:195], off
	s_and_saveexec_b64 s[0:1], vcc
	s_cbranch_execz .LBB0_868
	s_waitcnt lgkmcnt(0)
	v_add_f32_e32 v0, v92, v93
	ds_write_b32 v221, v0 offset:128
.LBB0_868:
	s_or_b64 exec, exec, s[0:1]
	s_waitcnt vmcnt(4) lgkmcnt(0)
	v_pk_fma_f32 v[92:93], v[78:79], v[110:111], v[122:123]
	v_pk_fma_f32 v[122:123], v[80:81], v[112:113], v[124:125]
	s_waitcnt vmcnt(2)
	v_pk_fma_f32 v[102:103], v[70:71], v[126:127], v[102:103]
	v_pk_fma_f32 v[104:105], v[72:73], v[128:129], v[104:105]
	v_pk_mul_f32 v[0:1], v[92:93], v[92:93]
	v_pk_mul_f32 v[78:79], v[122:123], v[122:123]
	v_pk_fma_f32 v[114:115], v[74:75], v[106:107], v[114:115]
	v_pk_fma_f32 v[116:117], v[76:77], v[108:109], v[116:117]
	v_pk_mul_f32 v[70:71], v[102:103], v[102:103]
	v_pk_mul_f32 v[72:73], v[104:105], v[104:105]
	v_pk_mul_f32 v[80:81], v[114:115], v[114:115]
	v_pk_mul_f32 v[124:125], v[116:117], v[116:117]
	v_add_f32_e32 v70, v70, v71
	v_add_f32_e32 v71, v72, v73
	v_add_f32_e32 v0, v0, v1
	v_add_f32_e32 v1, v78, v79
	v_pk_fma_f32 v[98:99], v[66:67], v[118:119], v[98:99]
	v_pk_fma_f32 v[100:101], v[68:69], v[120:121], v[100:101]
	v_add_f32_e32 v70, v70, v71
	v_add_f32_e32 v0, v0, v1
	v_add_f32_e32 v1, v124, v125
	v_add_f32_e32 v71, v80, v81
	v_pk_mul_f32 v[66:67], v[98:99], v[98:99]
	v_pk_mul_f32 v[68:69], v[100:101], v[100:101]
	v_add_f32_e32 v1, v71, v1
	v_add_f32_e32 v0, v0, v1
	v_add_f32_e32 v1, v68, v69
	v_add_f32_e32 v66, v66, v67
	v_lshl_add_u64 v[184:185], s[8:9], 0, v[184:185]
	v_add_f32_e32 v0, v0, v70
	v_add_f32_e32 v1, v66, v1
	v_add_f32_e32 v70, v0, v1
	v_cvt_pk_bf16_f32 v66, v102, v103
	v_cvt_pk_bf16_f32 v67, v104, v105
	v_cvt_pk_bf16_f32 v68, v98, v99
	v_cvt_pk_bf16_f32 v69, v100, v101
	v_lshl_add_u64 v[0:1], v[184:185], 0, v[190:191]
	global_store_dwordx4 v[0:1], v[66:69], off
	s_nop 0
	v_cvt_pk_bf16_f32 v74, v92, v93
	v_cvt_pk_bf16_f32 v75, v122, v123
	v_cvt_pk_bf16_f32 v76, v114, v115
	v_cvt_pk_bf16_f32 v77, v116, v117
	s_waitcnt lgkmcnt(0)
	v_mov_b32_e32 v0, v70
	v_mov_b32_e32 v66, v70
	s_nop 1
	v_permlane16_swap_b32_e32 v0, v66
	v_add_f32_e32 v66, v66, v0
	v_mov_b32_e32 v67, v66
	s_nop 1
	v_permlane32_swap_b32_e32 v67, v66
	v_lshl_add_u64 v[186:187], v[184:185], 0, v[170:171]
	global_store_dwordx4 v[186:187], v[74:77], off
	s_and_saveexec_b64 s[0:1], vcc
	s_cbranch_execz .LBB0_870
	s_waitcnt lgkmcnt(0)
	v_add_f32_e32 v0, v66, v67
	ds_write_b32 v221, v0 offset:192
.LBB0_870:
	s_or_b64 exec, exec, s[0:1]
	v_add_u32_e32 v124, 0x80, v172
	v_ashrrev_i32_e32 v125, 31, v124
	v_lshlrev_b64 v[0:1], 12, v[124:125]
	s_waitcnt lgkmcnt(0)
	v_lshl_add_u64 v[66:67], v[188:189], 0, v[0:1]
	global_load_dwordx4 v[194:197], v[66:67], off
	global_load_dwordx4 v[198:201], v[66:67], off offset:16
	global_load_dwordx4 v[202:205], v[66:67], off offset:512
	global_load_dwordx4 v[206:209], v[66:67], off offset:528
	v_add_u32_e32 v184, 0x90, v172
	v_ashrrev_i32_e32 v185, 31, v184
	v_lshlrev_b64 v[192:193], 12, v[184:185]
	v_lshl_add_u64 v[70:71], v[188:189], 0, v[192:193]
	global_load_dwordx4 v[74:77], v[70:71], off offset:16
	global_load_dwordx4 v[78:81], v[70:71], off
	global_load_dwordx4 v[66:69], v[70:71], off offset:528
	s_nop 0
	global_load_dwordx4 v[70:73], v[70:71], off offset:512
	v_lshl_add_u64 v[0:1], s[8:9], 0, v[0:1]
	s_waitcnt vmcnt(7)
	v_pk_fma_f32 v[186:187], v[62:63], v[110:111], v[194:195]
	v_pk_fma_f32 v[64:65], v[64:65], v[112:113], v[196:197]
	s_waitcnt vmcnt(6)
	v_pk_fma_f32 v[62:63], v[58:59], v[106:107], v[198:199]
	v_pk_fma_f32 v[58:59], v[60:61], v[108:109], v[200:201]
	s_waitcnt vmcnt(5)
	v_pk_fma_f32 v[54:55], v[54:55], v[126:127], v[202:203]
	v_pk_fma_f32 v[56:57], v[56:57], v[128:129], v[204:205]
	v_pk_mul_f32 v[60:61], v[186:187], v[186:187]
	v_pk_mul_f32 v[198:199], v[64:65], v[64:65]
	v_pk_mul_f32 v[200:201], v[62:63], v[62:63]
	v_pk_mul_f32 v[202:203], v[58:59], v[58:59]
	s_waitcnt vmcnt(4)
	v_pk_fma_f32 v[50:51], v[50:51], v[118:119], v[206:207]
	v_pk_fma_f32 v[52:53], v[52:53], v[120:121], v[208:209]
	v_pk_mul_f32 v[204:205], v[54:55], v[54:55]
	v_pk_mul_f32 v[206:207], v[56:57], v[56:57]
	v_add_f32_e32 v202, v202, v203
	v_add_f32_e32 v200, v200, v201
	v_add_f32_e32 v198, v198, v199
	v_add_f32_e32 v60, v60, v61
	v_pk_mul_f32 v[208:209], v[50:51], v[50:51]
	v_pk_mul_f32 v[224:225], v[52:53], v[52:53]
	v_add_f32_e32 v61, v206, v207
	v_add_f32_e32 v199, v204, v205
	v_add_f32_e32 v200, v200, v202
	v_add_f32_e32 v60, v60, v198
	v_add_f32_e32 v201, v224, v225
	v_add_f32_e32 v203, v208, v209
	v_add_f32_e32 v61, v199, v61
	v_add_f32_e32 v60, v60, v200
	v_add_f32_e32 v60, v60, v61
	v_add_f32_e32 v61, v203, v201
	v_add_f32_e32 v198, v60, v61
	s_nop 0
	v_cvt_pk_bf16_f32 v194, v186, v187
	v_cvt_pk_bf16_f32 v195, v64, v65
	v_cvt_pk_bf16_f32 v196, v62, v63
	v_cvt_pk_bf16_f32 v197, v58, v59
	v_lshl_add_u64 v[60:61], v[0:1], 0, v[170:171]
	global_store_dwordx4 v[60:61], v[194:197], off
	s_waitcnt lgkmcnt(0)
	v_mov_b32_e32 v199, v198
	v_mov_b32_e32 v60, v198
	s_nop 1
	v_permlane16_swap_b32_e32 v199, v60
	v_add_f32_e32 v60, v60, v199
	v_mov_b32_e32 v61, v60
	s_nop 1
	v_permlane32_swap_b32_e32 v61, v60
	v_cvt_pk_bf16_f32 v194, v54, v55
	v_cvt_pk_bf16_f32 v195, v56, v57
	v_cvt_pk_bf16_f32 v196, v50, v51
	v_cvt_pk_bf16_f32 v197, v52, v53
	v_lshl_add_u64 v[0:1], v[0:1], 0, v[190:191]
	global_store_dwordx4 v[0:1], v[194:197], off
	s_and_saveexec_b64 s[0:1], vcc
	s_cbranch_execz .LBB0_872
	s_waitcnt lgkmcnt(0)
	v_add_f32_e32 v0, v60, v61
	ds_write_b32 v221, v0 offset:256
.LBB0_872:
	s_or_b64 exec, exec, s[0:1]
	s_waitcnt vmcnt(4) lgkmcnt(0)
	v_pk_fma_f32 v[60:61], v[46:47], v[110:111], v[78:79]
	v_pk_fma_f32 v[78:79], v[48:49], v[112:113], v[80:81]
	s_waitcnt vmcnt(2)
	v_pk_fma_f32 v[70:71], v[38:39], v[126:127], v[70:71]
	v_pk_fma_f32 v[72:73], v[40:41], v[128:129], v[72:73]
	v_pk_mul_f32 v[0:1], v[60:61], v[60:61]
	v_pk_mul_f32 v[46:47], v[78:79], v[78:79]
	v_pk_fma_f32 v[74:75], v[42:43], v[106:107], v[74:75]
	v_pk_fma_f32 v[76:77], v[44:45], v[108:109], v[76:77]
	v_pk_mul_f32 v[38:39], v[70:71], v[70:71]
	v_pk_mul_f32 v[40:41], v[72:73], v[72:73]
	v_pk_mul_f32 v[48:49], v[74:75], v[74:75]
	v_pk_mul_f32 v[80:81], v[76:77], v[76:77]
	v_add_f32_e32 v38, v38, v39
	v_add_f32_e32 v39, v40, v41
	v_add_f32_e32 v0, v0, v1
	v_add_f32_e32 v1, v46, v47
	v_pk_fma_f32 v[66:67], v[34:35], v[118:119], v[66:67]
	v_pk_fma_f32 v[68:69], v[36:37], v[120:121], v[68:69]
	v_add_f32_e32 v38, v38, v39
	v_add_f32_e32 v0, v0, v1
	v_add_f32_e32 v1, v80, v81
	v_add_f32_e32 v39, v48, v49
	v_pk_mul_f32 v[34:35], v[66:67], v[66:67]
	v_pk_mul_f32 v[36:37], v[68:69], v[68:69]
	v_add_f32_e32 v1, v39, v1
	v_add_f32_e32 v0, v0, v1
	v_add_f32_e32 v1, v36, v37
	v_add_f32_e32 v34, v34, v35
	v_lshl_add_u64 v[192:193], s[8:9], 0, v[192:193]
	v_add_f32_e32 v0, v0, v38
	v_add_f32_e32 v1, v34, v1
	v_add_f32_e32 v38, v0, v1
	v_cvt_pk_bf16_f32 v34, v70, v71
	v_cvt_pk_bf16_f32 v35, v72, v73
	v_cvt_pk_bf16_f32 v36, v66, v67
	v_cvt_pk_bf16_f32 v37, v68, v69
	v_lshl_add_u64 v[0:1], v[192:193], 0, v[190:191]
	global_store_dwordx4 v[0:1], v[34:37], off
	s_nop 0
	v_cvt_pk_bf16_f32 v42, v60, v61
	v_cvt_pk_bf16_f32 v43, v78, v79
	v_cvt_pk_bf16_f32 v44, v74, v75
	v_cvt_pk_bf16_f32 v45, v76, v77
	s_waitcnt lgkmcnt(0)
	v_mov_b32_e32 v0, v38
	v_mov_b32_e32 v34, v38
	s_nop 1
	v_permlane16_swap_b32_e32 v0, v34
	v_add_f32_e32 v34, v34, v0
	v_mov_b32_e32 v35, v34
	s_nop 1
	v_permlane32_swap_b32_e32 v35, v34
	v_lshl_add_u64 v[194:195], v[192:193], 0, v[170:171]
	global_store_dwordx4 v[194:195], v[42:45], off
	s_and_saveexec_b64 s[0:1], vcc
	s_cbranch_execz .LBB0_874
	s_waitcnt lgkmcnt(0)
	v_add_f32_e32 v0, v34, v35
	ds_write_b32 v221, v0 offset:320
.LBB0_874:
	s_or_b64 exec, exec, s[0:1]
	v_add_u32_e32 v80, 0xa0, v172
	v_ashrrev_i32_e32 v81, 31, v80
	v_lshlrev_b64 v[0:1], 12, v[80:81]
	s_waitcnt lgkmcnt(0)
	v_lshl_add_u64 v[34:35], v[188:189], 0, v[0:1]
	global_load_dwordx4 v[194:197], v[34:35], off
	global_load_dwordx4 v[198:201], v[34:35], off offset:16
	global_load_dwordx4 v[224:227], v[34:35], off offset:512
	global_load_dwordx4 v[228:231], v[34:35], off offset:528
	v_add_u32_e32 v192, 0xb0, v172
	v_ashrrev_i32_e32 v193, 31, v192
	v_lshlrev_b64 v[208:209], 12, v[192:193]
	v_lshl_add_u64 v[38:39], v[188:189], 0, v[208:209]
	global_load_dwordx4 v[42:45], v[38:39], off offset:16
	global_load_dwordx4 v[46:49], v[38:39], off
	global_load_dwordx4 v[34:37], v[38:39], off offset:528
	s_nop 0
	global_load_dwordx4 v[38:41], v[38:39], off offset:512
	v_lshl_add_u64 v[0:1], s[8:9], 0, v[0:1]
	s_waitcnt vmcnt(7)
	v_pk_fma_f32 v[206:207], v[30:31], v[110:111], v[194:195]
	v_pk_fma_f32 v[204:205], v[32:33], v[112:113], v[196:197]
	s_waitcnt vmcnt(6)
	v_pk_fma_f32 v[202:203], v[26:27], v[106:107], v[198:199]
	v_pk_fma_f32 v[200:201], v[28:29], v[108:109], v[200:201]
	s_waitcnt vmcnt(5)
	v_pk_fma_f32 v[188:189], v[22:23], v[126:127], v[224:225]
	v_pk_fma_f32 v[194:195], v[24:25], v[128:129], v[226:227]
	v_pk_mul_f32 v[22:23], v[206:207], v[206:207]
	v_pk_mul_f32 v[24:25], v[204:205], v[204:205]
	v_pk_mul_f32 v[26:27], v[202:203], v[202:203]
	v_pk_mul_f32 v[28:29], v[200:201], v[200:201]
	s_waitcnt vmcnt(4)
	v_pk_fma_f32 v[196:197], v[18:19], v[118:119], v[228:229]
	v_pk_fma_f32 v[198:199], v[20:21], v[120:121], v[230:231]
	v_pk_mul_f32 v[30:31], v[188:189], v[188:189]
	v_pk_mul_f32 v[32:33], v[194:195], v[194:195]
	v_add_f32_e32 v28, v28, v29
	v_add_f32_e32 v26, v26, v27
	v_add_f32_e32 v24, v24, v25
	v_add_f32_e32 v22, v22, v23
	v_pk_mul_f32 v[224:225], v[196:197], v[196:197]
	v_pk_mul_f32 v[226:227], v[198:199], v[198:199]
	v_add_f32_e32 v23, v32, v33
	v_add_f32_e32 v25, v30, v31
	v_add_f32_e32 v26, v26, v28
	v_add_f32_e32 v22, v22, v24
	v_add_f32_e32 v27, v226, v227
	v_add_f32_e32 v29, v224, v225
	v_add_f32_e32 v23, v25, v23
	v_add_f32_e32 v22, v22, v26
	v_add_f32_e32 v22, v22, v23
	v_add_f32_e32 v23, v29, v27
	v_add_f32_e32 v24, v22, v23
	s_nop 0
	v_cvt_pk_bf16_f32 v18, v206, v207
	v_cvt_pk_bf16_f32 v19, v204, v205
	v_cvt_pk_bf16_f32 v20, v202, v203
	v_cvt_pk_bf16_f32 v21, v200, v201
	v_lshl_add_u64 v[22:23], v[0:1], 0, v[170:171]
	global_store_dwordx4 v[22:23], v[18:21], off
	v_cvt_pk_bf16_f32 v22, v196, v197
	v_cvt_pk_bf16_f32 v23, v198, v199
	s_waitcnt lgkmcnt(0)
	v_mov_b32_e32 v25, v24
	v_mov_b32_e32 v18, v24
	s_nop 1
	v_permlane16_swap_b32_e32 v25, v18
	v_add_f32_e32 v18, v18, v25
	v_mov_b32_e32 v19, v18
	s_nop 1
	v_permlane32_swap_b32_e32 v19, v18
	v_cvt_pk_bf16_f32 v20, v188, v189
	v_cvt_pk_bf16_f32 v21, v194, v195
	v_lshl_add_u64 v[0:1], v[0:1], 0, v[190:191]
	global_store_dwordx4 v[0:1], v[20:23], off
	s_and_saveexec_b64 s[0:1], vcc
	s_cbranch_execz .LBB0_876
	s_waitcnt lgkmcnt(0)
	v_add_f32_e32 v0, v18, v19
	ds_write_b32 v221, v0 offset:384
.LBB0_876:
	s_or_b64 exec, exec, s[0:1]
	s_waitcnt vmcnt(4)
	v_pk_fma_f32 v[110:111], v[14:15], v[110:111], v[46:47]
	v_pk_fma_f32 v[112:113], v[16:17], v[112:113], v[48:49]
	s_waitcnt vmcnt(2)
	v_pk_fma_f32 v[126:127], v[6:7], v[126:127], v[38:39]
	v_pk_fma_f32 v[128:129], v[8:9], v[128:129], v[40:41]
	v_pk_mul_f32 v[0:1], v[110:111], v[110:111]
	v_pk_mul_f32 v[14:15], v[112:113], v[112:113]
	v_pk_fma_f32 v[106:107], v[10:11], v[106:107], v[42:43]
	v_pk_fma_f32 v[108:109], v[12:13], v[108:109], v[44:45]
	v_pk_mul_f32 v[6:7], v[126:127], v[126:127]
	v_pk_mul_f32 v[8:9], v[128:129], v[128:129]
	v_pk_mul_f32 v[16:17], v[106:107], v[106:107]
	s_waitcnt lgkmcnt(0)
	v_pk_mul_f32 v[18:19], v[108:109], v[108:109]
	v_add_f32_e32 v6, v6, v7
	v_add_f32_e32 v7, v8, v9
	v_add_f32_e32 v0, v0, v1
	v_add_f32_e32 v1, v14, v15
	v_pk_fma_f32 v[118:119], v[2:3], v[118:119], v[34:35]
	v_pk_fma_f32 v[120:121], v[4:5], v[120:121], v[36:37]
	v_add_f32_e32 v6, v6, v7
	v_add_f32_e32 v0, v0, v1
	v_add_f32_e32 v1, v18, v19
	v_add_f32_e32 v7, v16, v17
	v_pk_mul_f32 v[2:3], v[118:119], v[118:119]
	v_pk_mul_f32 v[4:5], v[120:121], v[120:121]
	v_add_f32_e32 v1, v7, v1
	v_add_f32_e32 v0, v0, v1
	v_add_f32_e32 v1, v4, v5
	v_add_f32_e32 v2, v2, v3
	v_add_f32_e32 v0, v0, v6
	v_add_f32_e32 v1, v2, v1
	v_add_f32_e32 v2, v0, v1
	s_nop 0
	v_lshl_add_u64 v[20:21], s[8:9], 0, v[208:209]
	v_cvt_pk_bf16_f32 v10, v110, v111
	v_cvt_pk_bf16_f32 v11, v112, v113
	v_cvt_pk_bf16_f32 v12, v106, v107
	s_waitcnt lgkmcnt(0)
	v_mov_b32_e32 v3, v2
	s_nop 1
	v_permlane16_swap_b32_e32 v3, v2
	v_add_f32_e32 v2, v2, v3
	v_mov_b32_e32 v3, v2
	s_nop 1
	v_permlane32_swap_b32_e32 v3, v2
	v_cvt_pk_bf16_f32 v13, v108, v109
	v_lshl_add_u64 v[0:1], v[20:21], 0, v[170:171]
	global_store_dwordx4 v[0:1], v[10:13], off
	v_cvt_pk_bf16_f32 v4, v126, v127
	v_cvt_pk_bf16_f32 v5, v128, v129
	v_cvt_pk_bf16_f32 v6, v118, v119
	v_cvt_pk_bf16_f32 v7, v120, v121
	v_lshl_add_u64 v[0:1], v[20:21], 0, v[190:191]
	global_store_dwordx4 v[0:1], v[4:7], off
	s_and_saveexec_b64 s[0:1], vcc
	s_cbranch_execz .LBB0_878
	s_waitcnt lgkmcnt(0)
	v_add_f32_e32 v0, v2, v3
	ds_write_b32 v221, v0 offset:448

.LBB0_1319:
	s_lshl_b32 s0, s30, 8
	v_mov_b32_e32 v252, v241
	v_mov_b32_e32 v253, v242
	s_or_b32 s0, s0, s67
	s_lshl_b32 s23, s73, 8
	v_lshl_add_u32 v224, v253, 3, s0
	v_ashrrev_i32_e32 v225, 31, v224
	v_lshl_add_u64 v[0:1], v[224:225], 2, s[16:17]
	global_load_dwordx4 v[70:73], v[0:1], off offset:16
	global_load_dwordx4 v[82:85], v[0:1], off
	global_load_dwordx4 v[58:61], v[0:1], off offset:528
	global_load_dwordx4 v[62:65], v[0:1], off offset:512
	s_add_i32 s0, s23, s66
	v_add_u32_e32 v0, s0, v252
	v_lshlrev_b32_e32 v1, 4, v253
	v_and_b32_e32 v218, 16, v1
	v_ashrrev_i32_e32 v80, 4, v224
	v_ashrrev_i32_e32 v1, 31, v0
	v_lshl_add_u64 v[78:79], s[12:13], 0, v[218:219]
	v_ashrrev_i32_e32 v81, 31, v80
	v_lshlrev_b64 v[90:91], 5, v[0:1]
	v_lshlrev_b64 v[80:81], 19, v[80:81]
	v_lshl_add_u64 v[90:91], v[78:79], 0, v[90:91]
	v_lshl_add_u64 v[92:93], v[90:91], 0, v[80:81]
	global_load_dwordx4 v[206:209], v[92:93], off
	v_add_u32_e32 v92, 0x80, v224
	v_ashrrev_i32_e32 v92, 4, v92
	v_ashrrev_i32_e32 v93, 31, v92
	v_lshlrev_b64 v[250:251], 19, v[92:93]
	v_lshl_add_u64 v[90:91], v[90:91], 0, v[250:251]
	global_load_dwordx4 v[202:205], v[90:91], off
	v_add_u32_e32 v238, 16, v0
	v_ashrrev_i32_e32 v239, 31, v238
	v_lshlrev_b64 v[90:91], 5, v[238:239]
	v_lshl_add_u64 v[90:91], v[78:79], 0, v[90:91]
	v_add_u32_e32 v236, 32, v0
	v_lshl_add_u64 v[92:93], v[90:91], 0, v[80:81]
	v_lshl_add_u64 v[90:91], v[90:91], 0, v[250:251]
	v_ashrrev_i32_e32 v237, 31, v236
	global_load_dwordx4 v[198:201], v[92:93], off
	global_load_dwordx4 v[194:197], v[90:91], off
	v_lshlrev_b64 v[90:91], 5, v[236:237]
	v_lshl_add_u64 v[90:91], v[78:79], 0, v[90:91]
	v_add_u32_e32 v234, 48, v0
	v_lshl_add_u64 v[92:93], v[90:91], 0, v[80:81]
	v_lshl_add_u64 v[90:91], v[90:91], 0, v[250:251]
	v_ashrrev_i32_e32 v235, 31, v234
	global_load_dwordx4 v[190:193], v[92:93], off
	global_load_dwordx4 v[182:185], v[90:91], off
	v_lshlrev_b64 v[90:91], 5, v[234:235]
	v_lshl_add_u64 v[90:91], v[78:79], 0, v[90:91]
	v_add_u32_e32 v232, 0x80, v0
	v_lshl_add_u64 v[92:93], v[90:91], 0, v[80:81]
	v_lshl_add_u64 v[90:91], v[90:91], 0, v[250:251]
	v_ashrrev_i32_e32 v233, 31, v232
	global_load_dwordx4 v[174:177], v[92:93], off
	global_load_dwordx4 v[166:169], v[90:91], off
	v_lshlrev_b64 v[90:91], 5, v[232:233]
	v_lshl_add_u64 v[90:91], v[78:79], 0, v[90:91]
	v_add_u32_e32 v230, 0x90, v0
	v_lshl_add_u64 v[92:93], v[90:91], 0, v[80:81]
	v_lshl_add_u64 v[90:91], v[90:91], 0, v[250:251]
	v_ashrrev_i32_e32 v231, 31, v230
	global_load_dwordx4 v[158:161], v[92:93], off
	global_load_dwordx4 v[146:149], v[90:91], off
	v_lshlrev_b64 v[90:91], 5, v[230:231]
	v_lshl_add_u64 v[90:91], v[78:79], 0, v[90:91]
	v_add_u32_e32 v228, 0xa0, v0
	v_lshl_add_u64 v[92:93], v[90:91], 0, v[80:81]
	v_lshl_add_u64 v[90:91], v[90:91], 0, v[250:251]
	v_ashrrev_i32_e32 v229, 31, v228
	global_load_dwordx4 v[134:137], v[92:93], off
	global_load_dwordx4 v[122:125], v[90:91], off
	v_lshlrev_b64 v[90:91], 5, v[228:229]
	v_lshl_add_u64 v[90:91], v[78:79], 0, v[90:91]
	v_add_u32_e32 v226, 0xb0, v0
	v_lshl_add_u64 v[92:93], v[90:91], 0, v[80:81]
	v_lshl_add_u64 v[90:91], v[90:91], 0, v[250:251]
	v_ashrrev_i32_e32 v227, 31, v226
	global_load_dwordx4 v[110:113], v[92:93], off
	global_load_dwordx4 v[98:101], v[90:91], off
	v_lshlrev_b64 v[90:91], 5, v[226:227]
	v_lshl_add_u64 v[78:79], v[78:79], 0, v[90:91]
	v_lshl_add_u64 v[80:81], v[78:79], 0, v[80:81]
	v_lshl_add_u64 v[78:79], v[78:79], 0, v[250:251]
	global_load_dwordx4 v[90:93], v[80:81], off
	v_and_b32_e32 v250, 64, v249
	global_load_dwordx4 v[78:81], v[78:79], off
	s_waitcnt vmcnt(0)
	v_add_f32_e32 v178, v178, v70
	v_add_f32_e32 v188, v188, v84
	v_add_f32_e32 v189, v189, v85
	v_mul_f32_e32 v188, 0xbfb8aa3b, v188
	v_mul_f32_e32 v189, 0xbfb8aa3b, v189
	v_add_f32_e32 v179, v179, v71
	v_exp_f32_e32 v188, v188
	v_exp_f32_e32 v189, v189
	v_mul_f32_e32 v178, 0xbfb8aa3b, v178
	v_mul_f32_e32 v179, 0xbfb8aa3b, v179
	v_exp_f32_e32 v178, v178
	v_exp_f32_e32 v179, v179
	v_xor_b32_e32 v218, 16, v249
	v_add_u32_e32 v251, 64, v250
	v_cmp_lt_i32_e32 vcc, v218, v251
	v_add_f32_e32 v188, 1.0, v188
	v_add_f32_e32 v189, 1.0, v189
	v_cndmask_b32_e32 v218, v249, v218, vcc
	v_lshlrev_b32_e32 v250, 2, v218
	v_xor_b32_e32 v218, 32, v249
	v_rcp_f32_e32 v188, v188
	v_rcp_f32_e32 v189, v189
	v_add_f32_e32 v178, 1.0, v178
	v_add_f32_e32 v179, 1.0, v179
	v_cmp_lt_i32_e32 vcc, v218, v251
	v_rcp_f32_e32 v178, v178
	v_rcp_f32_e32 v179, v179
	v_cndmask_b32_e32 v218, v249, v218, vcc
	v_lshlrev_b32_e32 v251, 2, v218
	v_cmp_eq_u32_e32 vcc, 0, v253
	v_lshl_add_u32 v218, v252, 2, s71
	v_lshlrev_b32_e32 v252, 16, v206
	v_and_b32_e32 v253, 0xffff0000, v206
	v_lshlrev_b32_e32 v206, 16, v207
	v_and_b32_e32 v207, 0xffff0000, v207
	v_pk_mul_f32 v[188:189], v[188:189], v[206:207]
	v_lshlrev_b32_e32 v206, 16, v208
	v_and_b32_e32 v207, 0xffff0000, v208
	v_add_f32_e32 v186, v186, v82
	v_add_f32_e32 v187, v187, v83
	v_pk_mul_f32 v[206:207], v[178:179], v[206:207]
	v_add_f32_e32 v178, v180, v72
	v_add_f32_e32 v179, v181, v73
	v_mul_f32_e32 v186, 0xbfb8aa3b, v186
	v_mul_f32_e32 v187, 0xbfb8aa3b, v187
	v_mul_f32_e32 v178, 0xbfb8aa3b, v178
	v_mul_f32_e32 v179, 0xbfb8aa3b, v179
	v_exp_f32_e32 v186, v186
	v_exp_f32_e32 v187, v187
	v_exp_f32_e32 v178, v178
	v_exp_f32_e32 v179, v179
	v_add_f32_e32 v186, 1.0, v186
	v_add_f32_e32 v187, 1.0, v187
	v_add_f32_e32 v178, 1.0, v178
	v_add_f32_e32 v179, 1.0, v179
	v_rcp_f32_e32 v186, v186
	v_rcp_f32_e32 v187, v187
	v_rcp_f32_e32 v178, v178
	v_rcp_f32_e32 v179, v179
	v_add_f32_e32 v170, v170, v62
	v_add_f32_e32 v171, v171, v63
	v_mul_f32_e32 v170, 0xbfb8aa3b, v170
	v_mul_f32_e32 v171, 0xbfb8aa3b, v171
	v_add_f32_e32 v172, v172, v64
	v_add_f32_e32 v173, v173, v65
	v_exp_f32_e32 v170, v170
	v_exp_f32_e32 v171, v171
	v_mul_f32_e32 v172, 0xbfb8aa3b, v172
	v_mul_f32_e32 v173, 0xbfb8aa3b, v173
	v_add_f32_e32 v162, v162, v58
	v_add_f32_e32 v163, v163, v59
	v_lshlrev_b64 v[0:1], 11, v[0:1]
	v_lshlrev_b32_e32 v180, 16, v209
	v_and_b32_e32 v181, 0xffff0000, v209
	v_exp_f32_e32 v172, v172
	v_exp_f32_e32 v173, v173
	v_mul_f32_e32 v162, 0xbfb8aa3b, v162
	v_mul_f32_e32 v163, 0xbfb8aa3b, v163
	v_pk_mul_f32 v[186:187], v[186:187], v[252:253]
	v_pk_mul_f32 v[208:209], v[178:179], v[180:181]
	v_lshl_add_u64 v[0:1], s[14:15], 0, v[0:1]
	v_exp_f32_e32 v162, v162
	v_exp_f32_e32 v163, v163
	v_cvt_pk_bf16_f32 v178, v186, v187
	v_cvt_pk_bf16_f32 v179, v188, v189
	v_cvt_pk_bf16_f32 v180, v206, v207
	v_cvt_pk_bf16_f32 v181, v208, v209
	v_lshl_add_u64 v[0:1], v[224:225], 1, v[0:1]
	global_store_dwordx4 v[0:1], v[178:181], off
	v_lshlrev_b32_e32 v186, 16, v178
	v_add_f32_e32 v170, 1.0, v170
	v_and_b32_e32 v178, 0xffff0000, v178
	v_add_f32_e32 v171, 1.0, v171
	v_mul_f32_e32 v206, v178, v178
	v_rcp_f32_e32 v170, v170
	v_rcp_f32_e32 v171, v171
	v_add_f32_e32 v172, 1.0, v172
	v_add_f32_e32 v173, 1.0, v173
	v_lshlrev_b32_e32 v187, 16, v179
	v_fmac_f32_e32 v206, v186, v186
	v_rcp_f32_e32 v172, v172
	v_rcp_f32_e32 v173, v173
	v_add_f32_e32 v162, 1.0, v162
	v_add_f32_e32 v163, 1.0, v163
	v_and_b32_e32 v179, 0xffff0000, v179
	v_fmac_f32_e32 v206, v187, v187
	v_rcp_f32_e32 v162, v162
	v_rcp_f32_e32 v163, v163
	v_fmac_f32_e32 v206, v179, v179
	v_lshlrev_b32_e32 v178, 16, v202
	v_and_b32_e32 v179, 0xffff0000, v202
	v_pk_mul_f32 v[170:171], v[170:171], v[178:179]
	v_lshlrev_b32_e32 v178, 16, v203
	v_and_b32_e32 v179, 0xffff0000, v203
	v_pk_mul_f32 v[172:173], v[172:173], v[178:179]
	v_lshlrev_b32_e32 v178, 16, v204
	v_and_b32_e32 v179, 0xffff0000, v204
	v_pk_mul_f32 v[178:179], v[162:163], v[178:179]
	v_add_f32_e32 v162, v164, v60
	v_add_f32_e32 v163, v165, v61
	v_mul_f32_e32 v162, 0xbfb8aa3b, v162
	v_mul_f32_e32 v163, 0xbfb8aa3b, v163
	v_exp_f32_e32 v162, v162
	v_exp_f32_e32 v163, v163
	v_lshlrev_b32_e32 v188, 16, v180
	v_and_b32_e32 v180, 0xffff0000, v180
	v_add_f32_e32 v162, 1.0, v162
	v_add_f32_e32 v163, 1.0, v163
	v_rcp_f32_e32 v162, v162
	v_rcp_f32_e32 v163, v163
	v_fmac_f32_e32 v206, v188, v188
	v_lshlrev_b32_e32 v189, 16, v181
	v_fmac_f32_e32 v206, v180, v180
	v_and_b32_e32 v181, 0xffff0000, v181
	v_fmac_f32_e32 v206, v189, v189
	v_lshlrev_b32_e32 v164, 16, v205
	v_and_b32_e32 v165, 0xffff0000, v205
	v_fmac_f32_e32 v206, v181, v181
	v_pk_mul_f32 v[180:181], v[162:163], v[164:165]
	v_cvt_pk_bf16_f32 v162, v170, v171
	v_cvt_pk_bf16_f32 v163, v172, v173
	v_cvt_pk_bf16_f32 v164, v178, v179
	v_cvt_pk_bf16_f32 v165, v180, v181
	global_store_dwordx4 v[0:1], v[162:165], off offset:256
	v_lshlrev_b32_e32 v0, 16, v162
	v_and_b32_e32 v1, 0xffff0000, v162
	v_fmac_f32_e32 v206, v0, v0
	v_lshlrev_b32_e32 v162, 16, v163
	v_fmac_f32_e32 v206, v1, v1
	v_and_b32_e32 v163, 0xffff0000, v163
	v_fmac_f32_e32 v206, v162, v162
	v_lshlrev_b32_e32 v170, 16, v164
	v_fmac_f32_e32 v206, v163, v163
	v_and_b32_e32 v164, 0xffff0000, v164
	v_fmac_f32_e32 v206, v170, v170
	v_lshlrev_b32_e32 v171, 16, v165
	v_fmac_f32_e32 v206, v164, v164
	v_and_b32_e32 v165, 0xffff0000, v165
	v_fmac_f32_e32 v206, v171, v171
	v_fmac_f32_e32 v206, v165, v165
	s_nop 0
	s_waitcnt lgkmcnt(0)
	v_mov_b32_e32 v0, v206
	v_mov_b32_e32 v162, v206
	s_nop 1
	v_permlane16_swap_b32_e32 v0, v162
	v_add_f32_e32 v162, v162, v0
	v_mov_b32_e32 v163, v162
	s_nop 1
	v_permlane32_swap_b32_e32 v163, v162
	s_and_saveexec_b64 s[0:1], vcc
	s_cbranch_execz .LBB0_1321
	s_waitcnt lgkmcnt(0)
	v_add_f32_e32 v0, v162, v163
	ds_write_b32 v218, v0
.LBB0_1321:
	s_or_b64 exec, exec, s[0:1]
	v_add_f32_e32 v0, v154, v82
	v_add_f32_e32 v1, v155, v83
	v_mul_f32_e32 v0, 0xbfb8aa3b, v0
	v_mul_f32_e32 v1, 0xbfb8aa3b, v1
	v_exp_f32_e32 v0, v0
	v_exp_f32_e32 v1, v1
	v_add_f32_e32 v156, v156, v84
	v_add_f32_e32 v157, v157, v85
	v_add_f32_e32 v0, 1.0, v0
	v_add_f32_e32 v1, 1.0, v1
	v_mul_f32_e32 v156, 0xbfb8aa3b, v156
	v_mul_f32_e32 v157, 0xbfb8aa3b, v157
	v_add_f32_e32 v150, v150, v70
	v_add_f32_e32 v151, v151, v71
	v_rcp_f32_e32 v0, v0
	v_rcp_f32_e32 v1, v1
	v_exp_f32_e32 v156, v156
	v_exp_f32_e32 v157, v157
	v_mul_f32_e32 v150, 0xbfb8aa3b, v150
	v_mul_f32_e32 v151, 0xbfb8aa3b, v151
	v_add_f32_e32 v152, v152, v72
	v_add_f32_e32 v153, v153, v73
	v_exp_f32_e32 v150, v150
	v_exp_f32_e32 v151, v151
	v_mul_f32_e32 v152, 0xbfb8aa3b, v152
	v_mul_f32_e32 v153, 0xbfb8aa3b, v153
	v_exp_f32_e32 v152, v152
	v_exp_f32_e32 v153, v153
	v_lshlrev_b32_e32 v154, 16, v198
	v_and_b32_e32 v155, 0xffff0000, v198
	v_pk_mul_f32 v[0:1], v[0:1], v[154:155]
	v_add_f32_e32 v154, 1.0, v156
	v_add_f32_e32 v155, 1.0, v157
	v_rcp_f32_e32 v154, v154
	v_rcp_f32_e32 v155, v155
	v_add_f32_e32 v150, 1.0, v150
	v_add_f32_e32 v151, 1.0, v151
	v_rcp_f32_e32 v150, v150
	v_rcp_f32_e32 v151, v151
	v_add_f32_e32 v152, 1.0, v152
	v_add_f32_e32 v153, 1.0, v153
	v_rcp_f32_e32 v152, v152
	v_rcp_f32_e32 v153, v153
	v_lshlrev_b32_e32 v156, 16, v199
	v_and_b32_e32 v157, 0xffff0000, v199
	v_pk_mul_f32 v[154:155], v[154:155], v[156:157]
	v_lshlrev_b32_e32 v156, 16, v200
	v_and_b32_e32 v157, 0xffff0000, v200
	v_pk_mul_f32 v[156:157], v[150:151], v[156:157]
	v_lshlrev_b32_e32 v150, 16, v201
	v_and_b32_e32 v151, 0xffff0000, v201
	s_waitcnt lgkmcnt(0)
	v_pk_mul_f32 v[162:163], v[152:153], v[150:151]
	v_cvt_pk_bf16_f32 v150, v0, v1
	v_and_b32_e32 v1, 0xffff0000, v150
	v_lshlrev_b32_e32 v0, 16, v150
	v_mul_f32_e32 v164, v1, v1
	v_fmac_f32_e32 v164, v0, v0
	v_add_f32_e32 v0, v142, v62
	v_add_f32_e32 v1, v143, v63
	v_mul_f32_e32 v0, 0xbfb8aa3b, v0
	v_mul_f32_e32 v1, 0xbfb8aa3b, v1
	v_exp_f32_e32 v0, v0
	v_exp_f32_e32 v1, v1
	v_add_f32_e32 v144, v144, v64
	v_add_f32_e32 v145, v145, v65
	v_add_f32_e32 v0, 1.0, v0
	v_add_f32_e32 v1, 1.0, v1
	v_mul_f32_e32 v144, 0xbfb8aa3b, v144
	v_mul_f32_e32 v145, 0xbfb8aa3b, v145
	v_rcp_f32_e32 v0, v0
	v_rcp_f32_e32 v1, v1
	v_exp_f32_e32 v144, v144
	v_exp_f32_e32 v145, v145
	v_cvt_pk_bf16_f32 v151, v154, v155
	v_add_f32_e32 v138, v138, v58
	v_lshlrev_b32_e32 v154, 16, v151
	v_mul_f32_e32 v138, 0xbfb8aa3b, v138
	v_fmac_f32_e32 v164, v154, v154
	v_lshlrev_b32_e32 v142, 16, v194
	v_and_b32_e32 v143, 0xffff0000, v194
	v_exp_f32_e32 v154, v138
	v_add_f32_e32 v138, v139, v59
	v_and_b32_e32 v155, 0xffff0000, v151
	v_pk_mul_f32 v[0:1], v[0:1], v[142:143]
	v_add_f32_e32 v142, 1.0, v144
	v_add_f32_e32 v143, 1.0, v145
	v_mul_f32_e32 v138, 0xbfb8aa3b, v138
	v_add_f32_e32 v140, v140, v60
	v_add_f32_e32 v141, v141, v61
	v_fmac_f32_e32 v164, v155, v155
	v_rcp_f32_e32 v142, v142
	v_rcp_f32_e32 v143, v143
	v_exp_f32_e32 v155, v138
	v_mul_f32_e32 v140, 0xbfb8aa3b, v140
	v_mul_f32_e32 v141, 0xbfb8aa3b, v141
	v_exp_f32_e32 v140, v140
	v_exp_f32_e32 v141, v141
	v_lshlrev_b32_e32 v144, 16, v195
	v_and_b32_e32 v145, 0xffff0000, v195
	v_pk_mul_f32 v[138:139], v[142:143], v[144:145]
	v_add_f32_e32 v142, 1.0, v154
	v_add_f32_e32 v143, 1.0, v155
	v_rcp_f32_e32 v142, v142
	v_rcp_f32_e32 v143, v143
	v_add_f32_e32 v140, 1.0, v140
	v_add_f32_e32 v141, 1.0, v141
	v_cvt_pk_bf16_f32 v152, v156, v157
	v_rcp_f32_e32 v140, v140
	v_rcp_f32_e32 v141, v141
	v_lshlrev_b32_e32 v156, 16, v152
	v_cvt_pk_bf16_f32 v153, v162, v163
	v_and_b32_e32 v157, 0xffff0000, v152
	v_fmac_f32_e32 v164, v156, v156
	v_lshlrev_b32_e32 v144, 16, v196
	v_and_b32_e32 v145, 0xffff0000, v196
	v_lshlrev_b32_e32 v162, 16, v153
	v_fmac_f32_e32 v164, v157, v157
	v_pk_mul_f32 v[142:143], v[142:143], v[144:145]
	v_lshlrev_b32_e32 v144, 16, v197
	v_and_b32_e32 v145, 0xffff0000, v197
	v_and_b32_e32 v163, 0xffff0000, v153
	v_fmac_f32_e32 v164, v162, v162
	v_pk_mul_f32 v[144:145], v[140:141], v[144:145]
	v_cvt_pk_bf16_f32 v140, v0, v1
	v_fmac_f32_e32 v164, v163, v163
	v_lshlrev_b32_e32 v0, 16, v140
	v_cvt_pk_bf16_f32 v141, v138, v139
	v_and_b32_e32 v1, 0xffff0000, v140
	v_fmac_f32_e32 v164, v0, v0
	v_lshlrev_b32_e32 v138, 16, v141
	v_fmac_f32_e32 v164, v1, v1
	v_cvt_pk_bf16_f32 v142, v142, v143
	v_and_b32_e32 v139, 0xffff0000, v141
	v_fmac_f32_e32 v164, v138, v138
	v_cvt_pk_bf16_f32 v143, v144, v145
	v_lshlrev_b32_e32 v144, 16, v142
	v_fmac_f32_e32 v164, v139, v139
	v_and_b32_e32 v145, 0xffff0000, v142
	v_fmac_f32_e32 v164, v144, v144
	v_lshlrev_b32_e32 v154, 16, v143
	v_fmac_f32_e32 v164, v145, v145
	v_and_b32_e32 v155, 0xffff0000, v143
	v_fmac_f32_e32 v164, v154, v154
	v_fmac_f32_e32 v164, v155, v155
	s_nop 0
	v_lshlrev_b64 v[0:1], 11, v[238:239]
	v_lshl_add_u64 v[0:1], s[14:15], 0, v[0:1]
	v_lshl_add_u64 v[0:1], v[224:225], 1, v[0:1]
	global_store_dwordx4 v[0:1], v[150:153], off
	global_store_dwordx4 v[0:1], v[140:143], off offset:256
	s_waitcnt lgkmcnt(0)
	v_mov_b32_e32 v138, v164
	s_nop 1
	v_permlane16_swap_b32_e32 v138, v164
	v_add_f32_e32 v138, v164, v138
	v_mov_b32_e32 v139, v138
	s_nop 1
	v_permlane32_swap_b32_e32 v139, v138
	s_and_saveexec_b64 s[0:1], vcc
	s_cbranch_execz .LBB0_1323
	s_waitcnt lgkmcnt(0)
	v_add_f32_e32 v0, v138, v139
	ds_write_b32 v218, v0 offset:64
.LBB0_1323:
	s_or_b64 exec, exec, s[0:1]
	v_add_f32_e32 v0, v130, v82
	v_add_f32_e32 v1, v131, v83
	v_mul_f32_e32 v0, 0xbfb8aa3b, v0
	v_mul_f32_e32 v1, 0xbfb8aa3b, v1
	v_exp_f32_e32 v0, v0
	v_exp_f32_e32 v1, v1
	v_add_f32_e32 v132, v132, v84
	v_add_f32_e32 v133, v133, v85
	v_add_f32_e32 v0, 1.0, v0
	v_add_f32_e32 v1, 1.0, v1
	v_mul_f32_e32 v132, 0xbfb8aa3b, v132
	v_mul_f32_e32 v133, 0xbfb8aa3b, v133
	v_add_f32_e32 v126, v126, v70
	v_add_f32_e32 v127, v127, v71
	v_rcp_f32_e32 v0, v0
	v_rcp_f32_e32 v1, v1
	v_exp_f32_e32 v132, v132
	v_exp_f32_e32 v133, v133
	v_mul_f32_e32 v126, 0xbfb8aa3b, v126
	v_mul_f32_e32 v127, 0xbfb8aa3b, v127
	v_add_f32_e32 v128, v128, v72
	v_add_f32_e32 v129, v129, v73
	v_exp_f32_e32 v126, v126
	v_exp_f32_e32 v127, v127
	v_mul_f32_e32 v128, 0xbfb8aa3b, v128
	v_mul_f32_e32 v129, 0xbfb8aa3b, v129
	v_exp_f32_e32 v128, v128
	v_exp_f32_e32 v129, v129
	v_lshlrev_b32_e32 v130, 16, v190
	v_and_b32_e32 v131, 0xffff0000, v190
	v_pk_mul_f32 v[0:1], v[0:1], v[130:131]
	v_add_f32_e32 v130, 1.0, v132
	v_add_f32_e32 v131, 1.0, v133
	v_rcp_f32_e32 v130, v130
	v_rcp_f32_e32 v131, v131
	v_add_f32_e32 v126, 1.0, v126
	v_add_f32_e32 v127, 1.0, v127
	v_rcp_f32_e32 v126, v126
	v_rcp_f32_e32 v127, v127
	v_add_f32_e32 v128, 1.0, v128
	v_add_f32_e32 v129, 1.0, v129
	v_rcp_f32_e32 v128, v128
	v_rcp_f32_e32 v129, v129
	v_lshlrev_b32_e32 v132, 16, v191
	v_and_b32_e32 v133, 0xffff0000, v191
	v_pk_mul_f32 v[130:131], v[130:131], v[132:133]
	v_lshlrev_b32_e32 v132, 16, v192
	v_and_b32_e32 v133, 0xffff0000, v192
	v_pk_mul_f32 v[132:133], v[126:127], v[132:133]
	v_lshlrev_b32_e32 v126, 16, v193
	v_and_b32_e32 v127, 0xffff0000, v193
	s_waitcnt lgkmcnt(0)
	v_pk_mul_f32 v[138:139], v[128:129], v[126:127]
	v_cvt_pk_bf16_f32 v126, v0, v1
	v_and_b32_e32 v1, 0xffff0000, v126
	v_lshlrev_b32_e32 v0, 16, v126
	v_mul_f32_e32 v140, v1, v1
	v_fmac_f32_e32 v140, v0, v0
	v_add_f32_e32 v0, v118, v62
	v_add_f32_e32 v1, v119, v63
	v_mul_f32_e32 v0, 0xbfb8aa3b, v0
	v_mul_f32_e32 v1, 0xbfb8aa3b, v1
	v_exp_f32_e32 v0, v0
	v_exp_f32_e32 v1, v1
	v_add_f32_e32 v120, v120, v64
	v_add_f32_e32 v121, v121, v65
	v_add_f32_e32 v0, 1.0, v0
	v_add_f32_e32 v1, 1.0, v1
	v_mul_f32_e32 v120, 0xbfb8aa3b, v120
	v_mul_f32_e32 v121, 0xbfb8aa3b, v121
	v_rcp_f32_e32 v0, v0
	v_rcp_f32_e32 v1, v1
	v_exp_f32_e32 v120, v120
	v_exp_f32_e32 v121, v121
	v_cvt_pk_bf16_f32 v127, v130, v131
	v_add_f32_e32 v114, v114, v58
	v_lshlrev_b32_e32 v130, 16, v127
	v_mul_f32_e32 v114, 0xbfb8aa3b, v114
	v_fmac_f32_e32 v140, v130, v130
	v_lshlrev_b32_e32 v118, 16, v182
	v_and_b32_e32 v119, 0xffff0000, v182
	v_exp_f32_e32 v130, v114
	v_add_f32_e32 v114, v115, v59
	v_and_b32_e32 v131, 0xffff0000, v127
	v_pk_mul_f32 v[0:1], v[0:1], v[118:119]
	v_add_f32_e32 v118, 1.0, v120
	v_add_f32_e32 v119, 1.0, v121
	v_mul_f32_e32 v114, 0xbfb8aa3b, v114
	v_add_f32_e32 v116, v116, v60
	v_add_f32_e32 v117, v117, v61
	v_fmac_f32_e32 v140, v131, v131
	v_rcp_f32_e32 v118, v118
	v_rcp_f32_e32 v119, v119
	v_exp_f32_e32 v131, v114
	v_mul_f32_e32 v116, 0xbfb8aa3b, v116
	v_mul_f32_e32 v117, 0xbfb8aa3b, v117
	v_exp_f32_e32 v116, v116
	v_exp_f32_e32 v117, v117
	v_lshlrev_b32_e32 v120, 16, v183
	v_and_b32_e32 v121, 0xffff0000, v183
	v_pk_mul_f32 v[114:115], v[118:119], v[120:121]
	v_add_f32_e32 v118, 1.0, v130
	v_add_f32_e32 v119, 1.0, v131
	v_rcp_f32_e32 v118, v118
	v_rcp_f32_e32 v119, v119
	v_add_f32_e32 v116, 1.0, v116
	v_add_f32_e32 v117, 1.0, v117
	v_cvt_pk_bf16_f32 v128, v132, v133
	v_rcp_f32_e32 v116, v116
	v_rcp_f32_e32 v117, v117
	v_lshlrev_b32_e32 v132, 16, v128
	v_cvt_pk_bf16_f32 v129, v138, v139
	v_and_b32_e32 v133, 0xffff0000, v128
	v_fmac_f32_e32 v140, v132, v132
	v_lshlrev_b32_e32 v120, 16, v184
	v_and_b32_e32 v121, 0xffff0000, v184
	v_lshlrev_b32_e32 v138, 16, v129
	v_fmac_f32_e32 v140, v133, v133
	v_pk_mul_f32 v[118:119], v[118:119], v[120:121]
	v_lshlrev_b32_e32 v120, 16, v185
	v_and_b32_e32 v121, 0xffff0000, v185
	v_and_b32_e32 v139, 0xffff0000, v129
	v_fmac_f32_e32 v140, v138, v138
	v_pk_mul_f32 v[120:121], v[116:117], v[120:121]
	v_cvt_pk_bf16_f32 v116, v0, v1
	v_fmac_f32_e32 v140, v139, v139
	v_lshlrev_b32_e32 v0, 16, v116
	v_cvt_pk_bf16_f32 v117, v114, v115
	v_and_b32_e32 v1, 0xffff0000, v116
	v_fmac_f32_e32 v140, v0, v0
	v_lshlrev_b32_e32 v114, 16, v117
	v_fmac_f32_e32 v140, v1, v1
	v_cvt_pk_bf16_f32 v118, v118, v119
	v_and_b32_e32 v115, 0xffff0000, v117
	v_fmac_f32_e32 v140, v114, v114
	v_cvt_pk_bf16_f32 v119, v120, v121
	v_lshlrev_b32_e32 v120, 16, v118
	v_fmac_f32_e32 v140, v115, v115
	v_and_b32_e32 v121, 0xffff0000, v118
	v_fmac_f32_e32 v140, v120, v120
	v_lshlrev_b32_e32 v130, 16, v119
	v_fmac_f32_e32 v140, v121, v121
	v_and_b32_e32 v131, 0xffff0000, v119
	v_fmac_f32_e32 v140, v130, v130
	v_fmac_f32_e32 v140, v131, v131
	s_nop 0
	v_lshlrev_b64 v[0:1], 11, v[236:237]
	v_lshl_add_u64 v[0:1], s[14:15], 0, v[0:1]
	v_lshl_add_u64 v[0:1], v[224:225], 1, v[0:1]
	global_store_dwordx4 v[0:1], v[126:129], off
	global_store_dwordx4 v[0:1], v[116:119], off offset:256
	s_waitcnt lgkmcnt(0)
	v_mov_b32_e32 v114, v140
	s_nop 1
	v_permlane16_swap_b32_e32 v114, v140
	v_add_f32_e32 v114, v140, v114
	v_mov_b32_e32 v115, v114
	s_nop 1
	v_permlane32_swap_b32_e32 v115, v114
	s_and_saveexec_b64 s[0:1], vcc
	s_cbranch_execz .LBB0_1325
	s_waitcnt lgkmcnt(0)
	v_add_f32_e32 v0, v114, v115
	ds_write_b32 v218, v0 offset:128
.LBB0_1325:
	s_or_b64 exec, exec, s[0:1]
	v_add_f32_e32 v0, v106, v82
	v_add_f32_e32 v1, v107, v83
	v_mul_f32_e32 v0, 0xbfb8aa3b, v0
	v_mul_f32_e32 v1, 0xbfb8aa3b, v1
	v_exp_f32_e32 v0, v0
	v_exp_f32_e32 v1, v1
	v_add_f32_e32 v108, v108, v84
	v_add_f32_e32 v109, v109, v85
	v_add_f32_e32 v0, 1.0, v0
	v_add_f32_e32 v1, 1.0, v1
	v_mul_f32_e32 v108, 0xbfb8aa3b, v108
	v_mul_f32_e32 v109, 0xbfb8aa3b, v109
	v_add_f32_e32 v102, v102, v70
	v_add_f32_e32 v103, v103, v71
	v_rcp_f32_e32 v0, v0
	v_rcp_f32_e32 v1, v1
	v_exp_f32_e32 v108, v108
	v_exp_f32_e32 v109, v109
	v_mul_f32_e32 v102, 0xbfb8aa3b, v102
	v_mul_f32_e32 v103, 0xbfb8aa3b, v103
	v_add_f32_e32 v104, v104, v72
	v_add_f32_e32 v105, v105, v73
	v_exp_f32_e32 v102, v102
	v_exp_f32_e32 v103, v103
	v_mul_f32_e32 v104, 0xbfb8aa3b, v104
	v_mul_f32_e32 v105, 0xbfb8aa3b, v105
	v_exp_f32_e32 v104, v104
	v_exp_f32_e32 v105, v105
	v_lshlrev_b32_e32 v106, 16, v174
	v_and_b32_e32 v107, 0xffff0000, v174
	v_pk_mul_f32 v[0:1], v[0:1], v[106:107]
	v_add_f32_e32 v106, 1.0, v108
	v_add_f32_e32 v107, 1.0, v109
	v_rcp_f32_e32 v106, v106
	v_rcp_f32_e32 v107, v107
	v_add_f32_e32 v102, 1.0, v102
	v_add_f32_e32 v103, 1.0, v103
	v_rcp_f32_e32 v102, v102
	v_rcp_f32_e32 v103, v103
	v_add_f32_e32 v104, 1.0, v104
	v_add_f32_e32 v105, 1.0, v105
	v_rcp_f32_e32 v104, v104
	v_rcp_f32_e32 v105, v105
	v_lshlrev_b32_e32 v108, 16, v175
	v_and_b32_e32 v109, 0xffff0000, v175
	v_pk_mul_f32 v[106:107], v[106:107], v[108:109]
	v_lshlrev_b32_e32 v108, 16, v176
	v_and_b32_e32 v109, 0xffff0000, v176
	v_pk_mul_f32 v[108:109], v[102:103], v[108:109]
	v_lshlrev_b32_e32 v102, 16, v177
	v_and_b32_e32 v103, 0xffff0000, v177
	s_waitcnt lgkmcnt(0)
	v_pk_mul_f32 v[114:115], v[104:105], v[102:103]
	v_cvt_pk_bf16_f32 v102, v0, v1
	v_and_b32_e32 v1, 0xffff0000, v102
	v_lshlrev_b32_e32 v0, 16, v102
	v_mul_f32_e32 v116, v1, v1
	v_fmac_f32_e32 v116, v0, v0
	v_add_f32_e32 v0, v94, v62
	v_add_f32_e32 v1, v95, v63
	v_mul_f32_e32 v0, 0xbfb8aa3b, v0
	v_mul_f32_e32 v1, 0xbfb8aa3b, v1
	v_exp_f32_e32 v0, v0
	v_exp_f32_e32 v1, v1
	v_add_f32_e32 v96, v96, v64
	v_add_f32_e32 v97, v97, v65
	v_add_f32_e32 v0, 1.0, v0
	v_add_f32_e32 v1, 1.0, v1
	v_mul_f32_e32 v96, 0xbfb8aa3b, v96
	v_mul_f32_e32 v97, 0xbfb8aa3b, v97
	v_rcp_f32_e32 v0, v0
	v_rcp_f32_e32 v1, v1
	v_exp_f32_e32 v96, v96
	v_exp_f32_e32 v97, v97
	v_cvt_pk_bf16_f32 v103, v106, v107
	v_add_f32_e32 v86, v86, v58
	v_lshlrev_b32_e32 v106, 16, v103
	v_mul_f32_e32 v86, 0xbfb8aa3b, v86
	v_fmac_f32_e32 v116, v106, v106
	v_lshlrev_b32_e32 v94, 16, v166
	v_and_b32_e32 v95, 0xffff0000, v166
	v_exp_f32_e32 v106, v86
	v_add_f32_e32 v86, v87, v59
	v_and_b32_e32 v107, 0xffff0000, v103
	v_pk_mul_f32 v[0:1], v[0:1], v[94:95]
	v_add_f32_e32 v94, 1.0, v96
	v_add_f32_e32 v95, 1.0, v97
	v_mul_f32_e32 v86, 0xbfb8aa3b, v86
	v_add_f32_e32 v88, v88, v60
	v_add_f32_e32 v89, v89, v61
	v_fmac_f32_e32 v116, v107, v107
	v_rcp_f32_e32 v94, v94
	v_rcp_f32_e32 v95, v95
	v_exp_f32_e32 v107, v86
	v_mul_f32_e32 v88, 0xbfb8aa3b, v88
	v_mul_f32_e32 v89, 0xbfb8aa3b, v89
	v_exp_f32_e32 v88, v88
	v_exp_f32_e32 v89, v89
	v_lshlrev_b32_e32 v96, 16, v167
	v_and_b32_e32 v97, 0xffff0000, v167
	v_pk_mul_f32 v[86:87], v[94:95], v[96:97]
	v_add_f32_e32 v94, 1.0, v106
	v_add_f32_e32 v95, 1.0, v107
	v_rcp_f32_e32 v94, v94
	v_rcp_f32_e32 v95, v95
	v_add_f32_e32 v88, 1.0, v88
	v_add_f32_e32 v89, 1.0, v89
	v_cvt_pk_bf16_f32 v104, v108, v109
	v_rcp_f32_e32 v88, v88
	v_rcp_f32_e32 v89, v89
	v_lshlrev_b32_e32 v108, 16, v104
	v_cvt_pk_bf16_f32 v105, v114, v115
	v_and_b32_e32 v109, 0xffff0000, v104
	v_fmac_f32_e32 v116, v108, v108
	v_lshlrev_b32_e32 v96, 16, v168
	v_and_b32_e32 v97, 0xffff0000, v168
	v_lshlrev_b32_e32 v114, 16, v105
	v_fmac_f32_e32 v116, v109, v109
	v_pk_mul_f32 v[96:97], v[94:95], v[96:97]
	v_lshlrev_b32_e32 v94, 16, v169
	v_and_b32_e32 v95, 0xffff0000, v169
	v_and_b32_e32 v115, 0xffff0000, v105
	v_fmac_f32_e32 v116, v114, v114
	v_pk_mul_f32 v[88:89], v[88:89], v[94:95]
	v_cvt_pk_bf16_f32 v94, v0, v1
	v_fmac_f32_e32 v116, v115, v115
	v_lshlrev_b32_e32 v0, 16, v94
	v_cvt_pk_bf16_f32 v95, v86, v87
	v_and_b32_e32 v1, 0xffff0000, v94
	v_fmac_f32_e32 v116, v0, v0
	v_lshlrev_b32_e32 v86, 16, v95
	v_fmac_f32_e32 v116, v1, v1
	v_cvt_pk_bf16_f32 v96, v96, v97
	v_and_b32_e32 v87, 0xffff0000, v95
	v_fmac_f32_e32 v116, v86, v86
	v_cvt_pk_bf16_f32 v97, v88, v89
	v_lshlrev_b32_e32 v88, 16, v96
	v_fmac_f32_e32 v116, v87, v87
	v_and_b32_e32 v89, 0xffff0000, v96
	v_fmac_f32_e32 v116, v88, v88
	v_lshlrev_b32_e32 v106, 16, v97
	v_fmac_f32_e32 v116, v89, v89
	v_and_b32_e32 v107, 0xffff0000, v97
	v_fmac_f32_e32 v116, v106, v106
	v_fmac_f32_e32 v116, v107, v107
	s_nop 0
	v_lshlrev_b64 v[0:1], 11, v[234:235]
	v_lshl_add_u64 v[0:1], s[14:15], 0, v[0:1]
	v_lshl_add_u64 v[0:1], v[224:225], 1, v[0:1]
	global_store_dwordx4 v[0:1], v[102:105], off
	global_store_dwordx4 v[0:1], v[94:97], off offset:256
	s_waitcnt lgkmcnt(0)
	v_mov_b32_e32 v86, v116
	s_nop 1
	v_permlane16_swap_b32_e32 v86, v116
	v_add_f32_e32 v86, v116, v86
	v_mov_b32_e32 v87, v86
	s_nop 1
	v_permlane32_swap_b32_e32 v87, v86
	s_and_saveexec_b64 s[0:1], vcc
	s_cbranch_execz .LBB0_1327
	s_waitcnt lgkmcnt(0)
	v_add_f32_e32 v0, v86, v87
	ds_write_b32 v218, v0 offset:192
.LBB0_1327:
	s_or_b64 exec, exec, s[0:1]
	v_add_f32_e32 v0, v74, v82
	v_add_f32_e32 v1, v75, v83
	v_mul_f32_e32 v0, 0xbfb8aa3b, v0
	v_mul_f32_e32 v1, 0xbfb8aa3b, v1
	v_exp_f32_e32 v0, v0
	v_exp_f32_e32 v1, v1
	v_add_f32_e32 v76, v76, v84
	v_add_f32_e32 v77, v77, v85
	v_add_f32_e32 v0, 1.0, v0
	v_add_f32_e32 v1, 1.0, v1
	v_mul_f32_e32 v76, 0xbfb8aa3b, v76
	v_mul_f32_e32 v77, 0xbfb8aa3b, v77
	v_add_f32_e32 v66, v66, v70
	v_add_f32_e32 v67, v67, v71
	v_rcp_f32_e32 v0, v0
	v_rcp_f32_e32 v1, v1
	v_exp_f32_e32 v76, v76
	v_exp_f32_e32 v77, v77
	v_mul_f32_e32 v66, 0xbfb8aa3b, v66
	v_mul_f32_e32 v67, 0xbfb8aa3b, v67
	v_add_f32_e32 v68, v68, v72
	v_add_f32_e32 v69, v69, v73
	v_exp_f32_e32 v66, v66
	v_exp_f32_e32 v67, v67
	v_mul_f32_e32 v68, 0xbfb8aa3b, v68
	v_mul_f32_e32 v69, 0xbfb8aa3b, v69
	v_exp_f32_e32 v68, v68
	v_exp_f32_e32 v69, v69
	v_lshlrev_b32_e32 v74, 16, v158
	v_and_b32_e32 v75, 0xffff0000, v158
	v_pk_mul_f32 v[0:1], v[0:1], v[74:75]
	v_add_f32_e32 v74, 1.0, v76
	v_add_f32_e32 v75, 1.0, v77
	v_rcp_f32_e32 v74, v74
	v_rcp_f32_e32 v75, v75
	v_add_f32_e32 v66, 1.0, v66
	v_add_f32_e32 v67, 1.0, v67
	v_rcp_f32_e32 v66, v66
	v_rcp_f32_e32 v67, v67
	v_add_f32_e32 v68, 1.0, v68
	v_add_f32_e32 v69, 1.0, v69
	v_rcp_f32_e32 v68, v68
	v_rcp_f32_e32 v69, v69
	v_lshlrev_b32_e32 v76, 16, v159
	v_and_b32_e32 v77, 0xffff0000, v159
	v_pk_mul_f32 v[74:75], v[74:75], v[76:77]
	v_lshlrev_b32_e32 v76, 16, v160
	v_and_b32_e32 v77, 0xffff0000, v160
	v_pk_mul_f32 v[76:77], v[66:67], v[76:77]
	v_lshlrev_b32_e32 v66, 16, v161
	v_and_b32_e32 v67, 0xffff0000, v161
	s_waitcnt lgkmcnt(0)
	v_pk_mul_f32 v[86:87], v[68:69], v[66:67]
	v_cvt_pk_bf16_f32 v66, v0, v1
	v_and_b32_e32 v1, 0xffff0000, v66
	v_lshlrev_b32_e32 v0, 16, v66
	v_mul_f32_e32 v88, v1, v1
	v_fmac_f32_e32 v88, v0, v0
	v_add_f32_e32 v0, v54, v62
	v_add_f32_e32 v1, v55, v63
	v_mul_f32_e32 v0, 0xbfb8aa3b, v0
	v_mul_f32_e32 v1, 0xbfb8aa3b, v1
	v_exp_f32_e32 v0, v0
	v_exp_f32_e32 v1, v1
	v_add_f32_e32 v56, v56, v64
	v_add_f32_e32 v57, v57, v65
	v_add_f32_e32 v0, 1.0, v0
	v_add_f32_e32 v1, 1.0, v1
	v_mul_f32_e32 v56, 0xbfb8aa3b, v56
	v_mul_f32_e32 v57, 0xbfb8aa3b, v57
	v_rcp_f32_e32 v0, v0
	v_rcp_f32_e32 v1, v1
	v_exp_f32_e32 v56, v56
	v_exp_f32_e32 v57, v57
	v_cvt_pk_bf16_f32 v67, v74, v75
	v_add_f32_e32 v50, v50, v58
	v_lshlrev_b32_e32 v74, 16, v67
	v_mul_f32_e32 v50, 0xbfb8aa3b, v50
	v_fmac_f32_e32 v88, v74, v74
	v_lshlrev_b32_e32 v54, 16, v146
	v_and_b32_e32 v55, 0xffff0000, v146
	v_exp_f32_e32 v74, v50
	v_add_f32_e32 v50, v51, v59
	v_and_b32_e32 v75, 0xffff0000, v67
	v_pk_mul_f32 v[0:1], v[0:1], v[54:55]
	v_add_f32_e32 v54, 1.0, v56
	v_add_f32_e32 v55, 1.0, v57
	v_mul_f32_e32 v50, 0xbfb8aa3b, v50
	v_add_f32_e32 v52, v52, v60
	v_add_f32_e32 v53, v53, v61
	v_fmac_f32_e32 v88, v75, v75
	v_rcp_f32_e32 v54, v54
	v_rcp_f32_e32 v55, v55
	v_exp_f32_e32 v75, v50
	v_mul_f32_e32 v52, 0xbfb8aa3b, v52
	v_mul_f32_e32 v53, 0xbfb8aa3b, v53
	v_exp_f32_e32 v52, v52
	v_exp_f32_e32 v53, v53
	v_lshlrev_b32_e32 v56, 16, v147
	v_and_b32_e32 v57, 0xffff0000, v147
	v_pk_mul_f32 v[50:51], v[54:55], v[56:57]
	v_add_f32_e32 v54, 1.0, v74
	v_add_f32_e32 v55, 1.0, v75
	v_rcp_f32_e32 v54, v54
	v_rcp_f32_e32 v55, v55
	v_add_f32_e32 v52, 1.0, v52
	v_add_f32_e32 v53, 1.0, v53
	v_cvt_pk_bf16_f32 v68, v76, v77
	v_rcp_f32_e32 v52, v52
	v_rcp_f32_e32 v53, v53
	v_lshlrev_b32_e32 v76, 16, v68
	v_cvt_pk_bf16_f32 v69, v86, v87
	v_and_b32_e32 v77, 0xffff0000, v68
	v_fmac_f32_e32 v88, v76, v76
	v_lshlrev_b32_e32 v56, 16, v148
	v_and_b32_e32 v57, 0xffff0000, v148
	v_lshlrev_b32_e32 v86, 16, v69
	v_fmac_f32_e32 v88, v77, v77
	v_pk_mul_f32 v[54:55], v[54:55], v[56:57]
	v_lshlrev_b32_e32 v56, 16, v149
	v_and_b32_e32 v57, 0xffff0000, v149
	v_and_b32_e32 v87, 0xffff0000, v69
	v_fmac_f32_e32 v88, v86, v86
	v_pk_mul_f32 v[56:57], v[52:53], v[56:57]
	v_cvt_pk_bf16_f32 v52, v0, v1
	v_fmac_f32_e32 v88, v87, v87
	v_lshlrev_b32_e32 v0, 16, v52
	v_cvt_pk_bf16_f32 v53, v50, v51
	v_and_b32_e32 v1, 0xffff0000, v52
	v_fmac_f32_e32 v88, v0, v0
	v_lshlrev_b32_e32 v50, 16, v53
	v_fmac_f32_e32 v88, v1, v1
	v_cvt_pk_bf16_f32 v54, v54, v55
	v_and_b32_e32 v51, 0xffff0000, v53
	v_fmac_f32_e32 v88, v50, v50
	v_cvt_pk_bf16_f32 v55, v56, v57
	v_lshlrev_b32_e32 v56, 16, v54
	v_fmac_f32_e32 v88, v51, v51
	v_and_b32_e32 v57, 0xffff0000, v54
	v_fmac_f32_e32 v88, v56, v56
	v_lshlrev_b32_e32 v74, 16, v55
	v_fmac_f32_e32 v88, v57, v57
	v_and_b32_e32 v75, 0xffff0000, v55
	v_fmac_f32_e32 v88, v74, v74
	v_fmac_f32_e32 v88, v75, v75
	s_nop 0
	v_lshlrev_b64 v[0:1], 11, v[232:233]
	v_lshl_add_u64 v[0:1], s[14:15], 0, v[0:1]
	v_lshl_add_u64 v[0:1], v[224:225], 1, v[0:1]
	global_store_dwordx4 v[0:1], v[66:69], off
	global_store_dwordx4 v[0:1], v[52:55], off offset:256
	s_waitcnt lgkmcnt(0)
	v_mov_b32_e32 v50, v88
	s_nop 1
	v_permlane16_swap_b32_e32 v50, v88
	v_add_f32_e32 v50, v88, v50
	v_mov_b32_e32 v51, v50
	s_nop 1
	v_permlane32_swap_b32_e32 v51, v50
	s_and_saveexec_b64 s[0:1], vcc
	s_cbranch_execz .LBB0_1329
	s_waitcnt lgkmcnt(0)
	v_add_f32_e32 v0, v50, v51
	ds_write_b32 v218, v0 offset:256
.LBB0_1329:
	s_or_b64 exec, exec, s[0:1]
	v_add_f32_e32 v0, v46, v82
	v_add_f32_e32 v1, v47, v83
	v_mul_f32_e32 v0, 0xbfb8aa3b, v0
	v_mul_f32_e32 v1, 0xbfb8aa3b, v1
	v_exp_f32_e32 v0, v0
	v_exp_f32_e32 v1, v1
	v_add_f32_e32 v48, v48, v84
	v_add_f32_e32 v49, v49, v85
	v_add_f32_e32 v0, 1.0, v0
	v_add_f32_e32 v1, 1.0, v1
	v_mul_f32_e32 v48, 0xbfb8aa3b, v48
	v_mul_f32_e32 v49, 0xbfb8aa3b, v49
	v_add_f32_e32 v42, v42, v70
	v_add_f32_e32 v43, v43, v71
	v_rcp_f32_e32 v0, v0
	v_rcp_f32_e32 v1, v1
	v_exp_f32_e32 v48, v48
	v_exp_f32_e32 v49, v49
	v_mul_f32_e32 v42, 0xbfb8aa3b, v42
	v_mul_f32_e32 v43, 0xbfb8aa3b, v43
	v_add_f32_e32 v44, v44, v72
	v_add_f32_e32 v45, v45, v73
	v_exp_f32_e32 v42, v42
	v_exp_f32_e32 v43, v43
	v_mul_f32_e32 v44, 0xbfb8aa3b, v44
	v_mul_f32_e32 v45, 0xbfb8aa3b, v45
	v_exp_f32_e32 v44, v44
	v_exp_f32_e32 v45, v45
	v_lshlrev_b32_e32 v46, 16, v134
	v_and_b32_e32 v47, 0xffff0000, v134
	v_pk_mul_f32 v[0:1], v[0:1], v[46:47]
	v_add_f32_e32 v46, 1.0, v48
	v_add_f32_e32 v47, 1.0, v49
	v_rcp_f32_e32 v46, v46
	v_rcp_f32_e32 v47, v47
	v_add_f32_e32 v42, 1.0, v42
	v_add_f32_e32 v43, 1.0, v43
	v_rcp_f32_e32 v42, v42
	v_rcp_f32_e32 v43, v43
	v_add_f32_e32 v44, 1.0, v44
	v_add_f32_e32 v45, 1.0, v45
	v_rcp_f32_e32 v44, v44
	v_rcp_f32_e32 v45, v45
	v_lshlrev_b32_e32 v48, 16, v135
	v_and_b32_e32 v49, 0xffff0000, v135
	v_pk_mul_f32 v[46:47], v[46:47], v[48:49]
	v_lshlrev_b32_e32 v48, 16, v136
	v_and_b32_e32 v49, 0xffff0000, v136
	v_pk_mul_f32 v[48:49], v[42:43], v[48:49]
	v_lshlrev_b32_e32 v42, 16, v137
	v_and_b32_e32 v43, 0xffff0000, v137
	s_waitcnt lgkmcnt(0)
	v_pk_mul_f32 v[50:51], v[44:45], v[42:43]
	v_cvt_pk_bf16_f32 v42, v0, v1
	v_and_b32_e32 v1, 0xffff0000, v42
	v_lshlrev_b32_e32 v0, 16, v42
	v_mul_f32_e32 v52, v1, v1
	v_fmac_f32_e32 v52, v0, v0
	v_add_f32_e32 v0, v38, v62
	v_add_f32_e32 v1, v39, v63
	v_mul_f32_e32 v0, 0xbfb8aa3b, v0
	v_mul_f32_e32 v1, 0xbfb8aa3b, v1
	v_exp_f32_e32 v0, v0
	v_exp_f32_e32 v1, v1
	v_add_f32_e32 v40, v40, v64
	v_add_f32_e32 v41, v41, v65
	v_add_f32_e32 v0, 1.0, v0
	v_add_f32_e32 v1, 1.0, v1
	v_mul_f32_e32 v40, 0xbfb8aa3b, v40
	v_mul_f32_e32 v41, 0xbfb8aa3b, v41
	v_rcp_f32_e32 v0, v0
	v_rcp_f32_e32 v1, v1
	v_exp_f32_e32 v40, v40
	v_exp_f32_e32 v41, v41
	v_cvt_pk_bf16_f32 v43, v46, v47
	v_add_f32_e32 v34, v34, v58
	v_lshlrev_b32_e32 v46, 16, v43
	v_mul_f32_e32 v34, 0xbfb8aa3b, v34
	v_fmac_f32_e32 v52, v46, v46
	v_lshlrev_b32_e32 v38, 16, v122
	v_and_b32_e32 v39, 0xffff0000, v122
	v_exp_f32_e32 v46, v34
	v_add_f32_e32 v34, v35, v59
	v_and_b32_e32 v47, 0xffff0000, v43
	v_pk_mul_f32 v[0:1], v[0:1], v[38:39]
	v_add_f32_e32 v38, 1.0, v40
	v_add_f32_e32 v39, 1.0, v41
	v_mul_f32_e32 v34, 0xbfb8aa3b, v34
	v_add_f32_e32 v36, v36, v60
	v_add_f32_e32 v37, v37, v61
	v_fmac_f32_e32 v52, v47, v47
	v_rcp_f32_e32 v38, v38
	v_rcp_f32_e32 v39, v39
	v_exp_f32_e32 v47, v34
	v_mul_f32_e32 v36, 0xbfb8aa3b, v36
	v_mul_f32_e32 v37, 0xbfb8aa3b, v37
	v_exp_f32_e32 v36, v36
	v_exp_f32_e32 v37, v37
	v_lshlrev_b32_e32 v40, 16, v123
	v_and_b32_e32 v41, 0xffff0000, v123
	v_pk_mul_f32 v[34:35], v[38:39], v[40:41]
	v_add_f32_e32 v38, 1.0, v46
	v_add_f32_e32 v39, 1.0, v47
	v_rcp_f32_e32 v38, v38
	v_rcp_f32_e32 v39, v39
	v_add_f32_e32 v36, 1.0, v36
	v_add_f32_e32 v37, 1.0, v37
	v_cvt_pk_bf16_f32 v44, v48, v49
	v_rcp_f32_e32 v36, v36
	v_rcp_f32_e32 v37, v37
	v_lshlrev_b32_e32 v48, 16, v44
	v_cvt_pk_bf16_f32 v45, v50, v51
	v_and_b32_e32 v49, 0xffff0000, v44
	v_fmac_f32_e32 v52, v48, v48
	v_lshlrev_b32_e32 v40, 16, v124
	v_and_b32_e32 v41, 0xffff0000, v124
	v_lshlrev_b32_e32 v50, 16, v45
	v_fmac_f32_e32 v52, v49, v49
	v_pk_mul_f32 v[38:39], v[38:39], v[40:41]
	v_lshlrev_b32_e32 v40, 16, v125
	v_and_b32_e32 v41, 0xffff0000, v125
	v_and_b32_e32 v51, 0xffff0000, v45
	v_fmac_f32_e32 v52, v50, v50
	v_pk_mul_f32 v[40:41], v[36:37], v[40:41]
	v_cvt_pk_bf16_f32 v36, v0, v1
	v_fmac_f32_e32 v52, v51, v51
	v_lshlrev_b32_e32 v0, 16, v36
	v_cvt_pk_bf16_f32 v37, v34, v35
	v_and_b32_e32 v1, 0xffff0000, v36
	v_fmac_f32_e32 v52, v0, v0
	v_lshlrev_b32_e32 v34, 16, v37
	v_fmac_f32_e32 v52, v1, v1
	v_cvt_pk_bf16_f32 v38, v38, v39
	v_and_b32_e32 v35, 0xffff0000, v37
	v_fmac_f32_e32 v52, v34, v34
	v_cvt_pk_bf16_f32 v39, v40, v41
	v_lshlrev_b32_e32 v40, 16, v38
	v_fmac_f32_e32 v52, v35, v35
	v_and_b32_e32 v41, 0xffff0000, v38
	v_fmac_f32_e32 v52, v40, v40
	v_lshlrev_b32_e32 v46, 16, v39
	v_fmac_f32_e32 v52, v41, v41
	v_and_b32_e32 v47, 0xffff0000, v39
	v_fmac_f32_e32 v52, v46, v46
	v_fmac_f32_e32 v52, v47, v47
	s_nop 0
	v_lshlrev_b64 v[0:1], 11, v[230:231]
	v_lshl_add_u64 v[0:1], s[14:15], 0, v[0:1]
	v_lshl_add_u64 v[0:1], v[224:225], 1, v[0:1]
	global_store_dwordx4 v[0:1], v[42:45], off
	global_store_dwordx4 v[0:1], v[36:39], off offset:256
	s_waitcnt lgkmcnt(0)
	v_mov_b32_e32 v34, v52
	s_nop 1
	v_permlane16_swap_b32_e32 v34, v52
	v_add_f32_e32 v34, v52, v34
	v_mov_b32_e32 v35, v34
	s_nop 1
	v_permlane32_swap_b32_e32 v35, v34
	s_and_saveexec_b64 s[0:1], vcc
	s_cbranch_execz .LBB0_1331
	s_waitcnt lgkmcnt(0)
	v_add_f32_e32 v0, v34, v35
	ds_write_b32 v218, v0 offset:320
.LBB0_1331:
	s_or_b64 exec, exec, s[0:1]
	v_add_f32_e32 v0, v30, v82
	v_add_f32_e32 v1, v31, v83
	v_mul_f32_e32 v0, 0xbfb8aa3b, v0
	v_mul_f32_e32 v1, 0xbfb8aa3b, v1
	v_exp_f32_e32 v0, v0
	v_exp_f32_e32 v1, v1
	v_add_f32_e32 v32, v32, v84
	v_add_f32_e32 v33, v33, v85
	v_add_f32_e32 v0, 1.0, v0
	v_add_f32_e32 v1, 1.0, v1
	v_mul_f32_e32 v32, 0xbfb8aa3b, v32
	v_mul_f32_e32 v33, 0xbfb8aa3b, v33
	v_add_f32_e32 v26, v26, v70
	v_add_f32_e32 v27, v27, v71
	v_rcp_f32_e32 v0, v0
	v_rcp_f32_e32 v1, v1
	v_exp_f32_e32 v32, v32
	v_exp_f32_e32 v33, v33
	v_mul_f32_e32 v26, 0xbfb8aa3b, v26
	v_mul_f32_e32 v27, 0xbfb8aa3b, v27
	v_add_f32_e32 v28, v28, v72
	v_add_f32_e32 v29, v29, v73
	v_exp_f32_e32 v26, v26
	v_exp_f32_e32 v27, v27
	v_mul_f32_e32 v28, 0xbfb8aa3b, v28
	v_mul_f32_e32 v29, 0xbfb8aa3b, v29
	v_exp_f32_e32 v28, v28
	v_exp_f32_e32 v29, v29
	v_lshlrev_b32_e32 v30, 16, v110
	v_and_b32_e32 v31, 0xffff0000, v110
	v_pk_mul_f32 v[0:1], v[0:1], v[30:31]
	v_add_f32_e32 v30, 1.0, v32
	v_add_f32_e32 v31, 1.0, v33
	v_rcp_f32_e32 v30, v30
	v_rcp_f32_e32 v31, v31
	v_add_f32_e32 v26, 1.0, v26
	v_add_f32_e32 v27, 1.0, v27
	v_rcp_f32_e32 v26, v26
	v_rcp_f32_e32 v27, v27
	v_add_f32_e32 v28, 1.0, v28
	v_add_f32_e32 v29, 1.0, v29
	v_rcp_f32_e32 v28, v28
	v_rcp_f32_e32 v29, v29
	v_lshlrev_b32_e32 v32, 16, v111
	v_and_b32_e32 v33, 0xffff0000, v111
	v_pk_mul_f32 v[30:31], v[30:31], v[32:33]
	v_lshlrev_b32_e32 v32, 16, v112
	v_and_b32_e32 v33, 0xffff0000, v112
	v_pk_mul_f32 v[32:33], v[26:27], v[32:33]
	v_lshlrev_b32_e32 v26, 16, v113
	v_and_b32_e32 v27, 0xffff0000, v113
	s_waitcnt lgkmcnt(0)
	v_pk_mul_f32 v[34:35], v[28:29], v[26:27]
	v_cvt_pk_bf16_f32 v26, v0, v1
	v_and_b32_e32 v1, 0xffff0000, v26
	v_lshlrev_b32_e32 v0, 16, v26
	v_mul_f32_e32 v36, v1, v1
	v_fmac_f32_e32 v36, v0, v0
	v_add_f32_e32 v0, v22, v62
	v_add_f32_e32 v1, v23, v63
	v_mul_f32_e32 v0, 0xbfb8aa3b, v0
	v_mul_f32_e32 v1, 0xbfb8aa3b, v1
	v_exp_f32_e32 v0, v0
	v_exp_f32_e32 v1, v1
	v_add_f32_e32 v24, v24, v64
	v_add_f32_e32 v25, v25, v65
	v_add_f32_e32 v0, 1.0, v0
	v_add_f32_e32 v1, 1.0, v1
	v_mul_f32_e32 v24, 0xbfb8aa3b, v24
	v_mul_f32_e32 v25, 0xbfb8aa3b, v25
	v_rcp_f32_e32 v0, v0
	v_rcp_f32_e32 v1, v1
	v_exp_f32_e32 v24, v24
	v_exp_f32_e32 v25, v25
	v_cvt_pk_bf16_f32 v27, v30, v31
	v_add_f32_e32 v18, v18, v58
	v_lshlrev_b32_e32 v30, 16, v27
	v_mul_f32_e32 v18, 0xbfb8aa3b, v18
	v_fmac_f32_e32 v36, v30, v30
	v_lshlrev_b32_e32 v22, 16, v98
	v_and_b32_e32 v23, 0xffff0000, v98
	v_exp_f32_e32 v30, v18
	v_add_f32_e32 v18, v19, v59
	v_and_b32_e32 v31, 0xffff0000, v27
	v_pk_mul_f32 v[0:1], v[0:1], v[22:23]
	v_add_f32_e32 v22, 1.0, v24
	v_add_f32_e32 v23, 1.0, v25
	v_mul_f32_e32 v18, 0xbfb8aa3b, v18
	v_add_f32_e32 v20, v20, v60
	v_add_f32_e32 v21, v21, v61
	v_fmac_f32_e32 v36, v31, v31
	v_rcp_f32_e32 v22, v22
	v_rcp_f32_e32 v23, v23
	v_exp_f32_e32 v31, v18
	v_mul_f32_e32 v20, 0xbfb8aa3b, v20
	v_mul_f32_e32 v21, 0xbfb8aa3b, v21
	v_exp_f32_e32 v20, v20
	v_exp_f32_e32 v21, v21
	v_lshlrev_b32_e32 v24, 16, v99
	v_and_b32_e32 v25, 0xffff0000, v99
	v_pk_mul_f32 v[18:19], v[22:23], v[24:25]
	v_add_f32_e32 v22, 1.0, v30
	v_add_f32_e32 v23, 1.0, v31
	v_rcp_f32_e32 v22, v22
	v_rcp_f32_e32 v23, v23
	v_add_f32_e32 v20, 1.0, v20
	v_add_f32_e32 v21, 1.0, v21
	v_cvt_pk_bf16_f32 v28, v32, v33
	v_rcp_f32_e32 v20, v20
	v_rcp_f32_e32 v21, v21
	v_lshlrev_b32_e32 v32, 16, v28
	v_cvt_pk_bf16_f32 v29, v34, v35
	v_and_b32_e32 v33, 0xffff0000, v28
	v_fmac_f32_e32 v36, v32, v32
	v_lshlrev_b32_e32 v24, 16, v100
	v_and_b32_e32 v25, 0xffff0000, v100
	v_lshlrev_b32_e32 v34, 16, v29
	v_fmac_f32_e32 v36, v33, v33
	v_pk_mul_f32 v[22:23], v[22:23], v[24:25]
	v_lshlrev_b32_e32 v24, 16, v101
	v_and_b32_e32 v25, 0xffff0000, v101
	v_and_b32_e32 v35, 0xffff0000, v29
	v_fmac_f32_e32 v36, v34, v34
	v_pk_mul_f32 v[24:25], v[20:21], v[24:25]
	v_cvt_pk_bf16_f32 v20, v0, v1
	v_fmac_f32_e32 v36, v35, v35
	v_lshlrev_b32_e32 v0, 16, v20
	v_cvt_pk_bf16_f32 v21, v18, v19
	v_and_b32_e32 v1, 0xffff0000, v20
	v_fmac_f32_e32 v36, v0, v0
	v_lshlrev_b32_e32 v18, 16, v21
	v_fmac_f32_e32 v36, v1, v1
	v_cvt_pk_bf16_f32 v22, v22, v23
	v_and_b32_e32 v19, 0xffff0000, v21
	v_fmac_f32_e32 v36, v18, v18
	v_cvt_pk_bf16_f32 v23, v24, v25
	v_lshlrev_b32_e32 v24, 16, v22
	v_fmac_f32_e32 v36, v19, v19
	v_and_b32_e32 v25, 0xffff0000, v22
	v_fmac_f32_e32 v36, v24, v24
	v_lshlrev_b32_e32 v30, 16, v23
	v_fmac_f32_e32 v36, v25, v25
	v_and_b32_e32 v31, 0xffff0000, v23
	v_fmac_f32_e32 v36, v30, v30
	v_fmac_f32_e32 v36, v31, v31
	s_nop 0
	v_lshlrev_b64 v[0:1], 11, v[228:229]
	v_lshl_add_u64 v[0:1], s[14:15], 0, v[0:1]
	v_lshl_add_u64 v[0:1], v[224:225], 1, v[0:1]
	global_store_dwordx4 v[0:1], v[26:29], off
	global_store_dwordx4 v[0:1], v[20:23], off offset:256
	s_waitcnt lgkmcnt(0)
	v_mov_b32_e32 v18, v36
	s_nop 1
	v_permlane16_swap_b32_e32 v18, v36
	v_add_f32_e32 v18, v36, v18
	v_mov_b32_e32 v19, v18
	s_nop 1
	v_permlane32_swap_b32_e32 v19, v18
	s_and_saveexec_b64 s[0:1], vcc
	s_cbranch_execz .LBB0_1333
	s_waitcnt lgkmcnt(0)
	v_add_f32_e32 v0, v18, v19
	ds_write_b32 v218, v0 offset:384
.LBB0_1333:
	s_or_b64 exec, exec, s[0:1]
	v_add_f32_e32 v0, v14, v82
	v_add_f32_e32 v1, v15, v83
	v_mul_f32_e32 v0, 0xbfb8aa3b, v0
	v_mul_f32_e32 v1, 0xbfb8aa3b, v1
	v_exp_f32_e32 v0, v0
	v_exp_f32_e32 v1, v1
	v_add_f32_e32 v16, v16, v84
	v_add_f32_e32 v17, v17, v85
	v_add_f32_e32 v0, 1.0, v0
	v_add_f32_e32 v1, 1.0, v1
	v_mul_f32_e32 v16, 0xbfb8aa3b, v16
	v_mul_f32_e32 v17, 0xbfb8aa3b, v17
	v_add_f32_e32 v10, v10, v70
	v_add_f32_e32 v11, v11, v71
	v_rcp_f32_e32 v0, v0
	v_rcp_f32_e32 v1, v1
	v_exp_f32_e32 v16, v16
	v_exp_f32_e32 v17, v17
	v_mul_f32_e32 v10, 0xbfb8aa3b, v10
	v_mul_f32_e32 v11, 0xbfb8aa3b, v11
	v_add_f32_e32 v12, v12, v72
	v_add_f32_e32 v13, v13, v73
	v_exp_f32_e32 v10, v10
	v_exp_f32_e32 v11, v11
	v_mul_f32_e32 v12, 0xbfb8aa3b, v12
	v_mul_f32_e32 v13, 0xbfb8aa3b, v13
	v_exp_f32_e32 v12, v12
	v_exp_f32_e32 v13, v13
	v_lshlrev_b32_e32 v14, 16, v90
	v_and_b32_e32 v15, 0xffff0000, v90
	v_pk_mul_f32 v[0:1], v[0:1], v[14:15]
	v_add_f32_e32 v14, 1.0, v16
	v_add_f32_e32 v15, 1.0, v17
	v_rcp_f32_e32 v14, v14
	v_rcp_f32_e32 v15, v15
	v_add_f32_e32 v10, 1.0, v10
	v_add_f32_e32 v11, 1.0, v11
	v_rcp_f32_e32 v10, v10
	v_rcp_f32_e32 v11, v11
	v_add_f32_e32 v12, 1.0, v12
	v_add_f32_e32 v13, 1.0, v13
	v_rcp_f32_e32 v12, v12
	v_rcp_f32_e32 v13, v13
	v_lshlrev_b32_e32 v16, 16, v91
	v_and_b32_e32 v17, 0xffff0000, v91
	v_pk_mul_f32 v[14:15], v[14:15], v[16:17]
	v_lshlrev_b32_e32 v16, 16, v92
	v_and_b32_e32 v17, 0xffff0000, v92
	v_pk_mul_f32 v[16:17], v[10:11], v[16:17]
	v_lshlrev_b32_e32 v10, 16, v93
	v_and_b32_e32 v11, 0xffff0000, v93
	s_waitcnt lgkmcnt(0)
	v_pk_mul_f32 v[18:19], v[12:13], v[10:11]
	v_cvt_pk_bf16_f32 v10, v0, v1
	v_and_b32_e32 v1, 0xffff0000, v10
	v_lshlrev_b32_e32 v0, 16, v10
	v_mul_f32_e32 v20, v1, v1
	v_fmac_f32_e32 v20, v0, v0
	v_add_f32_e32 v0, v6, v62
	v_add_f32_e32 v1, v7, v63
	v_mul_f32_e32 v0, 0xbfb8aa3b, v0
	v_mul_f32_e32 v1, 0xbfb8aa3b, v1
	v_exp_f32_e32 v0, v0
	v_exp_f32_e32 v1, v1
	v_add_f32_e32 v8, v8, v64
	v_add_f32_e32 v9, v9, v65
	v_add_f32_e32 v0, 1.0, v0
	v_add_f32_e32 v1, 1.0, v1
	v_mul_f32_e32 v8, 0xbfb8aa3b, v8
	v_mul_f32_e32 v9, 0xbfb8aa3b, v9
	v_rcp_f32_e32 v0, v0
	v_rcp_f32_e32 v1, v1
	v_exp_f32_e32 v8, v8
	v_exp_f32_e32 v9, v9
	v_cvt_pk_bf16_f32 v11, v14, v15
	v_add_f32_e32 v2, v2, v58
	v_lshlrev_b32_e32 v14, 16, v11
	v_mul_f32_e32 v2, 0xbfb8aa3b, v2
	v_fmac_f32_e32 v20, v14, v14
	v_lshlrev_b32_e32 v6, 16, v78
	v_and_b32_e32 v7, 0xffff0000, v78
	v_exp_f32_e32 v14, v2
	v_add_f32_e32 v2, v3, v59
	v_and_b32_e32 v15, 0xffff0000, v11
	v_pk_mul_f32 v[0:1], v[0:1], v[6:7]
	v_add_f32_e32 v6, 1.0, v8
	v_add_f32_e32 v7, 1.0, v9
	v_mul_f32_e32 v2, 0xbfb8aa3b, v2
	v_add_f32_e32 v4, v4, v60
	v_add_f32_e32 v5, v5, v61
	v_fmac_f32_e32 v20, v15, v15
	v_rcp_f32_e32 v6, v6
	v_rcp_f32_e32 v7, v7
	v_exp_f32_e32 v15, v2
	v_mul_f32_e32 v4, 0xbfb8aa3b, v4
	v_mul_f32_e32 v5, 0xbfb8aa3b, v5
	v_exp_f32_e32 v4, v4
	v_exp_f32_e32 v5, v5
	v_lshlrev_b32_e32 v8, 16, v79
	v_and_b32_e32 v9, 0xffff0000, v79
	v_pk_mul_f32 v[2:3], v[6:7], v[8:9]
	v_add_f32_e32 v6, 1.0, v14
	v_add_f32_e32 v7, 1.0, v15
	v_rcp_f32_e32 v6, v6
	v_rcp_f32_e32 v7, v7
	v_add_f32_e32 v4, 1.0, v4
	v_add_f32_e32 v5, 1.0, v5
	v_cvt_pk_bf16_f32 v12, v16, v17
	v_rcp_f32_e32 v4, v4
	v_rcp_f32_e32 v5, v5
	v_lshlrev_b32_e32 v16, 16, v12
	v_cvt_pk_bf16_f32 v13, v18, v19
	v_and_b32_e32 v17, 0xffff0000, v12
	v_fmac_f32_e32 v20, v16, v16
	v_lshlrev_b32_e32 v8, 16, v80
	v_and_b32_e32 v9, 0xffff0000, v80
	v_lshlrev_b32_e32 v18, 16, v13
	v_fmac_f32_e32 v20, v17, v17
	v_pk_mul_f32 v[6:7], v[6:7], v[8:9]
	v_lshlrev_b32_e32 v8, 16, v81
	v_and_b32_e32 v9, 0xffff0000, v81
	v_and_b32_e32 v19, 0xffff0000, v13
	v_fmac_f32_e32 v20, v18, v18
	v_pk_mul_f32 v[8:9], v[4:5], v[8:9]
	v_cvt_pk_bf16_f32 v4, v0, v1
	v_fmac_f32_e32 v20, v19, v19
	v_lshlrev_b32_e32 v0, 16, v4
	v_cvt_pk_bf16_f32 v5, v2, v3
	v_and_b32_e32 v1, 0xffff0000, v4
	v_fmac_f32_e32 v20, v0, v0
	v_lshlrev_b32_e32 v2, 16, v5
	v_fmac_f32_e32 v20, v1, v1
	v_cvt_pk_bf16_f32 v6, v6, v7
	v_and_b32_e32 v3, 0xffff0000, v5
	v_fmac_f32_e32 v20, v2, v2
	v_cvt_pk_bf16_f32 v7, v8, v9
	v_lshlrev_b32_e32 v8, 16, v6
	v_fmac_f32_e32 v20, v3, v3
	v_and_b32_e32 v9, 0xffff0000, v6
	v_fmac_f32_e32 v20, v8, v8
	v_lshlrev_b32_e32 v14, 16, v7
	v_fmac_f32_e32 v20, v9, v9
	v_and_b32_e32 v15, 0xffff0000, v7
	v_fmac_f32_e32 v20, v14, v14
	v_fmac_f32_e32 v20, v15, v15
	s_nop 0
	v_lshlrev_b64 v[0:1], 11, v[226:227]
	v_lshl_add_u64 v[0:1], s[14:15], 0, v[0:1]
	v_lshl_add_u64 v[0:1], v[224:225], 1, v[0:1]
	global_store_dwordx4 v[0:1], v[10:13], off
	global_store_dwordx4 v[0:1], v[4:7], off offset:256
	s_waitcnt lgkmcnt(0)
	v_mov_b32_e32 v2, v20
	s_nop 1
	v_permlane16_swap_b32_e32 v2, v20
	v_add_f32_e32 v2, v20, v2
	v_mov_b32_e32 v3, v2
	s_nop 1
	v_permlane32_swap_b32_e32 v3, v2
	s_and_saveexec_b64 s[0:1], vcc
	s_cbranch_execz .LBB0_1335
	s_waitcnt lgkmcnt(0)
	v_add_f32_e32 v0, v2, v3
	ds_write_b32 v218, v0 offset:448

.LBB0_1709:
	v_readlane_b32 s36, v255, 31
	s_lshl_b32 s18, s36, 8
	v_mov_b32_e32 v195, v184
	v_mov_b32_e32 v202, v185
	s_or_b32 s18, s18, s67
	v_readlane_b32 s37, v255, 32
	v_lshl_add_u32 v160, v202, 3, s18
	s_ashr_i32 s18, s84, 31
	s_lshr_b32 s18, s18, 29
	s_add_i32 s18, s84, s18
	s_ashr_i32 s18, s18, 3
	s_mul_i32 s36, s18, 3
	s_ashr_i32 s37, s36, 31
	s_lshl_b64 s[36:37], s[36:37], 12
	s_add_u32 s36, s60, s36
	s_addc_u32 s37, s61, s37
	s_lshl_b32 s18, s84, 8
	v_add_u32_e32 v193, s66, v195
	v_add_u32_e32 v178, s18, v193
	v_ashrrev_i32_e32 v179, 31, v178
	v_ashrrev_i32_e32 v161, 31, v160
	v_lshlrev_b64 v[162:163], 12, v[178:179]
	v_lshlrev_b64 v[180:181], 1, v[160:161]
	v_lshl_add_u64 v[128:129], s[74:75], 0, v[162:163]
	v_lshl_add_u64 v[130:131], v[128:129], 0, v[180:181]
	v_lshl_add_u64 v[182:183], v[180:181], 0, s[22:23]
	global_load_dwordx4 v[166:169], v[130:131], off
	v_lshl_add_u64 v[128:129], v[128:129], 0, v[182:183]
	global_load_dwordx4 v[170:173], v[128:129], off
	v_lshl_add_u64 v[132:133], v[160:161], 2, s[36:37]
	global_load_dwordx4 v[136:139], v[132:133], off
	global_load_dwordx4 v[128:131], v[132:133], off offset:16
	global_load_dwordx4 v[140:143], v[132:133], off offset:512
	s_nop 0
	global_load_dwordx4 v[132:135], v[132:133], off offset:528
	v_add_u32_e32 v144, 16, v178
	v_ashrrev_i32_e32 v145, 31, v144
	v_lshlrev_b64 v[164:165], 12, v[144:145]
	v_lshl_add_u64 v[144:145], s[74:75], 0, v[164:165]
	v_lshl_add_u64 v[146:147], v[144:145], 0, v[180:181]
	v_lshl_add_u64 v[144:145], v[144:145], 0, v[182:183]
	global_load_dwordx4 v[148:151], v[146:147], off
	s_nop 0
	global_load_dwordx4 v[144:147], v[144:145], off
	v_and_b32_e32 v175, 64, v191
	v_xor_b32_e32 v174, 16, v191
	v_add_u32_e32 v179, 64, v175
	v_cmp_lt_i32_e32 vcc, v174, v179
	v_lshl_add_u32 v195, v195, 2, s70
	s_waitcnt vmcnt(0)
	v_and_b32_e32 v175, 0xffff0000, v166
	v_cndmask_b32_e32 v174, v191, v174, vcc
	v_lshlrev_b32_e32 v194, 2, v174
	v_lshlrev_b32_e32 v174, 16, v166
	v_lshlrev_b32_e32 v176, 16, v167
	v_and_b32_e32 v177, 0xffff0000, v167
	v_lshlrev_b32_e32 v196, 16, v168
	v_and_b32_e32 v197, 0xffff0000, v168
	v_lshlrev_b32_e32 v168, 16, v169
	v_and_b32_e32 v169, 0xffff0000, v169
	v_lshlrev_b32_e32 v198, 16, v170
	v_and_b32_e32 v199, 0xffff0000, v170
	v_lshlrev_b32_e32 v170, 16, v171
	v_and_b32_e32 v171, 0xffff0000, v171
	v_lshlrev_b32_e32 v200, 16, v172
	v_and_b32_e32 v201, 0xffff0000, v172
	v_lshlrev_b32_e32 v172, 16, v173
	v_and_b32_e32 v173, 0xffff0000, v173
	v_pk_fma_f32 v[166:167], v[124:125], v[136:137], v[174:175]
	v_pk_fma_f32 v[126:127], v[126:127], v[138:139], v[176:177]
	v_pk_fma_f32 v[124:125], v[120:121], v[128:129], v[196:197]
	v_pk_fma_f32 v[122:123], v[122:123], v[130:131], v[168:169]
	v_pk_fma_f32 v[120:121], v[116:117], v[140:141], v[198:199]
	v_pk_fma_f32 v[116:117], v[118:119], v[142:143], v[170:171]
	v_pk_fma_f32 v[114:115], v[114:115], v[134:135], v[172:173]
	v_pk_mul_f32 v[118:119], v[166:167], v[166:167]
	v_pk_mul_f32 v[168:169], v[126:127], v[126:127]
	v_pk_mul_f32 v[170:171], v[124:125], v[124:125]
	v_pk_mul_f32 v[172:173], v[122:123], v[122:123]
	v_pk_fma_f32 v[112:113], v[112:113], v[132:133], v[200:201]
	v_pk_mul_f32 v[174:175], v[120:121], v[120:121]
	v_pk_mul_f32 v[176:177], v[116:117], v[116:117]
	v_add_f32_e32 v172, v172, v173
	v_add_f32_e32 v170, v170, v171
	v_add_f32_e32 v168, v168, v169
	v_add_f32_e32 v118, v118, v119
	v_pk_mul_f32 v[196:197], v[112:113], v[112:113]
	v_pk_mul_f32 v[198:199], v[114:115], v[114:115]
	v_add_f32_e32 v119, v176, v177
	v_add_f32_e32 v169, v174, v175
	v_add_f32_e32 v170, v170, v172
	v_add_f32_e32 v118, v118, v168
	v_add_f32_e32 v171, v198, v199
	v_add_f32_e32 v173, v196, v197
	v_add_f32_e32 v119, v169, v119
	v_add_f32_e32 v118, v118, v170
	v_add_f32_e32 v118, v118, v119
	v_add_f32_e32 v119, v173, v171
	v_add_f32_e32 v118, v119, v118
	s_nop 0
	v_xor_b32_e32 v168, 32, v191
	v_cmp_lt_i32_e32 vcc, v168, v179
	s_waitcnt lgkmcnt(0)
	v_mov_b32_e32 v119, v118
	s_nop 1
	v_permlane16_swap_b32_e32 v119, v118
	v_add_f32_e32 v118, v118, v119
	v_cndmask_b32_e32 v168, v191, v168, vcc
	v_lshlrev_b32_e32 v196, 2, v168
	v_mov_b32_e32 v119, v118
	s_nop 1
	v_permlane32_swap_b32_e32 v119, v118
	v_cmp_eq_u32_e32 vcc, 0, v202
	s_and_saveexec_b64 s[36:37], vcc
	s_cbranch_execz .LBB0_1711
	s_waitcnt lgkmcnt(0)
	v_add_f32_e32 v118, v118, v119
	ds_write_b32 v195, v118
.LBB0_1711:
	s_or_b64 exec, exec, s[36:37]
	v_lshlrev_b32_e32 v118, 16, v148
	s_waitcnt lgkmcnt(0)
	v_and_b32_e32 v119, 0xffff0000, v148
	v_pk_fma_f32 v[108:109], v[108:109], v[136:137], v[118:119]
	v_lshlrev_b32_e32 v118, 16, v149
	v_and_b32_e32 v119, 0xffff0000, v149
	v_pk_fma_f32 v[110:111], v[110:111], v[138:139], v[118:119]
	v_lshlrev_b32_e32 v118, 16, v150
	v_and_b32_e32 v119, 0xffff0000, v150
	v_pk_fma_f32 v[104:105], v[104:105], v[128:129], v[118:119]
	v_lshlrev_b32_e32 v118, 16, v151
	v_and_b32_e32 v119, 0xffff0000, v151
	v_pk_fma_f32 v[106:107], v[106:107], v[130:131], v[118:119]
	v_lshlrev_b32_e32 v118, 16, v144
	v_and_b32_e32 v119, 0xffff0000, v144
	v_pk_mul_f32 v[172:173], v[104:105], v[104:105]
	v_pk_mul_f32 v[174:175], v[106:107], v[106:107]
	v_pk_fma_f32 v[118:119], v[100:101], v[140:141], v[118:119]
	v_lshlrev_b32_e32 v100, 16, v145
	v_and_b32_e32 v101, 0xffff0000, v145
	v_lshlrev_b32_e32 v144, 16, v146
	v_and_b32_e32 v145, 0xffff0000, v146
	v_pk_mul_f32 v[168:169], v[108:109], v[108:109]
	v_pk_mul_f32 v[170:171], v[110:111], v[110:111]
	v_pk_fma_f32 v[148:149], v[102:103], v[142:143], v[100:101]
	v_pk_fma_f32 v[150:151], v[96:97], v[132:133], v[144:145]
	v_lshlrev_b32_e32 v96, 16, v147
	v_and_b32_e32 v97, 0xffff0000, v147
	v_add_f32_e32 v144, v174, v175
	v_add_f32_e32 v145, v172, v173
	v_pk_mul_f32 v[100:101], v[118:119], v[118:119]
	v_pk_mul_f32 v[102:103], v[148:149], v[148:149]
	v_pk_fma_f32 v[146:147], v[98:99], v[134:135], v[96:97]
	v_add_f32_e32 v144, v145, v144
	v_add_f32_e32 v145, v170, v171
	v_add_f32_e32 v168, v168, v169
	v_pk_mul_f32 v[96:97], v[150:151], v[150:151]
	v_pk_mul_f32 v[98:99], v[146:147], v[146:147]
	v_add_f32_e32 v145, v168, v145
	v_add_f32_e32 v102, v102, v103
	v_add_f32_e32 v100, v100, v101
	v_add_f32_e32 v144, v145, v144
	v_add_f32_e32 v100, v100, v102
	v_add_f32_e32 v98, v98, v99
	v_add_f32_e32 v96, v96, v97
	v_add_f32_e32 v100, v144, v100
	v_add_f32_e32 v96, v96, v98
	v_add_f32_e32 v96, v96, v100
	s_nop 0
	s_waitcnt lgkmcnt(0)
	v_mov_b32_e32 v97, v96
	s_nop 1
	v_permlane16_swap_b32_e32 v97, v96
	v_add_f32_e32 v96, v96, v97
	v_mov_b32_e32 v97, v96
	s_nop 1
	v_permlane32_swap_b32_e32 v97, v96
	s_and_saveexec_b64 s[36:37], vcc
	s_cbranch_execz .LBB0_1713
	s_waitcnt lgkmcnt(0)
	v_add_f32_e32 v96, v96, v97
	ds_write_b32 v195, v96 offset:64
.LBB0_1713:
	s_or_b64 exec, exec, s[36:37]
	v_add_u32_e32 v96, 32, v178
	s_waitcnt lgkmcnt(0)
	v_ashrrev_i32_e32 v97, 31, v96
	v_lshlrev_b64 v[168:169], 12, v[96:97]
	v_lshl_add_u64 v[96:97], s[74:75], 0, v[168:169]
	v_lshl_add_u64 v[98:99], v[96:97], 0, v[180:181]
	global_load_dwordx4 v[170:173], v[98:99], off
	v_lshl_add_u64 v[96:97], v[96:97], 0, v[182:183]
	global_load_dwordx4 v[174:177], v[96:97], off
	v_add_u32_e32 v96, 48, v178
	v_ashrrev_i32_e32 v97, 31, v96
	v_lshlrev_b64 v[144:145], 12, v[96:97]
	v_lshl_add_u64 v[96:97], s[74:75], 0, v[144:145]
	v_lshl_add_u64 v[98:99], v[96:97], 0, v[180:181]
	v_lshl_add_u64 v[96:97], v[96:97], 0, v[182:183]
	global_load_dwordx4 v[100:103], v[98:99], off
	s_nop 0
	global_load_dwordx4 v[96:99], v[96:97], off
	s_waitcnt vmcnt(3)
	v_lshlrev_b32_e32 v198, 16, v170
	v_and_b32_e32 v199, 0xffff0000, v170
	v_lshlrev_b32_e32 v200, 16, v171
	v_and_b32_e32 v201, 0xffff0000, v171
	v_lshlrev_b32_e32 v202, 16, v172
	v_and_b32_e32 v203, 0xffff0000, v172
	v_lshlrev_b32_e32 v172, 16, v173
	v_and_b32_e32 v173, 0xffff0000, v173
	s_waitcnt vmcnt(2)
	v_lshlrev_b32_e32 v204, 16, v174
	v_and_b32_e32 v205, 0xffff0000, v174
	v_lshlrev_b32_e32 v174, 16, v175
	v_and_b32_e32 v175, 0xffff0000, v175
	v_lshlrev_b32_e32 v206, 16, v176
	v_and_b32_e32 v207, 0xffff0000, v176
	v_lshlrev_b32_e32 v176, 16, v177
	v_and_b32_e32 v177, 0xffff0000, v177
	v_pk_fma_f32 v[170:171], v[92:93], v[136:137], v[198:199]
	v_pk_fma_f32 v[94:95], v[94:95], v[138:139], v[200:201]
	v_pk_fma_f32 v[92:93], v[88:89], v[128:129], v[202:203]
	v_pk_fma_f32 v[90:91], v[90:91], v[130:131], v[172:173]
	v_pk_fma_f32 v[88:89], v[84:85], v[140:141], v[204:205]
	v_pk_fma_f32 v[84:85], v[86:87], v[142:143], v[174:175]
	v_pk_fma_f32 v[82:83], v[82:83], v[134:135], v[176:177]
	v_pk_mul_f32 v[86:87], v[170:171], v[170:171]
	v_pk_mul_f32 v[172:173], v[94:95], v[94:95]
	v_pk_mul_f32 v[174:175], v[92:93], v[92:93]
	v_pk_mul_f32 v[176:177], v[90:91], v[90:91]
	v_pk_fma_f32 v[80:81], v[80:81], v[132:133], v[206:207]
	v_pk_mul_f32 v[198:199], v[88:89], v[88:89]
	v_pk_mul_f32 v[200:201], v[84:85], v[84:85]
	v_add_f32_e32 v176, v176, v177
	v_add_f32_e32 v174, v174, v175
	v_add_f32_e32 v172, v172, v173
	v_add_f32_e32 v86, v86, v87
	v_pk_mul_f32 v[202:203], v[80:81], v[80:81]
	v_pk_mul_f32 v[204:205], v[82:83], v[82:83]
	v_add_f32_e32 v87, v200, v201
	v_add_f32_e32 v173, v198, v199
	v_add_f32_e32 v174, v174, v176
	v_add_f32_e32 v86, v86, v172
	v_add_f32_e32 v175, v204, v205
	v_add_f32_e32 v177, v202, v203
	v_add_f32_e32 v87, v173, v87
	v_add_f32_e32 v86, v86, v174
	v_add_f32_e32 v86, v86, v87
	v_add_f32_e32 v87, v177, v175
	v_add_f32_e32 v86, v87, v86
	s_nop 0
	s_waitcnt lgkmcnt(0)
	v_mov_b32_e32 v87, v86
	s_nop 1
	v_permlane16_swap_b32_e32 v87, v86
	v_add_f32_e32 v86, v86, v87
	v_mov_b32_e32 v87, v86
	s_nop 1
	v_permlane32_swap_b32_e32 v87, v86
	s_and_saveexec_b64 s[36:37], vcc
	s_cbranch_execz .LBB0_1715
	s_waitcnt lgkmcnt(0)
	v_add_f32_e32 v86, v86, v87
	ds_write_b32 v195, v86 offset:128
.LBB0_1715:
	s_or_b64 exec, exec, s[36:37]
	s_waitcnt vmcnt(1)
	v_lshlrev_b32_e32 v86, 16, v100
	s_waitcnt lgkmcnt(0)
	v_and_b32_e32 v87, 0xffff0000, v100
	v_pk_fma_f32 v[76:77], v[76:77], v[136:137], v[86:87]
	v_lshlrev_b32_e32 v86, 16, v101
	v_and_b32_e32 v87, 0xffff0000, v101
	v_pk_fma_f32 v[78:79], v[78:79], v[138:139], v[86:87]
	v_lshlrev_b32_e32 v86, 16, v102
	v_and_b32_e32 v87, 0xffff0000, v102
	v_pk_fma_f32 v[72:73], v[72:73], v[128:129], v[86:87]
	v_lshlrev_b32_e32 v86, 16, v103
	v_and_b32_e32 v87, 0xffff0000, v103
	v_pk_fma_f32 v[74:75], v[74:75], v[130:131], v[86:87]
	s_waitcnt vmcnt(0)
	v_lshlrev_b32_e32 v86, 16, v96
	v_and_b32_e32 v87, 0xffff0000, v96
	v_pk_mul_f32 v[176:177], v[72:73], v[72:73]
	v_pk_mul_f32 v[198:199], v[74:75], v[74:75]
	v_pk_fma_f32 v[86:87], v[68:69], v[140:141], v[86:87]
	v_lshlrev_b32_e32 v68, 16, v97
	v_and_b32_e32 v69, 0xffff0000, v97
	v_lshlrev_b32_e32 v96, 16, v98
	v_and_b32_e32 v97, 0xffff0000, v98
	v_pk_mul_f32 v[172:173], v[76:77], v[76:77]
	v_pk_mul_f32 v[174:175], v[78:79], v[78:79]
	v_pk_fma_f32 v[100:101], v[70:71], v[142:143], v[68:69]
	v_pk_fma_f32 v[102:103], v[64:65], v[132:133], v[96:97]
	v_lshlrev_b32_e32 v64, 16, v99
	v_and_b32_e32 v65, 0xffff0000, v99
	v_add_f32_e32 v96, v198, v199
	v_add_f32_e32 v97, v176, v177
	v_pk_mul_f32 v[68:69], v[86:87], v[86:87]
	v_pk_mul_f32 v[70:71], v[100:101], v[100:101]
	v_pk_fma_f32 v[98:99], v[66:67], v[134:135], v[64:65]
	v_add_f32_e32 v96, v97, v96
	v_add_f32_e32 v97, v174, v175
	v_add_f32_e32 v172, v172, v173
	v_pk_mul_f32 v[64:65], v[102:103], v[102:103]
	v_pk_mul_f32 v[66:67], v[98:99], v[98:99]
	v_add_f32_e32 v97, v172, v97
	v_add_f32_e32 v70, v70, v71
	v_add_f32_e32 v68, v68, v69
	v_add_f32_e32 v96, v97, v96
	v_add_f32_e32 v68, v68, v70
	v_add_f32_e32 v66, v66, v67
	v_add_f32_e32 v64, v64, v65
	v_add_f32_e32 v68, v96, v68
	v_add_f32_e32 v64, v64, v66
	v_add_f32_e32 v64, v64, v68
	s_nop 0
	s_waitcnt lgkmcnt(0)
	v_mov_b32_e32 v65, v64
	s_nop 1
	v_permlane16_swap_b32_e32 v65, v64
	v_add_f32_e32 v64, v64, v65
	v_mov_b32_e32 v65, v64
	s_nop 1
	v_permlane32_swap_b32_e32 v65, v64
	s_and_saveexec_b64 s[36:37], vcc
	s_cbranch_execz .LBB0_1717
	s_waitcnt lgkmcnt(0)
	v_add_f32_e32 v64, v64, v65
	ds_write_b32 v195, v64 offset:192
.LBB0_1717:
	s_or_b64 exec, exec, s[36:37]
	v_add_u32_e32 v64, 0x80, v178
	s_waitcnt lgkmcnt(0)
	v_ashrrev_i32_e32 v65, 31, v64
	v_lshlrev_b64 v[172:173], 12, v[64:65]
	v_lshl_add_u64 v[64:65], s[74:75], 0, v[172:173]
	v_lshl_add_u64 v[66:67], v[64:65], 0, v[180:181]
	global_load_dwordx4 v[174:177], v[66:67], off
	v_lshl_add_u64 v[64:65], v[64:65], 0, v[182:183]
	global_load_dwordx4 v[198:201], v[64:65], off
	v_add_u32_e32 v64, 0x90, v178
	v_ashrrev_i32_e32 v65, 31, v64
	v_lshlrev_b64 v[96:97], 12, v[64:65]
	v_lshl_add_u64 v[64:65], s[74:75], 0, v[96:97]
	v_lshl_add_u64 v[66:67], v[64:65], 0, v[180:181]
	v_lshl_add_u64 v[64:65], v[64:65], 0, v[182:183]
	global_load_dwordx4 v[68:71], v[66:67], off
	s_nop 0
	global_load_dwordx4 v[64:67], v[64:65], off
	s_waitcnt vmcnt(3)
	v_lshlrev_b32_e32 v202, 16, v174
	v_and_b32_e32 v203, 0xffff0000, v174
	v_lshlrev_b32_e32 v204, 16, v175
	v_and_b32_e32 v205, 0xffff0000, v175
	v_lshlrev_b32_e32 v206, 16, v176
	v_and_b32_e32 v207, 0xffff0000, v176
	v_lshlrev_b32_e32 v176, 16, v177
	v_and_b32_e32 v177, 0xffff0000, v177
	s_waitcnt vmcnt(2)
	v_lshlrev_b32_e32 v208, 16, v198
	v_and_b32_e32 v209, 0xffff0000, v198
	v_lshlrev_b32_e32 v198, 16, v199
	v_and_b32_e32 v199, 0xffff0000, v199
	v_lshlrev_b32_e32 v210, 16, v200
	v_and_b32_e32 v211, 0xffff0000, v200
	v_lshlrev_b32_e32 v200, 16, v201
	v_and_b32_e32 v201, 0xffff0000, v201
	v_pk_fma_f32 v[174:175], v[60:61], v[136:137], v[202:203]
	v_pk_fma_f32 v[62:63], v[62:63], v[138:139], v[204:205]
	v_pk_fma_f32 v[60:61], v[56:57], v[128:129], v[206:207]
	v_pk_fma_f32 v[58:59], v[58:59], v[130:131], v[176:177]
	v_pk_fma_f32 v[56:57], v[52:53], v[140:141], v[208:209]
	v_pk_fma_f32 v[52:53], v[54:55], v[142:143], v[198:199]
	v_pk_fma_f32 v[50:51], v[50:51], v[134:135], v[200:201]
	v_pk_mul_f32 v[54:55], v[174:175], v[174:175]
	v_pk_mul_f32 v[176:177], v[62:63], v[62:63]
	v_pk_mul_f32 v[198:199], v[60:61], v[60:61]
	v_pk_mul_f32 v[200:201], v[58:59], v[58:59]
	v_pk_fma_f32 v[48:49], v[48:49], v[132:133], v[210:211]
	v_pk_mul_f32 v[202:203], v[56:57], v[56:57]
	v_pk_mul_f32 v[204:205], v[52:53], v[52:53]
	v_add_f32_e32 v179, v200, v201
	v_add_f32_e32 v197, v198, v199
	v_add_f32_e32 v176, v176, v177
	v_add_f32_e32 v54, v54, v55
	v_pk_mul_f32 v[206:207], v[48:49], v[48:49]
	v_pk_mul_f32 v[208:209], v[50:51], v[50:51]
	v_add_f32_e32 v55, v204, v205
	v_add_f32_e32 v177, v202, v203
	v_add_f32_e32 v179, v197, v179
	v_add_f32_e32 v54, v54, v176
	v_add_f32_e32 v198, v208, v209
	v_add_f32_e32 v199, v206, v207
	v_add_f32_e32 v55, v177, v55
	v_add_f32_e32 v54, v54, v179
	v_add_f32_e32 v54, v54, v55
	v_add_f32_e32 v55, v199, v198
	v_add_f32_e32 v54, v55, v54
	s_nop 0
	s_waitcnt lgkmcnt(0)
	v_mov_b32_e32 v55, v54
	s_nop 1
	v_permlane16_swap_b32_e32 v55, v54
	v_add_f32_e32 v54, v54, v55
	v_mov_b32_e32 v55, v54
	s_nop 1
	v_permlane32_swap_b32_e32 v55, v54
	s_and_saveexec_b64 s[36:37], vcc
	s_cbranch_execz .LBB0_1719
	s_waitcnt lgkmcnt(0)
	v_add_f32_e32 v54, v54, v55
	ds_write_b32 v195, v54 offset:256
.LBB0_1719:
	s_or_b64 exec, exec, s[36:37]
	s_waitcnt vmcnt(1)
	v_lshlrev_b32_e32 v54, 16, v68
	s_waitcnt lgkmcnt(0)
	v_and_b32_e32 v55, 0xffff0000, v68
	v_pk_fma_f32 v[44:45], v[44:45], v[136:137], v[54:55]
	v_lshlrev_b32_e32 v54, 16, v69
	v_and_b32_e32 v55, 0xffff0000, v69
	v_pk_fma_f32 v[46:47], v[46:47], v[138:139], v[54:55]
	v_lshlrev_b32_e32 v54, 16, v70
	v_and_b32_e32 v55, 0xffff0000, v70
	v_pk_fma_f32 v[40:41], v[40:41], v[128:129], v[54:55]
	v_lshlrev_b32_e32 v54, 16, v71
	v_and_b32_e32 v55, 0xffff0000, v71
	v_pk_fma_f32 v[42:43], v[42:43], v[130:131], v[54:55]
	s_waitcnt vmcnt(0)
	v_lshlrev_b32_e32 v54, 16, v64
	v_and_b32_e32 v55, 0xffff0000, v64
	v_pk_mul_f32 v[200:201], v[40:41], v[40:41]
	v_pk_mul_f32 v[202:203], v[42:43], v[42:43]
	v_pk_fma_f32 v[54:55], v[36:37], v[140:141], v[54:55]
	v_lshlrev_b32_e32 v36, 16, v65
	v_and_b32_e32 v37, 0xffff0000, v65
	v_lshlrev_b32_e32 v64, 16, v66
	v_and_b32_e32 v65, 0xffff0000, v66
	v_pk_mul_f32 v[176:177], v[44:45], v[44:45]
	v_pk_mul_f32 v[198:199], v[46:47], v[46:47]
	v_pk_fma_f32 v[68:69], v[38:39], v[142:143], v[36:37]
	v_pk_fma_f32 v[70:71], v[32:33], v[132:133], v[64:65]
	v_lshlrev_b32_e32 v32, 16, v67
	v_and_b32_e32 v33, 0xffff0000, v67
	v_add_f32_e32 v64, v202, v203
	v_add_f32_e32 v65, v200, v201
	v_pk_mul_f32 v[36:37], v[54:55], v[54:55]
	v_pk_mul_f32 v[38:39], v[68:69], v[68:69]
	v_pk_fma_f32 v[66:67], v[34:35], v[134:135], v[32:33]
	v_add_f32_e32 v64, v65, v64
	v_add_f32_e32 v65, v198, v199
	v_add_f32_e32 v176, v176, v177
	v_pk_mul_f32 v[32:33], v[70:71], v[70:71]
	v_pk_mul_f32 v[34:35], v[66:67], v[66:67]
	v_add_f32_e32 v65, v176, v65
	v_add_f32_e32 v38, v38, v39
	v_add_f32_e32 v36, v36, v37
	v_add_f32_e32 v64, v65, v64
	v_add_f32_e32 v36, v36, v38
	v_add_f32_e32 v34, v34, v35
	v_add_f32_e32 v32, v32, v33
	v_add_f32_e32 v36, v64, v36
	v_add_f32_e32 v32, v32, v34
	v_add_f32_e32 v32, v32, v36
	s_nop 0
	s_waitcnt lgkmcnt(0)
	v_mov_b32_e32 v33, v32
	s_nop 1
	v_permlane16_swap_b32_e32 v33, v32
	v_add_f32_e32 v32, v32, v33
	v_mov_b32_e32 v33, v32
	s_nop 1
	v_permlane32_swap_b32_e32 v33, v32
	s_and_saveexec_b64 s[36:37], vcc
	s_cbranch_execz .LBB0_1721
	s_waitcnt lgkmcnt(0)
	v_add_f32_e32 v32, v32, v33
	ds_write_b32 v195, v32 offset:320
.LBB0_1721:
	s_or_b64 exec, exec, s[36:37]
	v_add_u32_e32 v32, 0xa0, v178
	s_waitcnt lgkmcnt(0)
	v_ashrrev_i32_e32 v33, 31, v32
	v_lshlrev_b64 v[176:177], 12, v[32:33]
	v_lshl_add_u64 v[32:33], s[74:75], 0, v[176:177]
	v_lshl_add_u64 v[34:35], v[32:33], 0, v[180:181]
	global_load_dwordx4 v[198:201], v[34:35], off
	v_lshl_add_u64 v[32:33], v[32:33], 0, v[182:183]
	global_load_dwordx4 v[202:205], v[32:33], off
	v_add_u32_e32 v32, 0xb0, v178
	v_ashrrev_i32_e32 v33, 31, v32
	v_lshlrev_b64 v[64:65], 12, v[32:33]
	v_lshl_add_u64 v[32:33], s[74:75], 0, v[64:65]
	v_lshl_add_u64 v[34:35], v[32:33], 0, v[180:181]
	v_lshl_add_u64 v[32:33], v[32:33], 0, v[182:183]
	global_load_dwordx4 v[36:39], v[34:35], off
	s_nop 0
	global_load_dwordx4 v[32:35], v[32:33], off
	s_waitcnt vmcnt(3)
	v_lshlrev_b32_e32 v178, 16, v198
	v_and_b32_e32 v179, 0xffff0000, v198
	v_lshlrev_b32_e32 v180, 16, v199
	v_and_b32_e32 v181, 0xffff0000, v199
	v_lshlrev_b32_e32 v182, 16, v200
	v_and_b32_e32 v183, 0xffff0000, v200
	v_lshlrev_b32_e32 v198, 16, v201
	v_and_b32_e32 v199, 0xffff0000, v201
	s_waitcnt vmcnt(2)
	v_lshlrev_b32_e32 v200, 16, v202
	v_and_b32_e32 v201, 0xffff0000, v202
	v_lshlrev_b32_e32 v202, 16, v203
	v_and_b32_e32 v203, 0xffff0000, v203
	v_pk_fma_f32 v[178:179], v[28:29], v[136:137], v[178:179]
	v_pk_fma_f32 v[30:31], v[30:31], v[138:139], v[180:181]
	v_pk_fma_f32 v[28:29], v[24:25], v[128:129], v[182:183]
	v_pk_fma_f32 v[26:27], v[26:27], v[130:131], v[198:199]
	v_lshlrev_b32_e32 v206, 16, v204
	v_and_b32_e32 v207, 0xffff0000, v204
	v_lshlrev_b32_e32 v204, 16, v205
	v_and_b32_e32 v205, 0xffff0000, v205
	v_pk_fma_f32 v[24:25], v[20:21], v[140:141], v[200:201]
	v_pk_fma_f32 v[20:21], v[22:23], v[142:143], v[202:203]
	v_pk_mul_f32 v[22:23], v[178:179], v[178:179]
	v_pk_mul_f32 v[180:181], v[30:31], v[30:31]
	v_pk_mul_f32 v[182:183], v[28:29], v[28:29]
	v_pk_mul_f32 v[198:199], v[26:27], v[26:27]
	v_pk_fma_f32 v[16:17], v[16:17], v[132:133], v[206:207]
	v_pk_fma_f32 v[18:19], v[18:19], v[134:135], v[204:205]
	v_pk_mul_f32 v[200:201], v[24:25], v[24:25]
	v_pk_mul_f32 v[202:203], v[20:21], v[20:21]
	v_add_f32_e32 v197, v198, v199
	v_add_f32_e32 v182, v182, v183
	v_add_f32_e32 v180, v180, v181
	v_add_f32_e32 v22, v22, v23
	v_pk_mul_f32 v[204:205], v[16:17], v[16:17]
	v_pk_mul_f32 v[206:207], v[18:19], v[18:19]
	v_add_f32_e32 v23, v202, v203
	v_add_f32_e32 v181, v200, v201
	v_add_f32_e32 v182, v182, v197
	v_add_f32_e32 v22, v22, v180
	v_add_f32_e32 v183, v206, v207
	v_add_f32_e32 v198, v204, v205
	v_add_f32_e32 v23, v181, v23
	v_add_f32_e32 v22, v22, v182
	v_add_f32_e32 v22, v22, v23
	v_add_f32_e32 v23, v198, v183
	v_add_f32_e32 v22, v23, v22
	s_nop 0
	s_waitcnt lgkmcnt(0)
	v_mov_b32_e32 v23, v22
	s_nop 1
	v_permlane16_swap_b32_e32 v23, v22
	v_add_f32_e32 v22, v22, v23
	v_mov_b32_e32 v23, v22
	s_nop 1
	v_permlane32_swap_b32_e32 v23, v22
	s_and_saveexec_b64 s[36:37], vcc
	s_cbranch_execz .LBB0_1723
	s_waitcnt lgkmcnt(0)
	v_add_f32_e32 v22, v22, v23
	ds_write_b32 v195, v22 offset:384
.LBB0_1723:
	s_or_b64 exec, exec, s[36:37]
	s_waitcnt vmcnt(1)
	v_lshlrev_b32_e32 v22, 16, v36
	s_waitcnt lgkmcnt(0)
	v_and_b32_e32 v23, 0xffff0000, v36
	v_pk_fma_f32 v[22:23], v[12:13], v[136:137], v[22:23]
	v_lshlrev_b32_e32 v136, 16, v38
	v_and_b32_e32 v137, 0xffff0000, v38
	v_pk_fma_f32 v[128:129], v[8:9], v[128:129], v[136:137]
	v_lshlrev_b32_e32 v8, 16, v39
	v_and_b32_e32 v9, 0xffff0000, v39
	v_lshlrev_b32_e32 v12, 16, v37
	v_and_b32_e32 v13, 0xffff0000, v37
	v_pk_fma_f32 v[38:39], v[10:11], v[130:131], v[8:9]
	s_waitcnt vmcnt(0)
	v_lshlrev_b32_e32 v130, 16, v32
	v_and_b32_e32 v131, 0xffff0000, v32
	v_pk_fma_f32 v[36:37], v[14:15], v[138:139], v[12:13]
	v_pk_mul_f32 v[8:9], v[128:129], v[128:129]
	v_pk_mul_f32 v[10:11], v[38:39], v[38:39]
	v_pk_fma_f32 v[130:131], v[4:5], v[140:141], v[130:131]
	v_lshlrev_b32_e32 v4, 16, v33
	v_and_b32_e32 v5, 0xffff0000, v33
	v_lshlrev_b32_e32 v136, 16, v34
	v_and_b32_e32 v137, 0xffff0000, v34
	v_pk_mul_f32 v[12:13], v[22:23], v[22:23]
	v_pk_mul_f32 v[14:15], v[36:37], v[36:37]
	v_pk_fma_f32 v[32:33], v[6:7], v[142:143], v[4:5]
	v_pk_fma_f32 v[132:133], v[0:1], v[132:133], v[136:137]
	v_lshlrev_b32_e32 v0, 16, v35
	v_and_b32_e32 v1, 0xffff0000, v35
	v_add_f32_e32 v10, v10, v11
	v_add_f32_e32 v8, v8, v9
	v_pk_mul_f32 v[4:5], v[130:131], v[130:131]
	v_pk_mul_f32 v[6:7], v[32:33], v[32:33]
	v_pk_fma_f32 v[34:35], v[2:3], v[134:135], v[0:1]
	v_add_f32_e32 v8, v8, v10
	v_add_f32_e32 v9, v14, v15
	v_add_f32_e32 v10, v12, v13
	v_pk_mul_f32 v[0:1], v[132:133], v[132:133]
	v_pk_mul_f32 v[2:3], v[34:35], v[34:35]
	v_add_f32_e32 v9, v10, v9
	v_add_f32_e32 v6, v6, v7
	v_add_f32_e32 v4, v4, v5
	v_add_f32_e32 v8, v9, v8
	v_add_f32_e32 v4, v4, v6
	v_add_f32_e32 v2, v2, v3
	v_add_f32_e32 v0, v0, v1
	v_add_f32_e32 v4, v8, v4
	v_add_f32_e32 v0, v0, v2
	v_add_f32_e32 v0, v0, v4
	s_nop 0
	s_waitcnt lgkmcnt(0)
	v_mov_b32_e32 v1, v0
	s_nop 1
	v_permlane16_swap_b32_e32 v1, v0
	v_add_f32_e32 v0, v0, v1
	v_mov_b32_e32 v1, v0
	s_nop 1
	v_permlane32_swap_b32_e32 v1, v0
	s_and_saveexec_b64 s[36:37], vcc
	s_cbranch_execz .LBB0_1725
	s_waitcnt lgkmcnt(0)
	v_add_f32_e32 v0, v0, v1
	ds_write_b32 v195, v0 offset:448
